# GEMM loops: MFMA blocks placed at byte phase 4 mod 8 (s_nop in load segments), mid-block setprio flip pairs removed; plus earlier epilogue edits
# baseline (speedup 1.0000x reference)
; #define PG8_STAGE(bufoff, gbase, voff) do { _Pragma("unroll") for (int _i = 0; _i < 2; ++_i) \
;         __builtin_amdgcn_global_load_lds((const unsigned*)((const char*)(gbase) + (voff)[_i]), (PG8_LAS unsigned*)(lds + (bufoff) + ldsw + _i * 8192), 16, 0, 0); } while (0)
; #define PG8_LDA(dst, b, h) do { _Pragma("unroll") for (int m = 0; m < 4; ++m) _Pragma("unroll") for (int k = 0; k < 2; ++k) dst[m][k] = *(const PG8_LAS bf16x8*)(lds + PG8_SA(b, h) + aoff + m * 2048 + k * 1024); } while (0)
; #define PG8_LDB(dst, b, h) do { _Pragma("unroll") for (int n = 0; n < 2; ++n) _Pragma("unroll") for (int k = 0; k < 2; ++k) dst[n][k] = *(const PG8_LAS bf16x8*)(lds + PG8_SB(b, h) + boff + n * 2048 + k * 1024); } while (0)
; #define PG8_MMA(ai, bj, At, Bt) do { __builtin_amdgcn_s_setprio(1); _Pragma("unroll") for (int m = 0; m < 4; ++m) _Pragma("unroll") for (int n = 0; n < 2; ++n) _Pragma("unroll") for (int k = 0; k < 2; ++k) \
;         acc[ai][bj][m][n] = __builtin_amdgcn_mfma_f32_16x16x32_bf16(Bt[n][k], At[m][k], acc[ai][bj][m][n], 0, 0, 0); __builtin_amdgcn_s_setprio(0); } while (0)
; #define PG8_WAIT_V(n) asm volatile("s_waitcnt vmcnt(" #n ")" ::: "memory")
; #define PG8_WAIT_L(n) asm volatile("s_waitcnt lgkmcnt(" #n ")" ::: "memory")
; #define PG8_BAR __builtin_amdgcn_s_barrier()
; #define PG8_SCHED __builtin_amdgcn_sched_barrier(0)
; template <class Epi, class Sched, bool ALIGN_EPI = false, bool SP2 = false>
; __device__ __forceinline__ void gemm_phase(PG8_LAS unsigned char* lds, const Gemm g, const Sched& S, const Epi& E) {
;     ...
;             const bool last = (t == nt - 2);
;             const char* a1 = cA + (size_t)(t + 1) * kstep;
;             const char* a2 = last ? nA : cA + (size_t)(t + 2) * kstep; const char* b2 = last ? nB : cB + (size_t)(t + 2) * kstep;
;             const char* a3 = a2 + kstep; const char* b3 = b2 + kstep;
;             if (last && has_next) S.a_ready(nxt);
;             if constexpr (SP2) {
;             PG8_LDB(B0, 0, 0); PG8_LDB(B1, 0, 1); PG8_SCHED; PG8_LDA(At, 0, 0); PG8_STAGE(PG8_SA(1, 1), a1 + hstep, voffA);
;             PG8_WAIT_V(8); PG8_WAIT_L(0); PG8_BAR; PG8_MMA(0, 0, At, B0); PG8_MMA(0, 1, At, B1); PG8_BAR; PG8_SCHED;
;             PG8_LDA(At, 0, 1); PG8_STAGE(PG8_SB(0, 0), b2, voffB); PG8_STAGE(PG8_SB(0, 1), b2 + hstep, voffB); PG8_STAGE(PG8_SA(0, 0), a2, voffA);
.LBB0_148:
	s_add_u32 s8, s6, 0xfff80080
	s_addc_u32 s9, s7, -1
	s_add_i32 s39, 0, 0x10000
	s_cmp_eq_u32 s38, 28
	s_cselect_b32 s31, s25, s9
	s_cselect_b32 s30, s34, s8
	s_cselect_b32 s9, s23, s37
	s_cselect_b32 s8, s35, s36
	s_add_i32 s58, 0, 0x14000
	v_add_u32_e32 v140, s39, v181
	v_add_u32_e32 v178, s58, v181
	ds_read_b128 v[128:131], v140
	ds_read_b128 v[132:135], v140 offset:1024
	ds_read_b128 v[136:139], v140 offset:2048
	ds_read_b128 v[140:143], v140 offset:3072
	ds_read_b128 v[174:177], v178
	ds_read_b128 v[184:187], v178 offset:1024
	ds_read_b128 v[198:201], v178 offset:2048
	ds_read_b128 v[202:205], v178 offset:3072
	v_lshl_add_u64 v[246:247], s[6:7], 0, v[154:155]
	s_add_i32 m0, s63, 0xc000
	ds_read_b128 v[206:209], v183
	ds_read_b128 v[210:213], v183 offset:1024
	ds_read_b128 v[214:217], v183 offset:2048
	ds_read_b128 v[218:221], v183 offset:3072
	ds_read_b128 v[222:225], v183 offset:4096
	ds_read_b128 v[226:229], v183 offset:5120
	ds_read_b128 v[238:241], v183 offset:6144
	ds_read_b128 v[242:245], v183 offset:7168
	global_load_lds_dwordx4 v[246:247], off
	v_lshl_add_u64 v[246:247], s[6:7], 0, v[156:157]
	s_add_i32 m0, s63, 0xe000
	s_nop 0
	global_load_lds_dwordx4 v[246:247], off
	s_waitcnt vmcnt(8)
	s_waitcnt lgkmcnt(0)
	s_barrier
	s_setprio 1
	s_waitcnt lgkmcnt(0)
	v_mfma_f32_16x16x32_bf16 v[124:127], v[128:131], v[206:209], v[124:127]
	v_mfma_f32_16x16x32_bf16 v[120:123], v[136:139], v[206:209], v[120:123]
	v_mfma_f32_16x16x32_bf16 v[108:111], v[128:131], v[214:217], v[108:111]
	v_mfma_f32_16x16x32_bf16 v[104:107], v[136:139], v[214:217], v[104:107]
	v_mfma_f32_16x16x32_bf16 v[92:95], v[128:131], v[222:225], v[92:95]
	v_mfma_f32_16x16x32_bf16 v[88:91], v[136:139], v[222:225], v[88:91]
	v_mfma_f32_16x16x32_bf16 v[76:79], v[128:131], v[238:241], v[76:79]
	v_mfma_f32_16x16x32_bf16 v[72:75], v[136:139], v[238:241], v[72:75]
	v_mfma_f32_16x16x32_bf16 v[124:127], v[132:135], v[210:213], v[124:127]
	v_mfma_f32_16x16x32_bf16 v[120:123], v[140:143], v[210:213], v[120:123]
	v_mfma_f32_16x16x32_bf16 v[108:111], v[132:135], v[218:221], v[108:111]
	v_mfma_f32_16x16x32_bf16 v[104:107], v[140:143], v[218:221], v[104:107]
	v_mfma_f32_16x16x32_bf16 v[92:95], v[132:135], v[226:229], v[92:95]
	v_mfma_f32_16x16x32_bf16 v[88:91], v[140:143], v[226:229], v[88:91]
	v_mfma_f32_16x16x32_bf16 v[76:79], v[132:135], v[242:245], v[76:79]
	v_mfma_f32_16x16x32_bf16 v[72:75], v[140:143], v[242:245], v[72:75]
	v_mfma_f32_16x16x32_bf16 v[116:119], v[174:177], v[206:209], v[116:119]
	v_mfma_f32_16x16x32_bf16 v[112:115], v[198:201], v[206:209], v[112:115]
	v_mfma_f32_16x16x32_bf16 v[100:103], v[174:177], v[214:217], v[100:103]
	v_mfma_f32_16x16x32_bf16 v[96:99], v[198:201], v[214:217], v[96:99]
	v_mfma_f32_16x16x32_bf16 v[84:87], v[174:177], v[222:225], v[84:87]
	v_mfma_f32_16x16x32_bf16 v[80:83], v[198:201], v[222:225], v[80:83]
	v_mfma_f32_16x16x32_bf16 v[68:71], v[174:177], v[238:241], v[68:71]
	v_mfma_f32_16x16x32_bf16 v[64:67], v[198:201], v[238:241], v[64:67]
	v_mfma_f32_16x16x32_bf16 v[116:119], v[184:187], v[210:213], v[116:119]
	v_mfma_f32_16x16x32_bf16 v[112:115], v[202:205], v[210:213], v[112:115]
	v_mfma_f32_16x16x32_bf16 v[100:103], v[184:187], v[218:221], v[100:103]
	v_mfma_f32_16x16x32_bf16 v[96:99], v[202:205], v[218:221], v[96:99]
	v_mfma_f32_16x16x32_bf16 v[84:87], v[184:187], v[226:229], v[84:87]
	v_mfma_f32_16x16x32_bf16 v[80:83], v[202:205], v[226:229], v[80:83]
	v_mfma_f32_16x16x32_bf16 v[68:71], v[184:187], v[242:245], v[68:71]
	v_mfma_f32_16x16x32_bf16 v[64:67], v[202:205], v[242:245], v[64:67]
	s_setprio 0
	s_barrier
	s_add_i32 s39, s39, s45
	v_lshl_add_u64 v[246:247], s[8:9], 0, v[148:149]
	s_mov_b32 m0, s39
	ds_read_b128 v[206:209], v183 offset:16384
	ds_read_b128 v[210:213], v183 offset:17408
	ds_read_b128 v[214:217], v183 offset:18432
	ds_read_b128 v[218:221], v183 offset:19456
	ds_read_b128 v[222:225], v183 offset:20480
	ds_read_b128 v[226:229], v183 offset:21504
	ds_read_b128 v[238:241], v183 offset:22528
	ds_read_b128 v[242:245], v183 offset:23552
	global_load_lds_dwordx4 v[246:247], off
	s_add_i32 m0, s39, 0x2000
	s_add_u32 s88, s8, 0x80000
	v_lshl_add_u64 v[248:249], s[8:9], 0, v[144:145]
	s_addc_u32 s89, s9, 0
	s_add_i32 s39, s58, s45
	global_load_lds_dwordx4 v[248:249], off
	v_lshl_add_u64 v[250:251], s[88:89], 0, v[148:149]
	s_mov_b32 m0, s39
	v_lshl_add_u64 v[252:253], s[30:31], 0, v[146:147]
	global_load_lds_dwordx4 v[250:251], off
	v_lshl_add_u64 v[250:251], s[88:89], 0, v[144:145]
	s_add_i32 m0, s39, 0x2000
	s_nop 0
	global_load_lds_dwordx4 v[250:251], off
	v_lshl_add_u64 v[250:251], s[30:31], 0, v[150:151]
	s_mov_b32 m0, s63
	s_nop 0
	global_load_lds_dwordx4 v[250:251], off
	s_mov_b32 m0, s66
	s_nop 0
	global_load_lds_dwordx4 v[252:253], off
	s_nop 0
	s_waitcnt vmcnt(8)
	s_waitcnt lgkmcnt(0)
	s_barrier
; #define PG8_STAGE(bufoff, gbase, voff) do { _Pragma("unroll") for (int _i = 0; _i < 2; ++_i) \
;         __builtin_amdgcn_global_load_lds((const unsigned*)((const char*)(gbase) + (voff)[_i]), (PG8_LAS unsigned*)(lds + (bufoff) + ldsw + _i * 8192), 16, 0, 0); } while (0)
; #define PG8_LDA(dst, b, h) do { _Pragma("unroll") for (int m = 0; m < 4; ++m) _Pragma("unroll") for (int k = 0; k < 2; ++k) dst[m][k] = *(const PG8_LAS bf16x8*)(lds + PG8_SA(b, h) + aoff + m * 2048 + k * 1024); } while (0)
; #define PG8_LDB(dst, b, h) do { _Pragma("unroll") for (int n = 0; n < 2; ++n) _Pragma("unroll") for (int k = 0; k < 2; ++k) dst[n][k] = *(const PG8_LAS bf16x8*)(lds + PG8_SB(b, h) + boff + n * 2048 + k * 1024); } while (0)
; #define PG8_MMA(ai, bj, At, Bt) do { __builtin_amdgcn_s_setprio(1); _Pragma("unroll") for (int m = 0; m < 4; ++m) _Pragma("unroll") for (int n = 0; n < 2; ++n) _Pragma("unroll") for (int k = 0; k < 2; ++k) \
;         acc[ai][bj][m][n] = __builtin_amdgcn_mfma_f32_16x16x32_bf16(Bt[n][k], At[m][k], acc[ai][bj][m][n], 0, 0, 0); __builtin_amdgcn_s_setprio(0); } while (0)
; #define PG8_WAIT_V(n) asm volatile("s_waitcnt vmcnt(" #n ")" ::: "memory")
; #define PG8_WAIT_L(n) asm volatile("s_waitcnt lgkmcnt(" #n ")" ::: "memory")
; #define PG8_BAR __builtin_amdgcn_s_barrier()
; #define PG8_SCHED __builtin_amdgcn_sched_barrier(0)
; template <class Epi, class Sched, bool ALIGN_EPI = false, bool SP2 = false>
; __device__ __forceinline__ void gemm_phase(PG8_LAS unsigned char* lds, const Gemm g, const Sched& S, const Epi& E) {
;     ...
;             PG8_WAIT_V(8); PG8_WAIT_L(0); PG8_BAR; PG8_MMA(1, 0, At, B0); PG8_MMA(1, 1, At, B1); PG8_BAR; PG8_SCHED;
;             PG8_LDB(B0, 1, 0); PG8_LDB(B1, 1, 1); PG8_SCHED; PG8_LDA(At, 1, 0); PG8_STAGE(PG8_SA(0, 1), a2 + hstep, voffA);
;             PG8_WAIT_V(8); PG8_WAIT_L(0); PG8_BAR; PG8_MMA(0, 0, At, B0); PG8_MMA(0, 1, At, B1); PG8_BAR; PG8_SCHED;
	s_setprio 1
	s_waitcnt lgkmcnt(0)
	v_mfma_f32_16x16x32_bf16 v[60:63], v[128:131], v[206:209], v[60:63]
	v_mfma_f32_16x16x32_bf16 v[56:59], v[136:139], v[206:209], v[56:59]
	v_mfma_f32_16x16x32_bf16 v[44:47], v[128:131], v[214:217], v[44:47]
	v_mfma_f32_16x16x32_bf16 v[40:43], v[136:139], v[214:217], v[40:43]
	v_mfma_f32_16x16x32_bf16 v[28:31], v[128:131], v[222:225], v[28:31]
	v_mfma_f32_16x16x32_bf16 v[24:27], v[136:139], v[222:225], v[24:27]
	v_mfma_f32_16x16x32_bf16 v[12:15], v[128:131], v[238:241], v[12:15]
	v_mfma_f32_16x16x32_bf16 v[8:11], v[136:139], v[238:241], v[8:11]
	v_mfma_f32_16x16x32_bf16 v[60:63], v[132:135], v[210:213], v[60:63]
	v_mfma_f32_16x16x32_bf16 v[56:59], v[140:143], v[210:213], v[56:59]
	v_mfma_f32_16x16x32_bf16 v[44:47], v[132:135], v[218:221], v[44:47]
	v_mfma_f32_16x16x32_bf16 v[40:43], v[140:143], v[218:221], v[40:43]
	v_mfma_f32_16x16x32_bf16 v[28:31], v[132:135], v[226:229], v[28:31]
	v_mfma_f32_16x16x32_bf16 v[24:27], v[140:143], v[226:229], v[24:27]
	v_mfma_f32_16x16x32_bf16 v[12:15], v[132:135], v[242:245], v[12:15]
	v_mfma_f32_16x16x32_bf16 v[8:11], v[140:143], v[242:245], v[8:11]
	v_mfma_f32_16x16x32_bf16 v[52:55], v[174:177], v[206:209], v[52:55]
	v_mfma_f32_16x16x32_bf16 v[48:51], v[198:201], v[206:209], v[48:51]
	v_mfma_f32_16x16x32_bf16 v[36:39], v[174:177], v[214:217], v[36:39]
	v_mfma_f32_16x16x32_bf16 v[32:35], v[198:201], v[214:217], v[32:35]
	v_mfma_f32_16x16x32_bf16 v[20:23], v[174:177], v[222:225], v[20:23]
	v_mfma_f32_16x16x32_bf16 v[16:19], v[198:201], v[222:225], v[16:19]
	v_mfma_f32_16x16x32_bf16 v[4:7], v[174:177], v[238:241], v[4:7]
	v_mfma_f32_16x16x32_bf16 v[0:3], v[198:201], v[238:241], v[0:3]
	v_mfma_f32_16x16x32_bf16 v[52:55], v[184:187], v[210:213], v[52:55]
	v_mfma_f32_16x16x32_bf16 v[48:51], v[202:205], v[210:213], v[48:51]
	v_mfma_f32_16x16x32_bf16 v[36:39], v[184:187], v[218:221], v[36:39]
	v_mfma_f32_16x16x32_bf16 v[32:35], v[202:205], v[218:221], v[32:35]
	v_mfma_f32_16x16x32_bf16 v[20:23], v[184:187], v[226:229], v[20:23]
	v_mfma_f32_16x16x32_bf16 v[16:19], v[202:205], v[226:229], v[16:19]
	v_mfma_f32_16x16x32_bf16 v[4:7], v[184:187], v[242:245], v[4:7]
	v_mfma_f32_16x16x32_bf16 v[0:3], v[202:205], v[242:245], v[0:3]
	s_setprio 0
	s_barrier
	s_add_i32 s39, 0, 0x18000
	s_add_i32 s58, 0, 0x1c000
	v_add_u32_e32 v140, s39, v181
	v_add_u32_e32 v178, s58, v181
	ds_read_b128 v[128:131], v140
	ds_read_b128 v[132:135], v140 offset:1024
	ds_read_b128 v[136:139], v140 offset:2048
	ds_read_b128 v[140:143], v140 offset:3072
	ds_read_b128 v[174:177], v178
	ds_read_b128 v[184:187], v178 offset:1024
	ds_read_b128 v[198:201], v178 offset:2048
	ds_read_b128 v[202:205], v178 offset:3072
	s_add_u32 s30, s30, 0x80000
	s_addc_u32 s31, s31, 0
	s_mov_b32 m0, s67
	v_lshl_add_u64 v[232:233], s[30:31], 0, v[150:151]
	ds_read_b128 v[206:209], v183 offset:32768
	ds_read_b128 v[210:213], v183 offset:33792
	ds_read_b128 v[214:217], v183 offset:34816
	ds_read_b128 v[218:221], v183 offset:35840
	ds_read_b128 v[222:225], v183 offset:36864
	ds_read_b128 v[226:229], v183 offset:37888
	ds_read_b128 v[238:241], v183 offset:38912
	ds_read_b128 v[242:245], v183 offset:39936
	global_load_lds_dwordx4 v[232:233], off
	v_lshl_add_u64 v[232:233], s[30:31], 0, v[146:147]
	s_mov_b32 m0, s72
	s_nop 0
	global_load_lds_dwordx4 v[232:233], off
	s_nop 0
	s_waitcnt vmcnt(8)
	s_waitcnt lgkmcnt(0)
	s_barrier
	s_setprio 1
	s_waitcnt lgkmcnt(0)
	v_mfma_f32_16x16x32_bf16 v[124:127], v[128:131], v[206:209], v[124:127]
	v_mfma_f32_16x16x32_bf16 v[120:123], v[136:139], v[206:209], v[120:123]
	v_mfma_f32_16x16x32_bf16 v[108:111], v[128:131], v[214:217], v[108:111]
	v_mfma_f32_16x16x32_bf16 v[104:107], v[136:139], v[214:217], v[104:107]
	v_mfma_f32_16x16x32_bf16 v[92:95], v[128:131], v[222:225], v[92:95]
	v_mfma_f32_16x16x32_bf16 v[88:91], v[136:139], v[222:225], v[88:91]
	v_mfma_f32_16x16x32_bf16 v[76:79], v[128:131], v[238:241], v[76:79]
	v_mfma_f32_16x16x32_bf16 v[72:75], v[136:139], v[238:241], v[72:75]
	v_mfma_f32_16x16x32_bf16 v[124:127], v[132:135], v[210:213], v[124:127]
	v_mfma_f32_16x16x32_bf16 v[120:123], v[140:143], v[210:213], v[120:123]
	v_mfma_f32_16x16x32_bf16 v[108:111], v[132:135], v[218:221], v[108:111]
	v_mfma_f32_16x16x32_bf16 v[104:107], v[140:143], v[218:221], v[104:107]
	v_mfma_f32_16x16x32_bf16 v[92:95], v[132:135], v[226:229], v[92:95]
	v_mfma_f32_16x16x32_bf16 v[88:91], v[140:143], v[226:229], v[88:91]
	v_mfma_f32_16x16x32_bf16 v[76:79], v[132:135], v[242:245], v[76:79]
	v_mfma_f32_16x16x32_bf16 v[72:75], v[140:143], v[242:245], v[72:75]
	v_mfma_f32_16x16x32_bf16 v[116:119], v[174:177], v[206:209], v[116:119]
	v_mfma_f32_16x16x32_bf16 v[112:115], v[198:201], v[206:209], v[112:115]
	v_mfma_f32_16x16x32_bf16 v[100:103], v[174:177], v[214:217], v[100:103]
	v_mfma_f32_16x16x32_bf16 v[96:99], v[198:201], v[214:217], v[96:99]
	v_mfma_f32_16x16x32_bf16 v[84:87], v[174:177], v[222:225], v[84:87]
	v_mfma_f32_16x16x32_bf16 v[80:83], v[198:201], v[222:225], v[80:83]
	v_mfma_f32_16x16x32_bf16 v[68:71], v[174:177], v[238:241], v[68:71]
	v_mfma_f32_16x16x32_bf16 v[64:67], v[198:201], v[238:241], v[64:67]
	v_mfma_f32_16x16x32_bf16 v[116:119], v[184:187], v[210:213], v[116:119]
	v_mfma_f32_16x16x32_bf16 v[112:115], v[202:205], v[210:213], v[112:115]
	v_mfma_f32_16x16x32_bf16 v[100:103], v[184:187], v[218:221], v[100:103]
	v_mfma_f32_16x16x32_bf16 v[96:99], v[202:205], v[218:221], v[96:99]
	v_mfma_f32_16x16x32_bf16 v[84:87], v[184:187], v[226:229], v[84:87]
	v_mfma_f32_16x16x32_bf16 v[80:83], v[202:205], v[226:229], v[80:83]
	v_mfma_f32_16x16x32_bf16 v[68:71], v[184:187], v[242:245], v[68:71]
	v_mfma_f32_16x16x32_bf16 v[64:67], v[202:205], v[242:245], v[64:67]
	s_setprio 0
	s_barrier
; #define PG8_STAGE(bufoff, gbase, voff) do { _Pragma("unroll") for (int _i = 0; _i < 2; ++_i) \
;         __builtin_amdgcn_global_load_lds((const unsigned*)((const char*)(gbase) + (voff)[_i]), (PG8_LAS unsigned*)(lds + (bufoff) + ldsw + _i * 8192), 16, 0, 0); } while (0)
; #define PG8_LDA(dst, b, h) do { _Pragma("unroll") for (int m = 0; m < 4; ++m) _Pragma("unroll") for (int k = 0; k < 2; ++k) dst[m][k] = *(const PG8_LAS bf16x8*)(lds + PG8_SA(b, h) + aoff + m * 2048 + k * 1024); } while (0)
; #define PG8_MMA(ai, bj, At, Bt) do { __builtin_amdgcn_s_setprio(1); _Pragma("unroll") for (int m = 0; m < 4; ++m) _Pragma("unroll") for (int n = 0; n < 2; ++n) _Pragma("unroll") for (int k = 0; k < 2; ++k) \
;         acc[ai][bj][m][n] = __builtin_amdgcn_mfma_f32_16x16x32_bf16(Bt[n][k], At[m][k], acc[ai][bj][m][n], 0, 0, 0); __builtin_amdgcn_s_setprio(0); } while (0)
; #define PG8_WAIT_V(n) asm volatile("s_waitcnt vmcnt(" #n ")" ::: "memory")
; #define PG8_WAIT_L(n) asm volatile("s_waitcnt lgkmcnt(" #n ")" ::: "memory")
; #define PG8_BAR __builtin_amdgcn_s_barrier()
; #define PG8_SCHED __builtin_amdgcn_sched_barrier(0)
; template <class Epi, class Sched, bool ALIGN_EPI = false, bool SP2 = false>
; __device__ __forceinline__ void gemm_phase(PG8_LAS unsigned char* lds, const Gemm g, const Sched& S, const Epi& E) {
;     ...
;             PG8_LDA(At, 1, 1); PG8_STAGE(PG8_SB(1, 0), b3, voffB); PG8_STAGE(PG8_SB(1, 1), b3 + hstep, voffB); PG8_STAGE(PG8_SA(1, 0), a3, voffA);
;             PG8_WAIT_V(8); PG8_WAIT_L(0); PG8_BAR; PG8_MMA(1, 0, At, B0); PG8_MMA(1, 1, At, B1); PG8_BAR; PG8_SCHED;
	s_add_i32 s30, s39, s45
	v_lshl_add_u64 v[232:233], v[246:247], 0, s[78:79]
	s_mov_b32 m0, s30
	ds_read_b128 v[206:209], v183 offset:49152
	ds_read_b128 v[210:213], v183 offset:50176
	ds_read_b128 v[214:217], v183 offset:51200
	ds_read_b128 v[218:221], v183 offset:52224
	ds_read_b128 v[222:225], v183 offset:53248
	ds_read_b128 v[226:229], v183 offset:54272
	ds_read_b128 v[238:241], v183 offset:55296
	ds_read_b128 v[242:245], v183 offset:56320
	global_load_lds_dwordx4 v[232:233], off
	s_add_i32 m0, s30, 0x2000
	s_add_u32 s8, s8, 0x80080
	v_lshl_add_u64 v[232:233], v[248:249], 0, s[78:79]
	s_addc_u32 s9, s9, 0
	s_add_i32 s30, s58, s45
	global_load_lds_dwordx4 v[232:233], off
	v_lshl_add_u64 v[232:233], s[8:9], 0, v[148:149]
	s_mov_b32 m0, s30
	s_nop 0
	global_load_lds_dwordx4 v[232:233], off
	v_lshl_add_u64 v[232:233], s[8:9], 0, v[144:145]
	s_add_i32 m0, s30, 0x2000
	s_nop 0
	global_load_lds_dwordx4 v[232:233], off
	v_lshl_add_u64 v[232:233], v[250:251], 0, s[78:79]
	s_mov_b32 m0, s73
	s_nop 0
	global_load_lds_dwordx4 v[232:233], off
	v_lshl_add_u64 v[232:233], v[252:253], 0, s[78:79]
	s_mov_b32 m0, s74
	s_nop 0
	global_load_lds_dwordx4 v[232:233], off
	s_waitcnt vmcnt(8)
	s_waitcnt lgkmcnt(0)
	s_barrier
	s_setprio 1
	s_waitcnt lgkmcnt(0)
	v_mfma_f32_16x16x32_bf16 v[60:63], v[128:131], v[206:209], v[60:63]
	v_mfma_f32_16x16x32_bf16 v[56:59], v[136:139], v[206:209], v[56:59]
	v_mfma_f32_16x16x32_bf16 v[44:47], v[128:131], v[214:217], v[44:47]
	v_mfma_f32_16x16x32_bf16 v[40:43], v[136:139], v[214:217], v[40:43]
	v_mfma_f32_16x16x32_bf16 v[28:31], v[128:131], v[222:225], v[28:31]
	v_mfma_f32_16x16x32_bf16 v[24:27], v[136:139], v[222:225], v[24:27]
	v_mfma_f32_16x16x32_bf16 v[12:15], v[128:131], v[238:241], v[12:15]
	v_mfma_f32_16x16x32_bf16 v[8:11], v[136:139], v[238:241], v[8:11]
	v_mfma_f32_16x16x32_bf16 v[60:63], v[132:135], v[210:213], v[60:63]
	v_mfma_f32_16x16x32_bf16 v[56:59], v[140:143], v[210:213], v[56:59]
	v_mfma_f32_16x16x32_bf16 v[44:47], v[132:135], v[218:221], v[44:47]
	v_mfma_f32_16x16x32_bf16 v[40:43], v[140:143], v[218:221], v[40:43]
	v_mfma_f32_16x16x32_bf16 v[28:31], v[132:135], v[226:229], v[28:31]
	v_mfma_f32_16x16x32_bf16 v[24:27], v[140:143], v[226:229], v[24:27]
	v_mfma_f32_16x16x32_bf16 v[12:15], v[132:135], v[242:245], v[12:15]
	v_mfma_f32_16x16x32_bf16 v[8:11], v[140:143], v[242:245], v[8:11]
	v_mfma_f32_16x16x32_bf16 v[52:55], v[174:177], v[206:209], v[52:55]
	v_mfma_f32_16x16x32_bf16 v[48:51], v[198:201], v[206:209], v[48:51]
	v_mfma_f32_16x16x32_bf16 v[36:39], v[174:177], v[214:217], v[36:39]
	v_mfma_f32_16x16x32_bf16 v[32:35], v[198:201], v[214:217], v[32:35]
	v_mfma_f32_16x16x32_bf16 v[20:23], v[174:177], v[222:225], v[20:23]
	v_mfma_f32_16x16x32_bf16 v[16:19], v[198:201], v[222:225], v[16:19]
	v_mfma_f32_16x16x32_bf16 v[4:7], v[174:177], v[238:241], v[4:7]
	v_mfma_f32_16x16x32_bf16 v[0:3], v[198:201], v[238:241], v[0:3]
	v_mfma_f32_16x16x32_bf16 v[52:55], v[184:187], v[210:213], v[52:55]
	v_mfma_f32_16x16x32_bf16 v[48:51], v[202:205], v[210:213], v[48:51]
	v_mfma_f32_16x16x32_bf16 v[36:39], v[184:187], v[218:221], v[36:39]
	v_mfma_f32_16x16x32_bf16 v[32:35], v[202:205], v[218:221], v[32:35]
	v_mfma_f32_16x16x32_bf16 v[20:23], v[184:187], v[226:229], v[20:23]
	v_mfma_f32_16x16x32_bf16 v[16:19], v[202:205], v[226:229], v[16:19]
	v_mfma_f32_16x16x32_bf16 v[4:7], v[184:187], v[242:245], v[4:7]
	v_mfma_f32_16x16x32_bf16 v[0:3], v[202:205], v[242:245], v[0:3]
	s_setprio 0
	s_barrier
	s_add_i32 s38, s38, 2
	s_add_u32 s6, s6, 0x100
	s_addc_u32 s7, s7, 0
	s_add_u32 s36, s36, 0x100
	s_addc_u32 s37, s37, 0
	s_cmp_gt_u32 s38, 29
	s_cbranch_scc0 .LBB0_148
	s_and_b64 vcc, exec, s[20:21]
	s_cbranch_vccz .LBB0_151
	s_barrier

; #define PG8_STAGE(bufoff, gbase, voff) do { _Pragma("unroll") for (int _i = 0; _i < 2; ++_i) \
;         __builtin_amdgcn_global_load_lds((const unsigned*)((const char*)(gbase) + (voff)[_i]), (PG8_LAS unsigned*)(lds + (bufoff) + ldsw + _i * 8192), 16, 0, 0); } while (0)
; #define PG8_LDA(dst, b, h) do { _Pragma("unroll") for (int m = 0; m < 4; ++m) _Pragma("unroll") for (int k = 0; k < 2; ++k) dst[m][k] = *(const PG8_LAS bf16x8*)(lds + PG8_SA(b, h) + aoff + m * 2048 + k * 1024); } while (0)
; #define PG8_LDB(dst, b, h) do { _Pragma("unroll") for (int n = 0; n < 2; ++n) _Pragma("unroll") for (int k = 0; k < 2; ++k) dst[n][k] = *(const PG8_LAS bf16x8*)(lds + PG8_SB(b, h) + boff + n * 2048 + k * 1024); } while (0)
; #define PG8_MMA(ai, bj, At, Bt) do { __builtin_amdgcn_s_setprio(1); _Pragma("unroll") for (int m = 0; m < 4; ++m) _Pragma("unroll") for (int n = 0; n < 2; ++n) _Pragma("unroll") for (int k = 0; k < 2; ++k) \
;         acc[ai][bj][m][n] = __builtin_amdgcn_mfma_f32_16x16x32_bf16(Bt[n][k], At[m][k], acc[ai][bj][m][n], 0, 0, 0); __builtin_amdgcn_s_setprio(0); } while (0)
; #define PG8_WAIT_V(n) asm volatile("s_waitcnt vmcnt(" #n ")" ::: "memory")
; #define PG8_WAIT_L(n) asm volatile("s_waitcnt lgkmcnt(" #n ")" ::: "memory")
; #define PG8_BAR __builtin_amdgcn_s_barrier()
; #define PG8_SCHED __builtin_amdgcn_sched_barrier(0)
; template <class Epi, class Sched, bool ALIGN_EPI = false, bool SP2 = false>
; __device__ __forceinline__ void gemm_phase(PG8_LAS unsigned char* lds, const Gemm g, const Sched& S, const Epi& E) {
;     ...
;             const bool last = (t == nt - 2);
;             const char* a1 = cA + (size_t)(t + 1) * kstep;
;             const char* a2 = last ? nA : cA + (size_t)(t + 2) * kstep; const char* b2 = last ? nB : cB + (size_t)(t + 2) * kstep;
;             const char* a3 = a2 + kstep; const char* b3 = b2 + kstep;
;             if (last && has_next) S.a_ready(nxt);
;             if constexpr (SP2) {
;             PG8_LDB(B0, 0, 0); PG8_LDB(B1, 0, 1); PG8_SCHED; PG8_LDA(At, 0, 0); PG8_STAGE(PG8_SA(1, 1), a1 + hstep, voffA);
;             PG8_WAIT_V(8); PG8_WAIT_L(0); PG8_BAR; PG8_MMA(0, 0, At, B0); PG8_MMA(0, 1, At, B1); PG8_BAR; PG8_SCHED;
;             PG8_LDA(At, 0, 1); PG8_STAGE(PG8_SB(0, 0), b2, voffB); PG8_STAGE(PG8_SB(0, 1), b2 + hstep, voffB); PG8_STAGE(PG8_SA(0, 0), a2, voffA);
.LBB0_424:
	s_add_u32 s8, s6, 0xfffc0080
	s_addc_u32 s9, s7, -1
	s_add_i32 s60, 0, 0x10000
	s_cmp_eq_u32 s58, 12
	s_cselect_b32 s25, s17, s9
	s_cselect_b32 s24, s38, s8
	s_cselect_b32 s9, s19, s52
	s_cselect_b32 s8, s39, s45
	s_add_i32 s62, 0, 0x14000
	v_add_u32_e32 v140, s60, v201
	v_add_u32_e32 v156, s62, v201
	ds_read_b128 v[128:131], v140
	ds_read_b128 v[132:135], v140 offset:1024
	ds_read_b128 v[136:139], v140 offset:2048
	ds_read_b128 v[140:143], v140 offset:3072
	ds_read_b128 v[144:147], v156
	ds_read_b128 v[148:151], v156 offset:1024
	ds_read_b128 v[152:155], v156 offset:2048
	ds_read_b128 v[156:159], v156 offset:3072
	v_lshl_add_u64 v[198:199], s[6:7], 0, v[168:169]
	s_add_i32 m0, s31, 0xc000
	ds_read_b128 v[172:175], v203
	ds_read_b128 v[176:179], v203 offset:1024
	ds_read_b128 v[180:183], v203 offset:2048
	ds_read_b128 v[184:187], v203 offset:3072
	ds_read_b128 v[204:207], v203 offset:4096
	ds_read_b128 v[208:211], v203 offset:5120
	ds_read_b128 v[212:215], v203 offset:6144
	ds_read_b128 v[216:219], v203 offset:7168
	global_load_lds_dwordx4 v[198:199], off
	v_lshl_add_u64 v[198:199], s[6:7], 0, v[170:171]
	s_add_i32 m0, s31, 0xe000
	s_nop 0
	global_load_lds_dwordx4 v[198:199], off
	s_nop 0
	s_waitcnt vmcnt(8)
	s_waitcnt lgkmcnt(0)
	s_barrier
	s_setprio 1
	s_waitcnt lgkmcnt(0)
	v_mfma_f32_16x16x32_bf16 v[124:127], v[128:131], v[172:175], v[124:127]
	v_mfma_f32_16x16x32_bf16 v[120:123], v[136:139], v[172:175], v[120:123]
	v_mfma_f32_16x16x32_bf16 v[116:119], v[128:131], v[180:183], v[116:119]
	v_mfma_f32_16x16x32_bf16 v[112:115], v[136:139], v[180:183], v[112:115]
	v_mfma_f32_16x16x32_bf16 v[108:111], v[128:131], v[204:207], v[108:111]
	v_mfma_f32_16x16x32_bf16 v[104:107], v[136:139], v[204:207], v[104:107]
	v_mfma_f32_16x16x32_bf16 v[100:103], v[128:131], v[212:215], v[100:103]
	v_mfma_f32_16x16x32_bf16 v[96:99], v[136:139], v[212:215], v[96:99]
	v_mfma_f32_16x16x32_bf16 v[124:127], v[132:135], v[176:179], v[124:127]
	v_mfma_f32_16x16x32_bf16 v[120:123], v[140:143], v[176:179], v[120:123]
	v_mfma_f32_16x16x32_bf16 v[116:119], v[132:135], v[184:187], v[116:119]
	v_mfma_f32_16x16x32_bf16 v[112:115], v[140:143], v[184:187], v[112:115]
	v_mfma_f32_16x16x32_bf16 v[108:111], v[132:135], v[208:211], v[108:111]
	v_mfma_f32_16x16x32_bf16 v[104:107], v[140:143], v[208:211], v[104:107]
	v_mfma_f32_16x16x32_bf16 v[100:103], v[132:135], v[216:219], v[100:103]
	v_mfma_f32_16x16x32_bf16 v[96:99], v[140:143], v[216:219], v[96:99]
	v_mfma_f32_16x16x32_bf16 v[92:95], v[144:147], v[172:175], v[92:95]
	v_mfma_f32_16x16x32_bf16 v[88:91], v[152:155], v[172:175], v[88:91]
	v_mfma_f32_16x16x32_bf16 v[84:87], v[144:147], v[180:183], v[84:87]
	v_mfma_f32_16x16x32_bf16 v[80:83], v[152:155], v[180:183], v[80:83]
	v_mfma_f32_16x16x32_bf16 v[76:79], v[144:147], v[204:207], v[76:79]
	v_mfma_f32_16x16x32_bf16 v[72:75], v[152:155], v[204:207], v[72:75]
	v_mfma_f32_16x16x32_bf16 v[68:71], v[144:147], v[212:215], v[68:71]
	v_mfma_f32_16x16x32_bf16 v[64:67], v[152:155], v[212:215], v[64:67]
	v_mfma_f32_16x16x32_bf16 v[92:95], v[148:151], v[176:179], v[92:95]
	v_mfma_f32_16x16x32_bf16 v[88:91], v[156:159], v[176:179], v[88:91]
	v_mfma_f32_16x16x32_bf16 v[84:87], v[148:151], v[184:187], v[84:87]
	v_mfma_f32_16x16x32_bf16 v[80:83], v[156:159], v[184:187], v[80:83]
	v_mfma_f32_16x16x32_bf16 v[76:79], v[148:151], v[208:211], v[76:79]
	v_mfma_f32_16x16x32_bf16 v[72:75], v[156:159], v[208:211], v[72:75]
	v_mfma_f32_16x16x32_bf16 v[68:71], v[148:151], v[216:219], v[68:71]
	v_mfma_f32_16x16x32_bf16 v[64:67], v[156:159], v[216:219], v[64:67]
	s_setprio 0
	s_barrier
	s_add_i32 s60, s60, s30
	v_lshl_add_u64 v[198:199], s[8:9], 0, v[164:165]
	s_mov_b32 m0, s60
	ds_read_b128 v[172:175], v203 offset:16384
	ds_read_b128 v[176:179], v203 offset:17408
	ds_read_b128 v[180:183], v203 offset:18432
	ds_read_b128 v[184:187], v203 offset:19456
	ds_read_b128 v[204:207], v203 offset:20480
	ds_read_b128 v[208:211], v203 offset:21504
	ds_read_b128 v[212:215], v203 offset:22528
	ds_read_b128 v[216:219], v203 offset:23552
	global_load_lds_dwordx4 v[198:199], off
	s_add_i32 m0, s60, 0x2000
	s_add_u32 s60, s8, 0x40000
	v_lshl_add_u64 v[220:221], s[8:9], 0, v[160:161]
	s_addc_u32 s61, s9, 0
	s_add_i32 s62, s62, s30
	global_load_lds_dwordx4 v[220:221], off
	v_lshl_add_u64 v[222:223], s[60:61], 0, v[164:165]
	s_mov_b32 m0, s62
	v_lshl_add_u64 v[224:225], s[24:25], 0, v[162:163]
	global_load_lds_dwordx4 v[222:223], off
	v_lshl_add_u64 v[222:223], s[60:61], 0, v[160:161]
	s_add_i32 m0, s62, 0x2000
	s_nop 0
	global_load_lds_dwordx4 v[222:223], off
	v_lshl_add_u64 v[222:223], s[24:25], 0, v[166:167]
	s_mov_b32 m0, s31
	s_nop 0
	global_load_lds_dwordx4 v[222:223], off
	s_mov_b32 m0, s34
	s_nop 0
	global_load_lds_dwordx4 v[224:225], off
	s_nop 0
	s_waitcnt vmcnt(8)
	s_waitcnt lgkmcnt(0)
	s_barrier
; #define PG8_STAGE(bufoff, gbase, voff) do { _Pragma("unroll") for (int _i = 0; _i < 2; ++_i) \
;         __builtin_amdgcn_global_load_lds((const unsigned*)((const char*)(gbase) + (voff)[_i]), (PG8_LAS unsigned*)(lds + (bufoff) + ldsw + _i * 8192), 16, 0, 0); } while (0)
; #define PG8_LDA(dst, b, h) do { _Pragma("unroll") for (int m = 0; m < 4; ++m) _Pragma("unroll") for (int k = 0; k < 2; ++k) dst[m][k] = *(const PG8_LAS bf16x8*)(lds + PG8_SA(b, h) + aoff + m * 2048 + k * 1024); } while (0)
; #define PG8_LDB(dst, b, h) do { _Pragma("unroll") for (int n = 0; n < 2; ++n) _Pragma("unroll") for (int k = 0; k < 2; ++k) dst[n][k] = *(const PG8_LAS bf16x8*)(lds + PG8_SB(b, h) + boff + n * 2048 + k * 1024); } while (0)
; #define PG8_MMA(ai, bj, At, Bt) do { __builtin_amdgcn_s_setprio(1); _Pragma("unroll") for (int m = 0; m < 4; ++m) _Pragma("unroll") for (int n = 0; n < 2; ++n) _Pragma("unroll") for (int k = 0; k < 2; ++k) \
;         acc[ai][bj][m][n] = __builtin_amdgcn_mfma_f32_16x16x32_bf16(Bt[n][k], At[m][k], acc[ai][bj][m][n], 0, 0, 0); __builtin_amdgcn_s_setprio(0); } while (0)
; #define PG8_WAIT_V(n) asm volatile("s_waitcnt vmcnt(" #n ")" ::: "memory")
; #define PG8_WAIT_L(n) asm volatile("s_waitcnt lgkmcnt(" #n ")" ::: "memory")
; #define PG8_BAR __builtin_amdgcn_s_barrier()
; #define PG8_SCHED __builtin_amdgcn_sched_barrier(0)
; template <class Epi, class Sched, bool ALIGN_EPI = false, bool SP2 = false>
; __device__ __forceinline__ void gemm_phase(PG8_LAS unsigned char* lds, const Gemm g, const Sched& S, const Epi& E) {
;     ...
;             PG8_WAIT_V(8); PG8_WAIT_L(0); PG8_BAR; PG8_MMA(1, 0, At, B0); PG8_MMA(1, 1, At, B1); PG8_BAR; PG8_SCHED;
;             PG8_LDB(B0, 1, 0); PG8_LDB(B1, 1, 1); PG8_SCHED; PG8_LDA(At, 1, 0); PG8_STAGE(PG8_SA(0, 1), a2 + hstep, voffA);
;             PG8_WAIT_V(8); PG8_WAIT_L(0); PG8_BAR; PG8_MMA(0, 0, At, B0); PG8_MMA(0, 1, At, B1); PG8_BAR; PG8_SCHED;
	s_setprio 1
	s_waitcnt lgkmcnt(0)
	v_mfma_f32_16x16x32_bf16 v[60:63], v[128:131], v[172:175], v[60:63]
	v_mfma_f32_16x16x32_bf16 v[56:59], v[136:139], v[172:175], v[56:59]
	v_mfma_f32_16x16x32_bf16 v[52:55], v[128:131], v[180:183], v[52:55]
	v_mfma_f32_16x16x32_bf16 v[48:51], v[136:139], v[180:183], v[48:51]
	v_mfma_f32_16x16x32_bf16 v[44:47], v[128:131], v[204:207], v[44:47]
	v_mfma_f32_16x16x32_bf16 v[40:43], v[136:139], v[204:207], v[40:43]
	v_mfma_f32_16x16x32_bf16 v[36:39], v[128:131], v[212:215], v[36:39]
	v_mfma_f32_16x16x32_bf16 v[32:35], v[136:139], v[212:215], v[32:35]
	v_mfma_f32_16x16x32_bf16 v[60:63], v[132:135], v[176:179], v[60:63]
	v_mfma_f32_16x16x32_bf16 v[56:59], v[140:143], v[176:179], v[56:59]
	v_mfma_f32_16x16x32_bf16 v[52:55], v[132:135], v[184:187], v[52:55]
	v_mfma_f32_16x16x32_bf16 v[48:51], v[140:143], v[184:187], v[48:51]
	v_mfma_f32_16x16x32_bf16 v[44:47], v[132:135], v[208:211], v[44:47]
	v_mfma_f32_16x16x32_bf16 v[40:43], v[140:143], v[208:211], v[40:43]
	v_mfma_f32_16x16x32_bf16 v[36:39], v[132:135], v[216:219], v[36:39]
	v_mfma_f32_16x16x32_bf16 v[32:35], v[140:143], v[216:219], v[32:35]
	v_mfma_f32_16x16x32_bf16 v[28:31], v[144:147], v[172:175], v[28:31]
	v_mfma_f32_16x16x32_bf16 v[24:27], v[152:155], v[172:175], v[24:27]
	v_mfma_f32_16x16x32_bf16 v[20:23], v[144:147], v[180:183], v[20:23]
	v_mfma_f32_16x16x32_bf16 v[16:19], v[152:155], v[180:183], v[16:19]
	v_mfma_f32_16x16x32_bf16 v[12:15], v[144:147], v[204:207], v[12:15]
	v_mfma_f32_16x16x32_bf16 v[8:11], v[152:155], v[204:207], v[8:11]
	v_mfma_f32_16x16x32_bf16 v[4:7], v[144:147], v[212:215], v[4:7]
	v_mfma_f32_16x16x32_bf16 v[0:3], v[152:155], v[212:215], v[0:3]
	v_mfma_f32_16x16x32_bf16 v[28:31], v[148:151], v[176:179], v[28:31]
	v_mfma_f32_16x16x32_bf16 v[24:27], v[156:159], v[176:179], v[24:27]
	v_mfma_f32_16x16x32_bf16 v[20:23], v[148:151], v[184:187], v[20:23]
	v_mfma_f32_16x16x32_bf16 v[16:19], v[156:159], v[184:187], v[16:19]
	v_mfma_f32_16x16x32_bf16 v[12:15], v[148:151], v[208:211], v[12:15]
	v_mfma_f32_16x16x32_bf16 v[8:11], v[156:159], v[208:211], v[8:11]
	v_mfma_f32_16x16x32_bf16 v[4:7], v[148:151], v[216:219], v[4:7]
	v_mfma_f32_16x16x32_bf16 v[0:3], v[156:159], v[216:219], v[0:3]
	s_setprio 0
	s_barrier
	s_add_i32 s60, 0, 0x18000
	s_add_i32 s61, 0, 0x1c000
	v_add_u32_e32 v140, s60, v201
	v_add_u32_e32 v156, s61, v201
	ds_read_b128 v[128:131], v140
	ds_read_b128 v[132:135], v140 offset:1024
	ds_read_b128 v[136:139], v140 offset:2048
	ds_read_b128 v[140:143], v140 offset:3072
	ds_read_b128 v[144:147], v156
	ds_read_b128 v[148:151], v156 offset:1024
	ds_read_b128 v[152:155], v156 offset:2048
	ds_read_b128 v[156:159], v156 offset:3072
	s_add_u32 s24, s24, 0x40000
	s_addc_u32 s25, s25, 0
	s_mov_b32 m0, s35
	v_lshl_add_u64 v[226:227], s[24:25], 0, v[166:167]
	ds_read_b128 v[172:175], v203 offset:32768
	ds_read_b128 v[176:179], v203 offset:33792
	ds_read_b128 v[180:183], v203 offset:34816
	ds_read_b128 v[184:187], v203 offset:35840
	ds_read_b128 v[204:207], v203 offset:36864
	ds_read_b128 v[208:211], v203 offset:37888
	ds_read_b128 v[212:215], v203 offset:38912
	ds_read_b128 v[216:219], v203 offset:39936
	global_load_lds_dwordx4 v[226:227], off
	v_lshl_add_u64 v[226:227], s[24:25], 0, v[162:163]
	s_mov_b32 m0, s36
	s_nop 0
	global_load_lds_dwordx4 v[226:227], off
	s_nop 0
	s_waitcnt vmcnt(8)
	s_waitcnt lgkmcnt(0)
	s_barrier
	s_setprio 1
	s_waitcnt lgkmcnt(0)
	v_mfma_f32_16x16x32_bf16 v[124:127], v[128:131], v[172:175], v[124:127]
	v_mfma_f32_16x16x32_bf16 v[120:123], v[136:139], v[172:175], v[120:123]
	v_mfma_f32_16x16x32_bf16 v[116:119], v[128:131], v[180:183], v[116:119]
	v_mfma_f32_16x16x32_bf16 v[112:115], v[136:139], v[180:183], v[112:115]
	v_mfma_f32_16x16x32_bf16 v[108:111], v[128:131], v[204:207], v[108:111]
	v_mfma_f32_16x16x32_bf16 v[104:107], v[136:139], v[204:207], v[104:107]
	v_mfma_f32_16x16x32_bf16 v[100:103], v[128:131], v[212:215], v[100:103]
	v_mfma_f32_16x16x32_bf16 v[96:99], v[136:139], v[212:215], v[96:99]
	v_mfma_f32_16x16x32_bf16 v[124:127], v[132:135], v[176:179], v[124:127]
	v_mfma_f32_16x16x32_bf16 v[120:123], v[140:143], v[176:179], v[120:123]
	v_mfma_f32_16x16x32_bf16 v[116:119], v[132:135], v[184:187], v[116:119]
	v_mfma_f32_16x16x32_bf16 v[112:115], v[140:143], v[184:187], v[112:115]
	v_mfma_f32_16x16x32_bf16 v[108:111], v[132:135], v[208:211], v[108:111]
	v_mfma_f32_16x16x32_bf16 v[104:107], v[140:143], v[208:211], v[104:107]
	v_mfma_f32_16x16x32_bf16 v[100:103], v[132:135], v[216:219], v[100:103]
	v_mfma_f32_16x16x32_bf16 v[96:99], v[140:143], v[216:219], v[96:99]
	v_mfma_f32_16x16x32_bf16 v[92:95], v[144:147], v[172:175], v[92:95]
	v_mfma_f32_16x16x32_bf16 v[88:91], v[152:155], v[172:175], v[88:91]
	v_mfma_f32_16x16x32_bf16 v[84:87], v[144:147], v[180:183], v[84:87]
	v_mfma_f32_16x16x32_bf16 v[80:83], v[152:155], v[180:183], v[80:83]
	v_mfma_f32_16x16x32_bf16 v[76:79], v[144:147], v[204:207], v[76:79]
	v_mfma_f32_16x16x32_bf16 v[72:75], v[152:155], v[204:207], v[72:75]
	v_mfma_f32_16x16x32_bf16 v[68:71], v[144:147], v[212:215], v[68:71]
	v_mfma_f32_16x16x32_bf16 v[64:67], v[152:155], v[212:215], v[64:67]
	v_mfma_f32_16x16x32_bf16 v[92:95], v[148:151], v[176:179], v[92:95]
	v_mfma_f32_16x16x32_bf16 v[88:91], v[156:159], v[176:179], v[88:91]
	v_mfma_f32_16x16x32_bf16 v[84:87], v[148:151], v[184:187], v[84:87]
	v_mfma_f32_16x16x32_bf16 v[80:83], v[156:159], v[184:187], v[80:83]
	v_mfma_f32_16x16x32_bf16 v[76:79], v[148:151], v[208:211], v[76:79]
	v_mfma_f32_16x16x32_bf16 v[72:75], v[156:159], v[208:211], v[72:75]
	v_mfma_f32_16x16x32_bf16 v[68:71], v[148:151], v[216:219], v[68:71]
	v_mfma_f32_16x16x32_bf16 v[64:67], v[156:159], v[216:219], v[64:67]
	s_setprio 0
	s_barrier
; #define PG8_STAGE(bufoff, gbase, voff) do { _Pragma("unroll") for (int _i = 0; _i < 2; ++_i) \
;         __builtin_amdgcn_global_load_lds((const unsigned*)((const char*)(gbase) + (voff)[_i]), (PG8_LAS unsigned*)(lds + (bufoff) + ldsw + _i * 8192), 16, 0, 0); } while (0)
; #define PG8_LDA(dst, b, h) do { _Pragma("unroll") for (int m = 0; m < 4; ++m) _Pragma("unroll") for (int k = 0; k < 2; ++k) dst[m][k] = *(const PG8_LAS bf16x8*)(lds + PG8_SA(b, h) + aoff + m * 2048 + k * 1024); } while (0)
; #define PG8_MMA(ai, bj, At, Bt) do { __builtin_amdgcn_s_setprio(1); _Pragma("unroll") for (int m = 0; m < 4; ++m) _Pragma("unroll") for (int n = 0; n < 2; ++n) _Pragma("unroll") for (int k = 0; k < 2; ++k) \
;         acc[ai][bj][m][n] = __builtin_amdgcn_mfma_f32_16x16x32_bf16(Bt[n][k], At[m][k], acc[ai][bj][m][n], 0, 0, 0); __builtin_amdgcn_s_setprio(0); } while (0)
; #define PG8_WAIT_V(n) asm volatile("s_waitcnt vmcnt(" #n ")" ::: "memory")
; #define PG8_WAIT_L(n) asm volatile("s_waitcnt lgkmcnt(" #n ")" ::: "memory")
; #define PG8_BAR __builtin_amdgcn_s_barrier()
; #define PG8_SCHED __builtin_amdgcn_sched_barrier(0)
; template <class Epi, class Sched, bool ALIGN_EPI = false, bool SP2 = false>
; __device__ __forceinline__ void gemm_phase(PG8_LAS unsigned char* lds, const Gemm g, const Sched& S, const Epi& E) {
;     ...
;             PG8_LDA(At, 1, 1); PG8_STAGE(PG8_SB(1, 0), b3, voffB); PG8_STAGE(PG8_SB(1, 1), b3 + hstep, voffB); PG8_STAGE(PG8_SA(1, 0), a3, voffA);
;             PG8_WAIT_V(8); PG8_WAIT_L(0); PG8_BAR; PG8_MMA(1, 0, At, B0); PG8_MMA(1, 1, At, B1); PG8_BAR; PG8_SCHED;
	s_add_i32 s24, s60, s30
	v_lshl_add_u64 v[198:199], v[198:199], 0, s[78:79]
	s_mov_b32 m0, s24
	ds_read_b128 v[172:175], v203 offset:49152
	ds_read_b128 v[176:179], v203 offset:50176
	ds_read_b128 v[180:183], v203 offset:51200
	ds_read_b128 v[184:187], v203 offset:52224
	ds_read_b128 v[204:207], v203 offset:53248
	ds_read_b128 v[208:211], v203 offset:54272
	ds_read_b128 v[212:215], v203 offset:55296
	ds_read_b128 v[216:219], v203 offset:56320
	global_load_lds_dwordx4 v[198:199], off
	s_add_i32 m0, s24, 0x2000
	s_add_u32 s8, s8, 0x40080
	v_lshl_add_u64 v[198:199], v[220:221], 0, s[78:79]
	s_addc_u32 s9, s9, 0
	s_add_i32 s24, s61, s30
	global_load_lds_dwordx4 v[198:199], off
	v_lshl_add_u64 v[198:199], s[8:9], 0, v[164:165]
	s_mov_b32 m0, s24
	s_nop 0
	global_load_lds_dwordx4 v[198:199], off
	v_lshl_add_u64 v[198:199], s[8:9], 0, v[160:161]
	s_add_i32 m0, s24, 0x2000
	s_nop 0
	global_load_lds_dwordx4 v[198:199], off
	v_lshl_add_u64 v[198:199], v[222:223], 0, s[78:79]
	s_mov_b32 m0, s37
	s_nop 0
	global_load_lds_dwordx4 v[198:199], off
	v_lshl_add_u64 v[198:199], v[224:225], 0, s[78:79]
	s_mov_b32 m0, s40
	s_nop 0
	global_load_lds_dwordx4 v[198:199], off
	s_waitcnt vmcnt(8)
	s_waitcnt lgkmcnt(0)
	s_barrier
	s_setprio 1
	s_waitcnt lgkmcnt(0)
	v_mfma_f32_16x16x32_bf16 v[60:63], v[128:131], v[172:175], v[60:63]
	v_mfma_f32_16x16x32_bf16 v[56:59], v[136:139], v[172:175], v[56:59]
	v_mfma_f32_16x16x32_bf16 v[52:55], v[128:131], v[180:183], v[52:55]
	v_mfma_f32_16x16x32_bf16 v[48:51], v[136:139], v[180:183], v[48:51]
	v_mfma_f32_16x16x32_bf16 v[44:47], v[128:131], v[204:207], v[44:47]
	v_mfma_f32_16x16x32_bf16 v[40:43], v[136:139], v[204:207], v[40:43]
	v_mfma_f32_16x16x32_bf16 v[36:39], v[128:131], v[212:215], v[36:39]
	v_mfma_f32_16x16x32_bf16 v[32:35], v[136:139], v[212:215], v[32:35]
	v_mfma_f32_16x16x32_bf16 v[60:63], v[132:135], v[176:179], v[60:63]
	v_mfma_f32_16x16x32_bf16 v[56:59], v[140:143], v[176:179], v[56:59]
	v_mfma_f32_16x16x32_bf16 v[52:55], v[132:135], v[184:187], v[52:55]
	v_mfma_f32_16x16x32_bf16 v[48:51], v[140:143], v[184:187], v[48:51]
	v_mfma_f32_16x16x32_bf16 v[44:47], v[132:135], v[208:211], v[44:47]
	v_mfma_f32_16x16x32_bf16 v[40:43], v[140:143], v[208:211], v[40:43]
	v_mfma_f32_16x16x32_bf16 v[36:39], v[132:135], v[216:219], v[36:39]
	v_mfma_f32_16x16x32_bf16 v[32:35], v[140:143], v[216:219], v[32:35]
	v_mfma_f32_16x16x32_bf16 v[28:31], v[144:147], v[172:175], v[28:31]
	v_mfma_f32_16x16x32_bf16 v[24:27], v[152:155], v[172:175], v[24:27]
	v_mfma_f32_16x16x32_bf16 v[20:23], v[144:147], v[180:183], v[20:23]
	v_mfma_f32_16x16x32_bf16 v[16:19], v[152:155], v[180:183], v[16:19]
	v_mfma_f32_16x16x32_bf16 v[12:15], v[144:147], v[204:207], v[12:15]
	v_mfma_f32_16x16x32_bf16 v[8:11], v[152:155], v[204:207], v[8:11]
	v_mfma_f32_16x16x32_bf16 v[4:7], v[144:147], v[212:215], v[4:7]
	v_mfma_f32_16x16x32_bf16 v[0:3], v[152:155], v[212:215], v[0:3]
	v_mfma_f32_16x16x32_bf16 v[28:31], v[148:151], v[176:179], v[28:31]
	v_mfma_f32_16x16x32_bf16 v[24:27], v[156:159], v[176:179], v[24:27]
	v_mfma_f32_16x16x32_bf16 v[20:23], v[148:151], v[184:187], v[20:23]
	v_mfma_f32_16x16x32_bf16 v[16:19], v[156:159], v[184:187], v[16:19]
	v_mfma_f32_16x16x32_bf16 v[12:15], v[148:151], v[208:211], v[12:15]
	v_mfma_f32_16x16x32_bf16 v[8:11], v[156:159], v[208:211], v[8:11]
	v_mfma_f32_16x16x32_bf16 v[4:7], v[148:151], v[216:219], v[4:7]
	v_mfma_f32_16x16x32_bf16 v[0:3], v[156:159], v[216:219], v[0:3]
	s_setprio 0
	s_barrier
	s_add_i32 s58, s58, 2
	s_add_u32 s6, s6, 0x100
	s_addc_u32 s7, s7, 0
	s_add_u32 s45, s45, 0x100
	s_addc_u32 s52, s52, 0
	s_cmp_gt_u32 s58, 13
	s_cbranch_scc0 .LBB0_424
	s_and_b64 vcc, exec, s[14:15]
	s_cbranch_vccz .LBB0_427
	s_barrier

; #define PG8_STAGE(bufoff, gbase, voff) do { _Pragma("unroll") for (int _i = 0; _i < 2; ++_i) \
;         __builtin_amdgcn_global_load_lds((const unsigned*)((const char*)(gbase) + (voff)[_i]), (PG8_LAS unsigned*)(lds + (bufoff) + ldsw + _i * 8192), 16, 0, 0); } while (0)
; #define PG8_LDA(dst, b, h) do { _Pragma("unroll") for (int m = 0; m < 4; ++m) _Pragma("unroll") for (int k = 0; k < 2; ++k) dst[m][k] = *(const PG8_LAS bf16x8*)(lds + PG8_SA(b, h) + aoff + m * 2048 + k * 1024); } while (0)
; #define PG8_LDB(dst, b, h) do { _Pragma("unroll") for (int n = 0; n < 2; ++n) _Pragma("unroll") for (int k = 0; k < 2; ++k) dst[n][k] = *(const PG8_LAS bf16x8*)(lds + PG8_SB(b, h) + boff + n * 2048 + k * 1024); } while (0)
; #define PG8_MMA(ai, bj, At, Bt) do { __builtin_amdgcn_s_setprio(1); _Pragma("unroll") for (int m = 0; m < 4; ++m) _Pragma("unroll") for (int n = 0; n < 2; ++n) _Pragma("unroll") for (int k = 0; k < 2; ++k) \
;         acc[ai][bj][m][n] = __builtin_amdgcn_mfma_f32_16x16x32_bf16(Bt[n][k], At[m][k], acc[ai][bj][m][n], 0, 0, 0); __builtin_amdgcn_s_setprio(0); } while (0)
; #define PG8_WAIT_V(n) asm volatile("s_waitcnt vmcnt(" #n ")" ::: "memory")
; #define PG8_WAIT_L(n) asm volatile("s_waitcnt lgkmcnt(" #n ")" ::: "memory")
; #define PG8_BAR __builtin_amdgcn_s_barrier()
; #define PG8_SCHED __builtin_amdgcn_sched_barrier(0)
; template <class Epi, class Sched, bool ALIGN_EPI = false, bool SP2 = false>
; __device__ __forceinline__ void gemm_phase(PG8_LAS unsigned char* lds, const Gemm g, const Sched& S, const Epi& E) {
;     ...
;             const bool last = (t == nt - 2);
;             const char* a1 = cA + (size_t)(t + 1) * kstep;
;             const char* a2 = last ? nA : cA + (size_t)(t + 2) * kstep; const char* b2 = last ? nB : cB + (size_t)(t + 2) * kstep;
;             const char* a3 = a2 + kstep; const char* b3 = b2 + kstep;
;             if (last && has_next) S.a_ready(nxt);
;             if constexpr (SP2) {
;             PG8_LDB(B0, 0, 0); PG8_LDB(B1, 0, 1); PG8_SCHED; PG8_LDA(At, 0, 0); PG8_STAGE(PG8_SA(1, 1), a1 + hstep, voffA);
;             PG8_WAIT_V(8); PG8_WAIT_L(0); PG8_BAR; PG8_MMA(0, 0, At, B0); PG8_MMA(0, 1, At, B1); PG8_BAR; PG8_SCHED;
;             PG8_LDA(At, 0, 1); PG8_STAGE(PG8_SB(0, 0), b2, voffB); PG8_STAGE(PG8_SB(0, 1), b2 + hstep, voffB); PG8_STAGE(PG8_SA(0, 0), a2, voffA);
.LBB0_596:
	s_add_u32 s26, s24, 0xfff80080
	s_addc_u32 s27, s25, -1
	s_add_i32 s60, 0, 0x10000
	s_cmp_eq_u32 s67, 28
	s_cselect_b32 s29, s19, s27
	s_cselect_b32 s28, s58, s26
	s_cselect_b32 s27, s17, s66
	s_cselect_b32 s26, s62, s63
	s_add_i32 s68, 0, 0x14000
	v_add_u32_e32 v124, s60, v239
	v_add_u32_e32 v148, s68, v239
	ds_read_b128 v[112:115], v124
	ds_read_b128 v[116:119], v124 offset:1024
	ds_read_b128 v[120:123], v124 offset:2048
	ds_read_b128 v[124:127], v124 offset:3072
	ds_read_b128 v[132:135], v148
	ds_read_b128 v[140:143], v148 offset:1024
	ds_read_b128 v[144:147], v148 offset:2048
	ds_read_b128 v[148:151], v148 offset:3072
	v_lshl_add_u64 v[212:213], s[24:25], 0, v[204:205]
	s_add_i32 m0, s36, 0xc000
	ds_read_b128 v[156:159], v241
	ds_read_b128 v[164:167], v241 offset:1024
	ds_read_b128 v[168:171], v241 offset:2048
	ds_read_b128 v[172:175], v241 offset:3072
	ds_read_b128 v[176:179], v241 offset:4096
	ds_read_b128 v[180:183], v241 offset:5120
	ds_read_b128 v[184:187], v241 offset:6144
	ds_read_b128 v[208:211], v241 offset:7168
	global_load_lds_dwordx4 v[212:213], off
	v_lshl_add_u64 v[212:213], s[24:25], 0, v[206:207]
	s_add_i32 m0, s36, 0xe000
	s_nop 0
	global_load_lds_dwordx4 v[212:213], off
	s_nop 0
	s_waitcnt vmcnt(8)
	s_waitcnt lgkmcnt(0)
	s_barrier
	s_setprio 1
	s_waitcnt lgkmcnt(0)
	v_mfma_f32_16x16x32_bf16 v[160:163], v[112:115], v[156:159], v[160:163]
	v_mfma_f32_16x16x32_bf16 v[152:155], v[120:123], v[156:159], v[152:155]
	v_mfma_f32_16x16x32_bf16 v[108:111], v[112:115], v[168:171], v[108:111]
	v_mfma_f32_16x16x32_bf16 v[104:107], v[120:123], v[168:171], v[104:107]
	v_mfma_f32_16x16x32_bf16 v[92:95], v[112:115], v[176:179], v[92:95]
	v_mfma_f32_16x16x32_bf16 v[88:91], v[120:123], v[176:179], v[88:91]
	v_mfma_f32_16x16x32_bf16 v[76:79], v[112:115], v[184:187], v[76:79]
	v_mfma_f32_16x16x32_bf16 v[72:75], v[120:123], v[184:187], v[72:75]
	v_mfma_f32_16x16x32_bf16 v[160:163], v[116:119], v[164:167], v[160:163]
	v_mfma_f32_16x16x32_bf16 v[152:155], v[124:127], v[164:167], v[152:155]
	v_mfma_f32_16x16x32_bf16 v[108:111], v[116:119], v[172:175], v[108:111]
	v_mfma_f32_16x16x32_bf16 v[104:107], v[124:127], v[172:175], v[104:107]
	v_mfma_f32_16x16x32_bf16 v[92:95], v[116:119], v[180:183], v[92:95]
	v_mfma_f32_16x16x32_bf16 v[88:91], v[124:127], v[180:183], v[88:91]
	v_mfma_f32_16x16x32_bf16 v[76:79], v[116:119], v[208:211], v[76:79]
	v_mfma_f32_16x16x32_bf16 v[72:75], v[124:127], v[208:211], v[72:75]
	v_mfma_f32_16x16x32_bf16 v[136:139], v[132:135], v[156:159], v[136:139]
	v_mfma_f32_16x16x32_bf16 v[128:131], v[144:147], v[156:159], v[128:131]
	v_mfma_f32_16x16x32_bf16 v[100:103], v[132:135], v[168:171], v[100:103]
	v_mfma_f32_16x16x32_bf16 v[96:99], v[144:147], v[168:171], v[96:99]
	v_mfma_f32_16x16x32_bf16 v[84:87], v[132:135], v[176:179], v[84:87]
	v_mfma_f32_16x16x32_bf16 v[80:83], v[144:147], v[176:179], v[80:83]
	v_mfma_f32_16x16x32_bf16 v[68:71], v[132:135], v[184:187], v[68:71]
	v_mfma_f32_16x16x32_bf16 v[64:67], v[144:147], v[184:187], v[64:67]
	v_mfma_f32_16x16x32_bf16 v[136:139], v[140:143], v[164:167], v[136:139]
	v_mfma_f32_16x16x32_bf16 v[128:131], v[148:151], v[164:167], v[128:131]
	v_mfma_f32_16x16x32_bf16 v[100:103], v[140:143], v[172:175], v[100:103]
	v_mfma_f32_16x16x32_bf16 v[96:99], v[148:151], v[172:175], v[96:99]
	v_mfma_f32_16x16x32_bf16 v[84:87], v[140:143], v[180:183], v[84:87]
	v_mfma_f32_16x16x32_bf16 v[80:83], v[148:151], v[180:183], v[80:83]
	v_mfma_f32_16x16x32_bf16 v[68:71], v[140:143], v[208:211], v[68:71]
	v_mfma_f32_16x16x32_bf16 v[64:67], v[148:151], v[208:211], v[64:67]
	s_setprio 0
	s_barrier
	s_add_i32 s60, s60, s35
	v_lshl_add_u64 v[212:213], s[26:27], 0, v[188:189]
	s_mov_b32 m0, s60
	ds_read_b128 v[156:159], v241 offset:16384
	ds_read_b128 v[164:167], v241 offset:17408
	ds_read_b128 v[168:171], v241 offset:18432
	ds_read_b128 v[172:175], v241 offset:19456
	ds_read_b128 v[176:179], v241 offset:20480
	ds_read_b128 v[180:183], v241 offset:21504
	ds_read_b128 v[184:187], v241 offset:22528
	ds_read_b128 v[208:211], v241 offset:23552
	global_load_lds_dwordx4 v[212:213], off
	s_add_i32 m0, s60, 0x2000
	s_add_u32 s60, s26, 0x80000
	v_lshl_add_u64 v[214:215], s[26:27], 0, v[198:199]
	s_addc_u32 s61, s27, 0
	s_add_i32 s68, s68, s35
	global_load_lds_dwordx4 v[214:215], off
	v_lshl_add_u64 v[216:217], s[60:61], 0, v[188:189]
	s_mov_b32 m0, s68
	v_lshl_add_u64 v[218:219], s[28:29], 0, v[200:201]
	global_load_lds_dwordx4 v[216:217], off
	v_lshl_add_u64 v[216:217], s[60:61], 0, v[198:199]
	s_add_i32 m0, s68, 0x2000
	s_nop 0
	global_load_lds_dwordx4 v[216:217], off
	v_lshl_add_u64 v[216:217], s[28:29], 0, v[202:203]
	s_mov_b32 m0, s36
	s_nop 0
	global_load_lds_dwordx4 v[216:217], off
	s_mov_b32 m0, s37
	s_nop 0
	global_load_lds_dwordx4 v[218:219], off
	s_nop 0
	s_waitcnt vmcnt(8)
	s_waitcnt lgkmcnt(0)
	s_barrier
; #define PG8_STAGE(bufoff, gbase, voff) do { _Pragma("unroll") for (int _i = 0; _i < 2; ++_i) \
;         __builtin_amdgcn_global_load_lds((const unsigned*)((const char*)(gbase) + (voff)[_i]), (PG8_LAS unsigned*)(lds + (bufoff) + ldsw + _i * 8192), 16, 0, 0); } while (0)
; #define PG8_LDA(dst, b, h) do { _Pragma("unroll") for (int m = 0; m < 4; ++m) _Pragma("unroll") for (int k = 0; k < 2; ++k) dst[m][k] = *(const PG8_LAS bf16x8*)(lds + PG8_SA(b, h) + aoff + m * 2048 + k * 1024); } while (0)
; #define PG8_LDB(dst, b, h) do { _Pragma("unroll") for (int n = 0; n < 2; ++n) _Pragma("unroll") for (int k = 0; k < 2; ++k) dst[n][k] = *(const PG8_LAS bf16x8*)(lds + PG8_SB(b, h) + boff + n * 2048 + k * 1024); } while (0)
; #define PG8_MMA(ai, bj, At, Bt) do { __builtin_amdgcn_s_setprio(1); _Pragma("unroll") for (int m = 0; m < 4; ++m) _Pragma("unroll") for (int n = 0; n < 2; ++n) _Pragma("unroll") for (int k = 0; k < 2; ++k) \
;         acc[ai][bj][m][n] = __builtin_amdgcn_mfma_f32_16x16x32_bf16(Bt[n][k], At[m][k], acc[ai][bj][m][n], 0, 0, 0); __builtin_amdgcn_s_setprio(0); } while (0)
; #define PG8_WAIT_V(n) asm volatile("s_waitcnt vmcnt(" #n ")" ::: "memory")
; #define PG8_WAIT_L(n) asm volatile("s_waitcnt lgkmcnt(" #n ")" ::: "memory")
; #define PG8_BAR __builtin_amdgcn_s_barrier()
; #define PG8_SCHED __builtin_amdgcn_sched_barrier(0)
; template <class Epi, class Sched, bool ALIGN_EPI = false, bool SP2 = false>
; __device__ __forceinline__ void gemm_phase(PG8_LAS unsigned char* lds, const Gemm g, const Sched& S, const Epi& E) {
;     ...
;             PG8_WAIT_V(8); PG8_WAIT_L(0); PG8_BAR; PG8_MMA(1, 0, At, B0); PG8_MMA(1, 1, At, B1); PG8_BAR; PG8_SCHED;
;             PG8_LDB(B0, 1, 0); PG8_LDB(B1, 1, 1); PG8_SCHED; PG8_LDA(At, 1, 0); PG8_STAGE(PG8_SA(0, 1), a2 + hstep, voffA);
;             PG8_WAIT_V(8); PG8_WAIT_L(0); PG8_BAR; PG8_MMA(0, 0, At, B0); PG8_MMA(0, 1, At, B1); PG8_BAR; PG8_SCHED;
	s_setprio 1
	s_waitcnt lgkmcnt(0)
	v_mfma_f32_16x16x32_bf16 v[60:63], v[112:115], v[156:159], v[60:63]
	v_mfma_f32_16x16x32_bf16 v[56:59], v[120:123], v[156:159], v[56:59]
	v_mfma_f32_16x16x32_bf16 v[44:47], v[112:115], v[168:171], v[44:47]
	v_mfma_f32_16x16x32_bf16 v[40:43], v[120:123], v[168:171], v[40:43]
	v_mfma_f32_16x16x32_bf16 v[28:31], v[112:115], v[176:179], v[28:31]
	v_mfma_f32_16x16x32_bf16 v[24:27], v[120:123], v[176:179], v[24:27]
	v_mfma_f32_16x16x32_bf16 v[12:15], v[112:115], v[184:187], v[12:15]
	v_mfma_f32_16x16x32_bf16 v[8:11], v[120:123], v[184:187], v[8:11]
	v_mfma_f32_16x16x32_bf16 v[60:63], v[116:119], v[164:167], v[60:63]
	v_mfma_f32_16x16x32_bf16 v[56:59], v[124:127], v[164:167], v[56:59]
	v_mfma_f32_16x16x32_bf16 v[44:47], v[116:119], v[172:175], v[44:47]
	v_mfma_f32_16x16x32_bf16 v[40:43], v[124:127], v[172:175], v[40:43]
	v_mfma_f32_16x16x32_bf16 v[28:31], v[116:119], v[180:183], v[28:31]
	v_mfma_f32_16x16x32_bf16 v[24:27], v[124:127], v[180:183], v[24:27]
	v_mfma_f32_16x16x32_bf16 v[12:15], v[116:119], v[208:211], v[12:15]
	v_mfma_f32_16x16x32_bf16 v[8:11], v[124:127], v[208:211], v[8:11]
	v_mfma_f32_16x16x32_bf16 v[52:55], v[132:135], v[156:159], v[52:55]
	v_mfma_f32_16x16x32_bf16 v[48:51], v[144:147], v[156:159], v[48:51]
	v_mfma_f32_16x16x32_bf16 v[36:39], v[132:135], v[168:171], v[36:39]
	v_mfma_f32_16x16x32_bf16 v[32:35], v[144:147], v[168:171], v[32:35]
	v_mfma_f32_16x16x32_bf16 v[20:23], v[132:135], v[176:179], v[20:23]
	v_mfma_f32_16x16x32_bf16 v[16:19], v[144:147], v[176:179], v[16:19]
	v_mfma_f32_16x16x32_bf16 v[4:7], v[132:135], v[184:187], v[4:7]
	v_mfma_f32_16x16x32_bf16 v[0:3], v[144:147], v[184:187], v[0:3]
	v_mfma_f32_16x16x32_bf16 v[52:55], v[140:143], v[164:167], v[52:55]
	v_mfma_f32_16x16x32_bf16 v[48:51], v[148:151], v[164:167], v[48:51]
	v_mfma_f32_16x16x32_bf16 v[36:39], v[140:143], v[172:175], v[36:39]
	v_mfma_f32_16x16x32_bf16 v[32:35], v[148:151], v[172:175], v[32:35]
	v_mfma_f32_16x16x32_bf16 v[20:23], v[140:143], v[180:183], v[20:23]
	v_mfma_f32_16x16x32_bf16 v[16:19], v[148:151], v[180:183], v[16:19]
	v_mfma_f32_16x16x32_bf16 v[4:7], v[140:143], v[208:211], v[4:7]
	v_mfma_f32_16x16x32_bf16 v[0:3], v[148:151], v[208:211], v[0:3]
	s_setprio 0
	s_barrier
	s_add_i32 s60, 0, 0x18000
	s_add_i32 s61, 0, 0x1c000
	v_add_u32_e32 v124, s60, v239
	v_add_u32_e32 v148, s61, v239
	ds_read_b128 v[112:115], v124
	ds_read_b128 v[116:119], v124 offset:1024
	ds_read_b128 v[120:123], v124 offset:2048
	ds_read_b128 v[124:127], v124 offset:3072
	ds_read_b128 v[132:135], v148
	ds_read_b128 v[140:143], v148 offset:1024
	ds_read_b128 v[144:147], v148 offset:2048
	ds_read_b128 v[148:151], v148 offset:3072
	s_add_u32 s28, s28, 0x80000
	s_addc_u32 s29, s29, 0
	s_mov_b32 m0, s38
	v_lshl_add_u64 v[220:221], s[28:29], 0, v[202:203]
	ds_read_b128 v[156:159], v241 offset:32768
	ds_read_b128 v[164:167], v241 offset:33792
	ds_read_b128 v[168:171], v241 offset:34816
	ds_read_b128 v[172:175], v241 offset:35840
	ds_read_b128 v[176:179], v241 offset:36864
	ds_read_b128 v[180:183], v241 offset:37888
	ds_read_b128 v[184:187], v241 offset:38912
	ds_read_b128 v[208:211], v241 offset:39936
	global_load_lds_dwordx4 v[220:221], off
	v_lshl_add_u64 v[220:221], s[28:29], 0, v[200:201]
	s_mov_b32 m0, s39
	s_nop 0
	global_load_lds_dwordx4 v[220:221], off
	s_nop 0
	s_waitcnt vmcnt(8)
	s_waitcnt lgkmcnt(0)
	s_barrier
	s_setprio 1
	s_waitcnt lgkmcnt(0)
	v_mfma_f32_16x16x32_bf16 v[160:163], v[112:115], v[156:159], v[160:163]
	v_mfma_f32_16x16x32_bf16 v[152:155], v[120:123], v[156:159], v[152:155]
	v_mfma_f32_16x16x32_bf16 v[108:111], v[112:115], v[168:171], v[108:111]
	v_mfma_f32_16x16x32_bf16 v[104:107], v[120:123], v[168:171], v[104:107]
	v_mfma_f32_16x16x32_bf16 v[92:95], v[112:115], v[176:179], v[92:95]
	v_mfma_f32_16x16x32_bf16 v[88:91], v[120:123], v[176:179], v[88:91]
	v_mfma_f32_16x16x32_bf16 v[76:79], v[112:115], v[184:187], v[76:79]
	v_mfma_f32_16x16x32_bf16 v[72:75], v[120:123], v[184:187], v[72:75]
	v_mfma_f32_16x16x32_bf16 v[160:163], v[116:119], v[164:167], v[160:163]
	v_mfma_f32_16x16x32_bf16 v[152:155], v[124:127], v[164:167], v[152:155]
	v_mfma_f32_16x16x32_bf16 v[108:111], v[116:119], v[172:175], v[108:111]
	v_mfma_f32_16x16x32_bf16 v[104:107], v[124:127], v[172:175], v[104:107]
	v_mfma_f32_16x16x32_bf16 v[92:95], v[116:119], v[180:183], v[92:95]
	v_mfma_f32_16x16x32_bf16 v[88:91], v[124:127], v[180:183], v[88:91]
	v_mfma_f32_16x16x32_bf16 v[76:79], v[116:119], v[208:211], v[76:79]
	v_mfma_f32_16x16x32_bf16 v[72:75], v[124:127], v[208:211], v[72:75]
	v_mfma_f32_16x16x32_bf16 v[136:139], v[132:135], v[156:159], v[136:139]
	v_mfma_f32_16x16x32_bf16 v[128:131], v[144:147], v[156:159], v[128:131]
	v_mfma_f32_16x16x32_bf16 v[100:103], v[132:135], v[168:171], v[100:103]
	v_mfma_f32_16x16x32_bf16 v[96:99], v[144:147], v[168:171], v[96:99]
	v_mfma_f32_16x16x32_bf16 v[84:87], v[132:135], v[176:179], v[84:87]
	v_mfma_f32_16x16x32_bf16 v[80:83], v[144:147], v[176:179], v[80:83]
	v_mfma_f32_16x16x32_bf16 v[68:71], v[132:135], v[184:187], v[68:71]
	v_mfma_f32_16x16x32_bf16 v[64:67], v[144:147], v[184:187], v[64:67]
	v_mfma_f32_16x16x32_bf16 v[136:139], v[140:143], v[164:167], v[136:139]
	v_mfma_f32_16x16x32_bf16 v[128:131], v[148:151], v[164:167], v[128:131]
	v_mfma_f32_16x16x32_bf16 v[100:103], v[140:143], v[172:175], v[100:103]
	v_mfma_f32_16x16x32_bf16 v[96:99], v[148:151], v[172:175], v[96:99]
	v_mfma_f32_16x16x32_bf16 v[84:87], v[140:143], v[180:183], v[84:87]
	v_mfma_f32_16x16x32_bf16 v[80:83], v[148:151], v[180:183], v[80:83]
	v_mfma_f32_16x16x32_bf16 v[68:71], v[140:143], v[208:211], v[68:71]
	v_mfma_f32_16x16x32_bf16 v[64:67], v[148:151], v[208:211], v[64:67]
	s_setprio 0
	s_barrier
; #define PG8_STAGE(bufoff, gbase, voff) do { _Pragma("unroll") for (int _i = 0; _i < 2; ++_i) \
;         __builtin_amdgcn_global_load_lds((const unsigned*)((const char*)(gbase) + (voff)[_i]), (PG8_LAS unsigned*)(lds + (bufoff) + ldsw + _i * 8192), 16, 0, 0); } while (0)
; #define PG8_LDA(dst, b, h) do { _Pragma("unroll") for (int m = 0; m < 4; ++m) _Pragma("unroll") for (int k = 0; k < 2; ++k) dst[m][k] = *(const PG8_LAS bf16x8*)(lds + PG8_SA(b, h) + aoff + m * 2048 + k * 1024); } while (0)
; #define PG8_MMA(ai, bj, At, Bt) do { __builtin_amdgcn_s_setprio(1); _Pragma("unroll") for (int m = 0; m < 4; ++m) _Pragma("unroll") for (int n = 0; n < 2; ++n) _Pragma("unroll") for (int k = 0; k < 2; ++k) \
;         acc[ai][bj][m][n] = __builtin_amdgcn_mfma_f32_16x16x32_bf16(Bt[n][k], At[m][k], acc[ai][bj][m][n], 0, 0, 0); __builtin_amdgcn_s_setprio(0); } while (0)
; #define PG8_WAIT_V(n) asm volatile("s_waitcnt vmcnt(" #n ")" ::: "memory")
; #define PG8_WAIT_L(n) asm volatile("s_waitcnt lgkmcnt(" #n ")" ::: "memory")
; #define PG8_BAR __builtin_amdgcn_s_barrier()
; #define PG8_SCHED __builtin_amdgcn_sched_barrier(0)
; template <class Epi, class Sched, bool ALIGN_EPI = false, bool SP2 = false>
; __device__ __forceinline__ void gemm_phase(PG8_LAS unsigned char* lds, const Gemm g, const Sched& S, const Epi& E) {
;     ...
;             PG8_LDA(At, 1, 1); PG8_STAGE(PG8_SB(1, 0), b3, voffB); PG8_STAGE(PG8_SB(1, 1), b3 + hstep, voffB); PG8_STAGE(PG8_SA(1, 0), a3, voffA);
;             PG8_WAIT_V(8); PG8_WAIT_L(0); PG8_BAR; PG8_MMA(1, 0, At, B0); PG8_MMA(1, 1, At, B1); PG8_BAR; PG8_SCHED;
	s_add_i32 s28, s60, s35
	v_lshl_add_u64 v[212:213], v[212:213], 0, s[78:79]
	s_mov_b32 m0, s28
	ds_read_b128 v[156:159], v241 offset:49152
	ds_read_b128 v[164:167], v241 offset:50176
	ds_read_b128 v[168:171], v241 offset:51200
	ds_read_b128 v[172:175], v241 offset:52224
	ds_read_b128 v[176:179], v241 offset:53248
	ds_read_b128 v[180:183], v241 offset:54272
	ds_read_b128 v[184:187], v241 offset:55296
	ds_read_b128 v[208:211], v241 offset:56320
	global_load_lds_dwordx4 v[212:213], off
	s_add_i32 m0, s28, 0x2000
	s_add_u32 s26, s26, 0x80080
	v_lshl_add_u64 v[212:213], v[214:215], 0, s[78:79]
	s_addc_u32 s27, s27, 0
	s_add_i32 s28, s61, s35
	global_load_lds_dwordx4 v[212:213], off
	v_lshl_add_u64 v[212:213], s[26:27], 0, v[188:189]
	s_mov_b32 m0, s28
	s_nop 0
	global_load_lds_dwordx4 v[212:213], off
	v_lshl_add_u64 v[212:213], s[26:27], 0, v[198:199]
	s_add_i32 m0, s28, 0x2000
	s_nop 0
	global_load_lds_dwordx4 v[212:213], off
	v_lshl_add_u64 v[212:213], v[216:217], 0, s[78:79]
	s_mov_b32 m0, s40
	s_nop 0
	global_load_lds_dwordx4 v[212:213], off
	v_lshl_add_u64 v[212:213], v[218:219], 0, s[78:79]
	s_mov_b32 m0, s41
	s_nop 0
	global_load_lds_dwordx4 v[212:213], off
	s_waitcnt vmcnt(8)
	s_waitcnt lgkmcnt(0)
	s_barrier
	s_setprio 1
	s_waitcnt lgkmcnt(0)
	v_mfma_f32_16x16x32_bf16 v[60:63], v[112:115], v[156:159], v[60:63]
	v_mfma_f32_16x16x32_bf16 v[56:59], v[120:123], v[156:159], v[56:59]
	v_mfma_f32_16x16x32_bf16 v[44:47], v[112:115], v[168:171], v[44:47]
	v_mfma_f32_16x16x32_bf16 v[40:43], v[120:123], v[168:171], v[40:43]
	v_mfma_f32_16x16x32_bf16 v[28:31], v[112:115], v[176:179], v[28:31]
	v_mfma_f32_16x16x32_bf16 v[24:27], v[120:123], v[176:179], v[24:27]
	v_mfma_f32_16x16x32_bf16 v[12:15], v[112:115], v[184:187], v[12:15]
	v_mfma_f32_16x16x32_bf16 v[8:11], v[120:123], v[184:187], v[8:11]
	v_mfma_f32_16x16x32_bf16 v[60:63], v[116:119], v[164:167], v[60:63]
	v_mfma_f32_16x16x32_bf16 v[56:59], v[124:127], v[164:167], v[56:59]
	v_mfma_f32_16x16x32_bf16 v[44:47], v[116:119], v[172:175], v[44:47]
	v_mfma_f32_16x16x32_bf16 v[40:43], v[124:127], v[172:175], v[40:43]
	v_mfma_f32_16x16x32_bf16 v[28:31], v[116:119], v[180:183], v[28:31]
	v_mfma_f32_16x16x32_bf16 v[24:27], v[124:127], v[180:183], v[24:27]
	v_mfma_f32_16x16x32_bf16 v[12:15], v[116:119], v[208:211], v[12:15]
	v_mfma_f32_16x16x32_bf16 v[8:11], v[124:127], v[208:211], v[8:11]
	v_mfma_f32_16x16x32_bf16 v[52:55], v[132:135], v[156:159], v[52:55]
	v_mfma_f32_16x16x32_bf16 v[48:51], v[144:147], v[156:159], v[48:51]
	v_mfma_f32_16x16x32_bf16 v[36:39], v[132:135], v[168:171], v[36:39]
	v_mfma_f32_16x16x32_bf16 v[32:35], v[144:147], v[168:171], v[32:35]
	v_mfma_f32_16x16x32_bf16 v[20:23], v[132:135], v[176:179], v[20:23]
	v_mfma_f32_16x16x32_bf16 v[16:19], v[144:147], v[176:179], v[16:19]
	v_mfma_f32_16x16x32_bf16 v[4:7], v[132:135], v[184:187], v[4:7]
	v_mfma_f32_16x16x32_bf16 v[0:3], v[144:147], v[184:187], v[0:3]
	v_mfma_f32_16x16x32_bf16 v[52:55], v[140:143], v[164:167], v[52:55]
	v_mfma_f32_16x16x32_bf16 v[48:51], v[148:151], v[164:167], v[48:51]
	v_mfma_f32_16x16x32_bf16 v[36:39], v[140:143], v[172:175], v[36:39]
	v_mfma_f32_16x16x32_bf16 v[32:35], v[148:151], v[172:175], v[32:35]
	v_mfma_f32_16x16x32_bf16 v[20:23], v[140:143], v[180:183], v[20:23]
	v_mfma_f32_16x16x32_bf16 v[16:19], v[148:151], v[180:183], v[16:19]
	v_mfma_f32_16x16x32_bf16 v[4:7], v[140:143], v[208:211], v[4:7]
	v_mfma_f32_16x16x32_bf16 v[0:3], v[148:151], v[208:211], v[0:3]
	s_setprio 0
	s_barrier
	s_add_i32 s67, s67, 2
	s_add_u32 s24, s24, 0x100
	s_addc_u32 s25, s25, 0
	s_add_u32 s63, s63, 0x100
	s_addc_u32 s66, s66, 0
	s_cmp_gt_u32 s67, 29
	s_cbranch_scc0 .LBB0_596
	s_and_b64 vcc, exec, s[14:15]
	s_cbranch_vccz .LBB0_599
	s_barrier

; #define PG8_STAGE(bufoff, gbase, voff) do { _Pragma("unroll") for (int _i = 0; _i < 2; ++_i) \
;         __builtin_amdgcn_global_load_lds((const unsigned*)((const char*)(gbase) + (voff)[_i]), (PG8_LAS unsigned*)(lds + (bufoff) + ldsw + _i * 8192), 16, 0, 0); } while (0)
; #define PG8_LDA(dst, b, h) do { _Pragma("unroll") for (int m = 0; m < 4; ++m) _Pragma("unroll") for (int k = 0; k < 2; ++k) dst[m][k] = *(const PG8_LAS bf16x8*)(lds + PG8_SA(b, h) + aoff + m * 2048 + k * 1024); } while (0)
; #define PG8_LDB(dst, b, h) do { _Pragma("unroll") for (int n = 0; n < 2; ++n) _Pragma("unroll") for (int k = 0; k < 2; ++k) dst[n][k] = *(const PG8_LAS bf16x8*)(lds + PG8_SB(b, h) + boff + n * 2048 + k * 1024); } while (0)
; #define PG8_MMA(ai, bj, At, Bt) do { __builtin_amdgcn_s_setprio(1); _Pragma("unroll") for (int m = 0; m < 4; ++m) _Pragma("unroll") for (int n = 0; n < 2; ++n) _Pragma("unroll") for (int k = 0; k < 2; ++k) \
;         acc[ai][bj][m][n] = __builtin_amdgcn_mfma_f32_16x16x32_bf16(Bt[n][k], At[m][k], acc[ai][bj][m][n], 0, 0, 0); __builtin_amdgcn_s_setprio(0); } while (0)
; #define PG8_WAIT_V(n) asm volatile("s_waitcnt vmcnt(" #n ")" ::: "memory")
; #define PG8_WAIT_L(n) asm volatile("s_waitcnt lgkmcnt(" #n ")" ::: "memory")
; #define PG8_BAR __builtin_amdgcn_s_barrier()
; #define PG8_SCHED __builtin_amdgcn_sched_barrier(0)
; template <class Epi, class Sched, bool ALIGN_EPI = false, bool SP2 = false>
; __device__ __forceinline__ void gemm_phase(PG8_LAS unsigned char* lds, const Gemm g, const Sched& S, const Epi& E) {
;     ...
;             const bool last = (t == nt - 2);
;             const char* a1 = cA + (size_t)(t + 1) * kstep;
;             const char* a2 = last ? nA : cA + (size_t)(t + 2) * kstep; const char* b2 = last ? nB : cB + (size_t)(t + 2) * kstep;
;             const char* a3 = a2 + kstep; const char* b3 = b2 + kstep;
;             if (last && has_next) S.a_ready(nxt);
;             if constexpr (SP2) {
;             PG8_LDB(B0, 0, 0); PG8_LDB(B1, 0, 1); PG8_SCHED; PG8_LDA(At, 0, 0); PG8_STAGE(PG8_SA(1, 1), a1 + hstep, voffA);
;             PG8_WAIT_V(8); PG8_WAIT_L(0); PG8_BAR; PG8_MMA(0, 0, At, B0); PG8_MMA(0, 1, At, B1); PG8_BAR; PG8_SCHED;
;             PG8_LDA(At, 0, 1); PG8_STAGE(PG8_SB(0, 0), b2, voffB); PG8_STAGE(PG8_SB(0, 1), b2 + hstep, voffB); PG8_STAGE(PG8_SA(0, 0), a2, voffA);
.LBB0_684:
	s_add_u32 s24, s8, 0xfff80080
	s_addc_u32 s25, s9, -1
	s_add_i32 s60, 0, 0x10000
	s_cmp_eq_u32 s63, 28
	s_cselect_b32 s27, s19, s25
	s_cselect_b32 s26, s45, s24
	v_add_u32_e32 v154, s60, v157
	s_cselect_b32 s25, s17, s62
	s_cselect_b32 s24, s52, s58
	s_add_i32 s66, 0, 0x14000
	ds_read_b128 v[160:163], v154
	ds_read_b128 v[164:167], v154 offset:1024
	ds_read_b128 v[168:171], v154 offset:2048
	ds_read_b128 v[172:175], v154 offset:3072
	v_add_u32_e32 v154, s66, v157
	ds_read_b128 v[176:179], v154
	ds_read_b128 v[180:183], v154 offset:1024
	ds_read_b128 v[184:187], v154 offset:2048
	ds_read_b128 v[198:201], v154 offset:3072
	v_lshl_add_u64 v[154:155], s[8:9], 0, v[134:135]
	s_add_i32 m0, s34, 0xc000
	ds_read_b128 v[202:205], v159
	ds_read_b128 v[206:209], v159 offset:1024
	ds_read_b128 v[210:213], v159 offset:2048
	ds_read_b128 v[214:217], v159 offset:3072
	ds_read_b128 v[218:221], v159 offset:4096
	ds_read_b128 v[222:225], v159 offset:5120
	ds_read_b128 v[226:229], v159 offset:6144
	ds_read_b128 v[238:241], v159 offset:7168
	global_load_lds_dwordx4 v[154:155], off
	v_lshl_add_u64 v[154:155], s[8:9], 0, v[136:137]
	s_add_i32 m0, s34, 0xe000
	s_nop 0
	global_load_lds_dwordx4 v[154:155], off
	s_nop 0
	s_waitcnt vmcnt(8)
	s_waitcnt lgkmcnt(0)
	s_barrier
	s_setprio 1
	s_waitcnt lgkmcnt(0)
	v_mfma_f32_16x16x32_bf16 v[124:127], v[160:163], v[202:205], v[124:127]
	v_mfma_f32_16x16x32_bf16 v[120:123], v[168:171], v[202:205], v[120:123]
	v_mfma_f32_16x16x32_bf16 v[108:111], v[160:163], v[210:213], v[108:111]
	v_mfma_f32_16x16x32_bf16 v[104:107], v[168:171], v[210:213], v[104:107]
	v_mfma_f32_16x16x32_bf16 v[92:95], v[160:163], v[218:221], v[92:95]
	v_mfma_f32_16x16x32_bf16 v[88:91], v[168:171], v[218:221], v[88:91]
	v_mfma_f32_16x16x32_bf16 v[76:79], v[160:163], v[226:229], v[76:79]
	v_mfma_f32_16x16x32_bf16 v[72:75], v[168:171], v[226:229], v[72:75]
	v_mfma_f32_16x16x32_bf16 v[124:127], v[164:167], v[206:209], v[124:127]
	v_mfma_f32_16x16x32_bf16 v[120:123], v[172:175], v[206:209], v[120:123]
	v_mfma_f32_16x16x32_bf16 v[108:111], v[164:167], v[214:217], v[108:111]
	v_mfma_f32_16x16x32_bf16 v[104:107], v[172:175], v[214:217], v[104:107]
	v_mfma_f32_16x16x32_bf16 v[92:95], v[164:167], v[222:225], v[92:95]
	v_mfma_f32_16x16x32_bf16 v[88:91], v[172:175], v[222:225], v[88:91]
	v_mfma_f32_16x16x32_bf16 v[76:79], v[164:167], v[238:241], v[76:79]
	v_mfma_f32_16x16x32_bf16 v[72:75], v[172:175], v[238:241], v[72:75]
	v_mfma_f32_16x16x32_bf16 v[116:119], v[176:179], v[202:205], v[116:119]
	v_mfma_f32_16x16x32_bf16 v[112:115], v[184:187], v[202:205], v[112:115]
	v_mfma_f32_16x16x32_bf16 v[100:103], v[176:179], v[210:213], v[100:103]
	v_mfma_f32_16x16x32_bf16 v[96:99], v[184:187], v[210:213], v[96:99]
	v_mfma_f32_16x16x32_bf16 v[84:87], v[176:179], v[218:221], v[84:87]
	v_mfma_f32_16x16x32_bf16 v[80:83], v[184:187], v[218:221], v[80:83]
	v_mfma_f32_16x16x32_bf16 v[68:71], v[176:179], v[226:229], v[68:71]
	v_mfma_f32_16x16x32_bf16 v[64:67], v[184:187], v[226:229], v[64:67]
	v_mfma_f32_16x16x32_bf16 v[116:119], v[180:183], v[206:209], v[116:119]
	v_mfma_f32_16x16x32_bf16 v[112:115], v[198:201], v[206:209], v[112:115]
	v_mfma_f32_16x16x32_bf16 v[100:103], v[180:183], v[214:217], v[100:103]
	v_mfma_f32_16x16x32_bf16 v[96:99], v[198:201], v[214:217], v[96:99]
	v_mfma_f32_16x16x32_bf16 v[84:87], v[180:183], v[222:225], v[84:87]
	v_mfma_f32_16x16x32_bf16 v[80:83], v[198:201], v[222:225], v[80:83]
	v_mfma_f32_16x16x32_bf16 v[68:71], v[180:183], v[238:241], v[68:71]
	v_mfma_f32_16x16x32_bf16 v[64:67], v[198:201], v[238:241], v[64:67]
	s_setprio 0
	s_barrier
	s_add_i32 s60, s60, s31
	v_lshl_add_u64 v[154:155], s[24:25], 0, v[188:189]
	s_mov_b32 m0, s60
	ds_read_b128 v[202:205], v159 offset:16384
	ds_read_b128 v[206:209], v159 offset:17408
	ds_read_b128 v[210:213], v159 offset:18432
	ds_read_b128 v[214:217], v159 offset:19456
	ds_read_b128 v[218:221], v159 offset:20480
	ds_read_b128 v[222:225], v159 offset:21504
	ds_read_b128 v[226:229], v159 offset:22528
	ds_read_b128 v[238:241], v159 offset:23552
	global_load_lds_dwordx4 v[154:155], off
	s_add_i32 m0, s60, 0x2000
	s_add_u32 s60, s24, 0x80000
	v_lshl_add_u64 v[232:233], s[24:25], 0, v[128:129]
	s_addc_u32 s61, s25, 0
	s_add_i32 s66, s66, s31
	global_load_lds_dwordx4 v[232:233], off
	v_lshl_add_u64 v[242:243], s[60:61], 0, v[188:189]
	s_mov_b32 m0, s66
	v_lshl_add_u64 v[244:245], s[26:27], 0, v[130:131]
	global_load_lds_dwordx4 v[242:243], off
	v_lshl_add_u64 v[242:243], s[60:61], 0, v[128:129]
	s_add_i32 m0, s66, 0x2000
	s_nop 0
	global_load_lds_dwordx4 v[242:243], off
	v_lshl_add_u64 v[242:243], s[26:27], 0, v[132:133]
	s_mov_b32 m0, s34
	s_nop 0
	global_load_lds_dwordx4 v[242:243], off
	s_mov_b32 m0, s35
	s_nop 0
	global_load_lds_dwordx4 v[244:245], off
	s_nop 0
	s_waitcnt vmcnt(8)
	s_waitcnt lgkmcnt(0)
	s_barrier
; #define PG8_STAGE(bufoff, gbase, voff) do { _Pragma("unroll") for (int _i = 0; _i < 2; ++_i) \
;         __builtin_amdgcn_global_load_lds((const unsigned*)((const char*)(gbase) + (voff)[_i]), (PG8_LAS unsigned*)(lds + (bufoff) + ldsw + _i * 8192), 16, 0, 0); } while (0)
; #define PG8_LDA(dst, b, h) do { _Pragma("unroll") for (int m = 0; m < 4; ++m) _Pragma("unroll") for (int k = 0; k < 2; ++k) dst[m][k] = *(const PG8_LAS bf16x8*)(lds + PG8_SA(b, h) + aoff + m * 2048 + k * 1024); } while (0)
; #define PG8_LDB(dst, b, h) do { _Pragma("unroll") for (int n = 0; n < 2; ++n) _Pragma("unroll") for (int k = 0; k < 2; ++k) dst[n][k] = *(const PG8_LAS bf16x8*)(lds + PG8_SB(b, h) + boff + n * 2048 + k * 1024); } while (0)
; #define PG8_MMA(ai, bj, At, Bt) do { __builtin_amdgcn_s_setprio(1); _Pragma("unroll") for (int m = 0; m < 4; ++m) _Pragma("unroll") for (int n = 0; n < 2; ++n) _Pragma("unroll") for (int k = 0; k < 2; ++k) \
;         acc[ai][bj][m][n] = __builtin_amdgcn_mfma_f32_16x16x32_bf16(Bt[n][k], At[m][k], acc[ai][bj][m][n], 0, 0, 0); __builtin_amdgcn_s_setprio(0); } while (0)
; #define PG8_WAIT_V(n) asm volatile("s_waitcnt vmcnt(" #n ")" ::: "memory")
; #define PG8_WAIT_L(n) asm volatile("s_waitcnt lgkmcnt(" #n ")" ::: "memory")
; #define PG8_BAR __builtin_amdgcn_s_barrier()
; #define PG8_SCHED __builtin_amdgcn_sched_barrier(0)
; template <class Epi, class Sched, bool ALIGN_EPI = false, bool SP2 = false>
; __device__ __forceinline__ void gemm_phase(PG8_LAS unsigned char* lds, const Gemm g, const Sched& S, const Epi& E) {
;     ...
;             PG8_WAIT_V(8); PG8_WAIT_L(0); PG8_BAR; PG8_MMA(1, 0, At, B0); PG8_MMA(1, 1, At, B1); PG8_BAR; PG8_SCHED;
;             PG8_LDB(B0, 1, 0); PG8_LDB(B1, 1, 1); PG8_SCHED; PG8_LDA(At, 1, 0); PG8_STAGE(PG8_SA(0, 1), a2 + hstep, voffA);
;             PG8_WAIT_V(8); PG8_WAIT_L(0); PG8_BAR; PG8_MMA(0, 0, At, B0); PG8_MMA(0, 1, At, B1); PG8_BAR; PG8_SCHED;
	s_setprio 1
	s_waitcnt lgkmcnt(0)
	v_mfma_f32_16x16x32_bf16 v[60:63], v[160:163], v[202:205], v[60:63]
	v_mfma_f32_16x16x32_bf16 v[56:59], v[168:171], v[202:205], v[56:59]
	v_mfma_f32_16x16x32_bf16 v[44:47], v[160:163], v[210:213], v[44:47]
	v_mfma_f32_16x16x32_bf16 v[40:43], v[168:171], v[210:213], v[40:43]
	v_mfma_f32_16x16x32_bf16 v[28:31], v[160:163], v[218:221], v[28:31]
	v_mfma_f32_16x16x32_bf16 v[24:27], v[168:171], v[218:221], v[24:27]
	v_mfma_f32_16x16x32_bf16 v[12:15], v[160:163], v[226:229], v[12:15]
	v_mfma_f32_16x16x32_bf16 v[8:11], v[168:171], v[226:229], v[8:11]
	v_mfma_f32_16x16x32_bf16 v[60:63], v[164:167], v[206:209], v[60:63]
	v_mfma_f32_16x16x32_bf16 v[56:59], v[172:175], v[206:209], v[56:59]
	v_mfma_f32_16x16x32_bf16 v[44:47], v[164:167], v[214:217], v[44:47]
	v_mfma_f32_16x16x32_bf16 v[40:43], v[172:175], v[214:217], v[40:43]
	v_mfma_f32_16x16x32_bf16 v[28:31], v[164:167], v[222:225], v[28:31]
	v_mfma_f32_16x16x32_bf16 v[24:27], v[172:175], v[222:225], v[24:27]
	v_mfma_f32_16x16x32_bf16 v[12:15], v[164:167], v[238:241], v[12:15]
	v_mfma_f32_16x16x32_bf16 v[8:11], v[172:175], v[238:241], v[8:11]
	v_mfma_f32_16x16x32_bf16 v[52:55], v[176:179], v[202:205], v[52:55]
	v_mfma_f32_16x16x32_bf16 v[48:51], v[184:187], v[202:205], v[48:51]
	v_mfma_f32_16x16x32_bf16 v[36:39], v[176:179], v[210:213], v[36:39]
	v_mfma_f32_16x16x32_bf16 v[32:35], v[184:187], v[210:213], v[32:35]
	v_mfma_f32_16x16x32_bf16 v[20:23], v[176:179], v[218:221], v[20:23]
	v_mfma_f32_16x16x32_bf16 v[16:19], v[184:187], v[218:221], v[16:19]
	v_mfma_f32_16x16x32_bf16 v[4:7], v[176:179], v[226:229], v[4:7]
	v_mfma_f32_16x16x32_bf16 v[0:3], v[184:187], v[226:229], v[0:3]
	v_mfma_f32_16x16x32_bf16 v[52:55], v[180:183], v[206:209], v[52:55]
	v_mfma_f32_16x16x32_bf16 v[48:51], v[198:201], v[206:209], v[48:51]
	v_mfma_f32_16x16x32_bf16 v[36:39], v[180:183], v[214:217], v[36:39]
	v_mfma_f32_16x16x32_bf16 v[32:35], v[198:201], v[214:217], v[32:35]
	v_mfma_f32_16x16x32_bf16 v[20:23], v[180:183], v[222:225], v[20:23]
	v_mfma_f32_16x16x32_bf16 v[16:19], v[198:201], v[222:225], v[16:19]
	v_mfma_f32_16x16x32_bf16 v[4:7], v[180:183], v[238:241], v[4:7]
	v_mfma_f32_16x16x32_bf16 v[0:3], v[198:201], v[238:241], v[0:3]
	s_setprio 0
	s_barrier
	s_add_i32 s60, 0, 0x18000
	s_add_i32 s61, 0, 0x1c000
	v_add_u32_e32 v172, s60, v157
	v_add_u32_e32 v194, s61, v157
	ds_read_b128 v[160:163], v172
	ds_read_b128 v[164:167], v172 offset:1024
	ds_read_b128 v[168:171], v172 offset:2048
	ds_read_b128 v[172:175], v172 offset:3072
	ds_read_b128 v[176:179], v194
	ds_read_b128 v[180:183], v194 offset:1024
	ds_read_b128 v[184:187], v194 offset:2048
	ds_read_b128 v[198:201], v194 offset:3072
	s_add_u32 s26, s26, 0x80000
	s_addc_u32 s27, s27, 0
	s_mov_b32 m0, s36
	v_lshl_add_u64 v[246:247], s[26:27], 0, v[132:133]
	ds_read_b128 v[202:205], v159 offset:32768
	ds_read_b128 v[206:209], v159 offset:33792
	ds_read_b128 v[210:213], v159 offset:34816
	ds_read_b128 v[214:217], v159 offset:35840
	ds_read_b128 v[218:221], v159 offset:36864
	ds_read_b128 v[222:225], v159 offset:37888
	ds_read_b128 v[226:229], v159 offset:38912
	ds_read_b128 v[238:241], v159 offset:39936
	global_load_lds_dwordx4 v[246:247], off
	v_lshl_add_u64 v[246:247], s[26:27], 0, v[130:131]
	s_mov_b32 m0, s37
	s_nop 0
	global_load_lds_dwordx4 v[246:247], off
	s_nop 0
	s_waitcnt vmcnt(8)
	s_waitcnt lgkmcnt(0)
	s_barrier
	s_setprio 1
	s_waitcnt lgkmcnt(0)
	v_mfma_f32_16x16x32_bf16 v[124:127], v[160:163], v[202:205], v[124:127]
	v_mfma_f32_16x16x32_bf16 v[120:123], v[168:171], v[202:205], v[120:123]
	v_mfma_f32_16x16x32_bf16 v[108:111], v[160:163], v[210:213], v[108:111]
	v_mfma_f32_16x16x32_bf16 v[104:107], v[168:171], v[210:213], v[104:107]
	v_mfma_f32_16x16x32_bf16 v[92:95], v[160:163], v[218:221], v[92:95]
	v_mfma_f32_16x16x32_bf16 v[88:91], v[168:171], v[218:221], v[88:91]
	v_mfma_f32_16x16x32_bf16 v[76:79], v[160:163], v[226:229], v[76:79]
	v_mfma_f32_16x16x32_bf16 v[72:75], v[168:171], v[226:229], v[72:75]
	v_mfma_f32_16x16x32_bf16 v[124:127], v[164:167], v[206:209], v[124:127]
	v_mfma_f32_16x16x32_bf16 v[120:123], v[172:175], v[206:209], v[120:123]
	v_mfma_f32_16x16x32_bf16 v[108:111], v[164:167], v[214:217], v[108:111]
	v_mfma_f32_16x16x32_bf16 v[104:107], v[172:175], v[214:217], v[104:107]
	v_mfma_f32_16x16x32_bf16 v[92:95], v[164:167], v[222:225], v[92:95]
	v_mfma_f32_16x16x32_bf16 v[88:91], v[172:175], v[222:225], v[88:91]
	v_mfma_f32_16x16x32_bf16 v[76:79], v[164:167], v[238:241], v[76:79]
	v_mfma_f32_16x16x32_bf16 v[72:75], v[172:175], v[238:241], v[72:75]
	v_mfma_f32_16x16x32_bf16 v[116:119], v[176:179], v[202:205], v[116:119]
	v_mfma_f32_16x16x32_bf16 v[112:115], v[184:187], v[202:205], v[112:115]
	v_mfma_f32_16x16x32_bf16 v[100:103], v[176:179], v[210:213], v[100:103]
	v_mfma_f32_16x16x32_bf16 v[96:99], v[184:187], v[210:213], v[96:99]
	v_mfma_f32_16x16x32_bf16 v[84:87], v[176:179], v[218:221], v[84:87]
	v_mfma_f32_16x16x32_bf16 v[80:83], v[184:187], v[218:221], v[80:83]
	v_mfma_f32_16x16x32_bf16 v[68:71], v[176:179], v[226:229], v[68:71]
	v_mfma_f32_16x16x32_bf16 v[64:67], v[184:187], v[226:229], v[64:67]
	v_mfma_f32_16x16x32_bf16 v[116:119], v[180:183], v[206:209], v[116:119]
	v_mfma_f32_16x16x32_bf16 v[112:115], v[198:201], v[206:209], v[112:115]
	v_mfma_f32_16x16x32_bf16 v[100:103], v[180:183], v[214:217], v[100:103]
	v_mfma_f32_16x16x32_bf16 v[96:99], v[198:201], v[214:217], v[96:99]
	v_mfma_f32_16x16x32_bf16 v[84:87], v[180:183], v[222:225], v[84:87]
	v_mfma_f32_16x16x32_bf16 v[80:83], v[198:201], v[222:225], v[80:83]
	v_mfma_f32_16x16x32_bf16 v[68:71], v[180:183], v[238:241], v[68:71]
	v_mfma_f32_16x16x32_bf16 v[64:67], v[198:201], v[238:241], v[64:67]
	s_setprio 0
	s_barrier
; #define PG8_STAGE(bufoff, gbase, voff) do { _Pragma("unroll") for (int _i = 0; _i < 2; ++_i) \
;         __builtin_amdgcn_global_load_lds((const unsigned*)((const char*)(gbase) + (voff)[_i]), (PG8_LAS unsigned*)(lds + (bufoff) + ldsw + _i * 8192), 16, 0, 0); } while (0)
; #define PG8_LDA(dst, b, h) do { _Pragma("unroll") for (int m = 0; m < 4; ++m) _Pragma("unroll") for (int k = 0; k < 2; ++k) dst[m][k] = *(const PG8_LAS bf16x8*)(lds + PG8_SA(b, h) + aoff + m * 2048 + k * 1024); } while (0)
; #define PG8_MMA(ai, bj, At, Bt) do { __builtin_amdgcn_s_setprio(1); _Pragma("unroll") for (int m = 0; m < 4; ++m) _Pragma("unroll") for (int n = 0; n < 2; ++n) _Pragma("unroll") for (int k = 0; k < 2; ++k) \
;         acc[ai][bj][m][n] = __builtin_amdgcn_mfma_f32_16x16x32_bf16(Bt[n][k], At[m][k], acc[ai][bj][m][n], 0, 0, 0); __builtin_amdgcn_s_setprio(0); } while (0)
; #define PG8_WAIT_V(n) asm volatile("s_waitcnt vmcnt(" #n ")" ::: "memory")
; #define PG8_WAIT_L(n) asm volatile("s_waitcnt lgkmcnt(" #n ")" ::: "memory")
; #define PG8_BAR __builtin_amdgcn_s_barrier()
; #define PG8_SCHED __builtin_amdgcn_sched_barrier(0)
; template <class Epi, class Sched, bool ALIGN_EPI = false, bool SP2 = false>
; __device__ __forceinline__ void gemm_phase(PG8_LAS unsigned char* lds, const Gemm g, const Sched& S, const Epi& E) {
;     ...
;             PG8_LDA(At, 1, 1); PG8_STAGE(PG8_SB(1, 0), b3, voffB); PG8_STAGE(PG8_SB(1, 1), b3 + hstep, voffB); PG8_STAGE(PG8_SA(1, 0), a3, voffA);
;             PG8_WAIT_V(8); PG8_WAIT_L(0); PG8_BAR; PG8_MMA(1, 0, At, B0); PG8_MMA(1, 1, At, B1); PG8_BAR; PG8_SCHED;
	s_add_i32 s26, s60, s31
	v_lshl_add_u64 v[154:155], v[154:155], 0, s[78:79]
	s_mov_b32 m0, s26
	ds_read_b128 v[202:205], v159 offset:49152
	ds_read_b128 v[206:209], v159 offset:50176
	ds_read_b128 v[210:213], v159 offset:51200
	ds_read_b128 v[214:217], v159 offset:52224
	ds_read_b128 v[218:221], v159 offset:53248
	ds_read_b128 v[222:225], v159 offset:54272
	ds_read_b128 v[226:229], v159 offset:55296
	ds_read_b128 v[238:241], v159 offset:56320
	global_load_lds_dwordx4 v[154:155], off
	s_add_i32 m0, s26, 0x2000
	s_add_u32 s24, s24, 0x80080
	v_lshl_add_u64 v[154:155], v[232:233], 0, s[78:79]
	s_addc_u32 s25, s25, 0
	s_add_i32 s26, s61, s31
	global_load_lds_dwordx4 v[154:155], off
	v_lshl_add_u64 v[154:155], s[24:25], 0, v[188:189]
	s_mov_b32 m0, s26
	s_nop 0
	global_load_lds_dwordx4 v[154:155], off
	v_lshl_add_u64 v[154:155], s[24:25], 0, v[128:129]
	s_add_i32 m0, s26, 0x2000
	s_nop 0
	global_load_lds_dwordx4 v[154:155], off
	v_lshl_add_u64 v[154:155], v[242:243], 0, s[78:79]
	s_mov_b32 m0, s38
	s_nop 0
	global_load_lds_dwordx4 v[154:155], off
	v_lshl_add_u64 v[154:155], v[244:245], 0, s[78:79]
	s_mov_b32 m0, s39
	s_nop 0
	global_load_lds_dwordx4 v[154:155], off
	s_waitcnt vmcnt(8)
	s_waitcnt lgkmcnt(0)
	s_barrier
	s_setprio 1
	s_waitcnt lgkmcnt(0)
	v_mfma_f32_16x16x32_bf16 v[60:63], v[160:163], v[202:205], v[60:63]
	v_mfma_f32_16x16x32_bf16 v[56:59], v[168:171], v[202:205], v[56:59]
	v_mfma_f32_16x16x32_bf16 v[44:47], v[160:163], v[210:213], v[44:47]
	v_mfma_f32_16x16x32_bf16 v[40:43], v[168:171], v[210:213], v[40:43]
	v_mfma_f32_16x16x32_bf16 v[28:31], v[160:163], v[218:221], v[28:31]
	v_mfma_f32_16x16x32_bf16 v[24:27], v[168:171], v[218:221], v[24:27]
	v_mfma_f32_16x16x32_bf16 v[12:15], v[160:163], v[226:229], v[12:15]
	v_mfma_f32_16x16x32_bf16 v[8:11], v[168:171], v[226:229], v[8:11]
	v_mfma_f32_16x16x32_bf16 v[60:63], v[164:167], v[206:209], v[60:63]
	v_mfma_f32_16x16x32_bf16 v[56:59], v[172:175], v[206:209], v[56:59]
	v_mfma_f32_16x16x32_bf16 v[44:47], v[164:167], v[214:217], v[44:47]
	v_mfma_f32_16x16x32_bf16 v[40:43], v[172:175], v[214:217], v[40:43]
	v_mfma_f32_16x16x32_bf16 v[28:31], v[164:167], v[222:225], v[28:31]
	v_mfma_f32_16x16x32_bf16 v[24:27], v[172:175], v[222:225], v[24:27]
	v_mfma_f32_16x16x32_bf16 v[12:15], v[164:167], v[238:241], v[12:15]
	v_mfma_f32_16x16x32_bf16 v[8:11], v[172:175], v[238:241], v[8:11]
	v_mfma_f32_16x16x32_bf16 v[52:55], v[176:179], v[202:205], v[52:55]
	v_mfma_f32_16x16x32_bf16 v[48:51], v[184:187], v[202:205], v[48:51]
	v_mfma_f32_16x16x32_bf16 v[36:39], v[176:179], v[210:213], v[36:39]
	v_mfma_f32_16x16x32_bf16 v[32:35], v[184:187], v[210:213], v[32:35]
	v_mfma_f32_16x16x32_bf16 v[20:23], v[176:179], v[218:221], v[20:23]
	v_mfma_f32_16x16x32_bf16 v[16:19], v[184:187], v[218:221], v[16:19]
	v_mfma_f32_16x16x32_bf16 v[4:7], v[176:179], v[226:229], v[4:7]
	v_mfma_f32_16x16x32_bf16 v[0:3], v[184:187], v[226:229], v[0:3]
	v_mfma_f32_16x16x32_bf16 v[52:55], v[180:183], v[206:209], v[52:55]
	v_mfma_f32_16x16x32_bf16 v[48:51], v[198:201], v[206:209], v[48:51]
	v_mfma_f32_16x16x32_bf16 v[36:39], v[180:183], v[214:217], v[36:39]
	v_mfma_f32_16x16x32_bf16 v[32:35], v[198:201], v[214:217], v[32:35]
	v_mfma_f32_16x16x32_bf16 v[20:23], v[180:183], v[222:225], v[20:23]
	v_mfma_f32_16x16x32_bf16 v[16:19], v[198:201], v[222:225], v[16:19]
	v_mfma_f32_16x16x32_bf16 v[4:7], v[180:183], v[238:241], v[4:7]
	v_mfma_f32_16x16x32_bf16 v[0:3], v[198:201], v[238:241], v[0:3]
	s_setprio 0
	s_barrier
	s_add_i32 s63, s63, 2
	s_add_u32 s8, s8, 0x100
	s_addc_u32 s9, s9, 0
	s_add_u32 s58, s58, 0x100
	s_addc_u32 s62, s62, 0
	s_cmp_gt_u32 s63, 29
	s_cbranch_scc0 .LBB0_684
	s_and_b64 vcc, exec, s[14:15]
	s_cbranch_vccz .LBB0_687
	s_barrier

; #define PG8_STAGE(bufoff, gbase, voff) do { _Pragma("unroll") for (int _i = 0; _i < 2; ++_i) \
;         __builtin_amdgcn_global_load_lds((const unsigned*)((const char*)(gbase) + (voff)[_i]), (PG8_LAS unsigned*)(lds + (bufoff) + ldsw + _i * 8192), 16, 0, 0); } while (0)
; #define PG8_LDA(dst, b, h) do { _Pragma("unroll") for (int m = 0; m < 4; ++m) _Pragma("unroll") for (int k = 0; k < 2; ++k) dst[m][k] = *(const PG8_LAS bf16x8*)(lds + PG8_SA(b, h) + aoff + m * 2048 + k * 1024); } while (0)
; #define PG8_LDB(dst, b, h) do { _Pragma("unroll") for (int n = 0; n < 2; ++n) _Pragma("unroll") for (int k = 0; k < 2; ++k) dst[n][k] = *(const PG8_LAS bf16x8*)(lds + PG8_SB(b, h) + boff + n * 2048 + k * 1024); } while (0)
; #define PG8_MMA(ai, bj, At, Bt) do { __builtin_amdgcn_s_setprio(1); _Pragma("unroll") for (int m = 0; m < 4; ++m) _Pragma("unroll") for (int n = 0; n < 2; ++n) _Pragma("unroll") for (int k = 0; k < 2; ++k) \
;         acc[ai][bj][m][n] = __builtin_amdgcn_mfma_f32_16x16x32_bf16(Bt[n][k], At[m][k], acc[ai][bj][m][n], 0, 0, 0); __builtin_amdgcn_s_setprio(0); } while (0)
; #define PG8_WAIT_V(n) asm volatile("s_waitcnt vmcnt(" #n ")" ::: "memory")
; #define PG8_WAIT_L(n) asm volatile("s_waitcnt lgkmcnt(" #n ")" ::: "memory")
; #define PG8_BAR __builtin_amdgcn_s_barrier()
; #define PG8_SCHED __builtin_amdgcn_sched_barrier(0)
; template <class Epi, class Sched, bool ALIGN_EPI = false, bool SP2 = false>
; __device__ __forceinline__ void gemm_phase(PG8_LAS unsigned char* lds, const Gemm g, const Sched& S, const Epi& E) {
;     ...
;             const bool last = (t == nt - 2);
;             const char* a1 = cA + (size_t)(t + 1) * kstep;
;             const char* a2 = last ? nA : cA + (size_t)(t + 2) * kstep; const char* b2 = last ? nB : cB + (size_t)(t + 2) * kstep;
;             const char* a3 = a2 + kstep; const char* b3 = b2 + kstep;
;             if (last && has_next) S.a_ready(nxt);
;             if constexpr (SP2) {
;             PG8_LDB(B0, 0, 0); PG8_LDB(B1, 0, 1); PG8_SCHED; PG8_LDA(At, 0, 0); PG8_STAGE(PG8_SA(1, 1), a1 + hstep, voffA);
;             PG8_WAIT_V(8); PG8_WAIT_L(0); PG8_BAR; PG8_MMA(0, 0, At, B0); PG8_MMA(0, 1, At, B1); PG8_BAR; PG8_SCHED;
;             PG8_LDA(At, 0, 1); PG8_STAGE(PG8_SB(0, 0), b2, voffB); PG8_STAGE(PG8_SB(0, 1), b2 + hstep, voffB); PG8_STAGE(PG8_SA(0, 0), a2, voffA);
.LBB0_757:
	s_add_u32 s28, s26, 0xffe00080
	s_addc_u32 s29, s27, -1
	s_add_i32 s60, 0, 0x10000
	s_cmpk_eq_i32 s72, 0x7c
	s_cselect_b32 s31, s21, s29
	s_cselect_b32 s30, s63, s28
	s_cselect_b32 s29, s19, s68
	s_cselect_b32 s28, s66, s67
	s_add_i32 s73, 0, 0x14000
	v_add_u32_e32 v124, s60, v239
	v_add_u32_e32 v148, s73, v239
	ds_read_b128 v[112:115], v124
	ds_read_b128 v[116:119], v124 offset:1024
	ds_read_b128 v[120:123], v124 offset:2048
	ds_read_b128 v[124:127], v124 offset:3072
	ds_read_b128 v[132:135], v148
	ds_read_b128 v[140:143], v148 offset:1024
	ds_read_b128 v[144:147], v148 offset:2048
	ds_read_b128 v[148:151], v148 offset:3072
	v_lshl_add_u64 v[212:213], s[26:27], 0, v[204:205]
	s_add_i32 m0, s38, 0xc000
	ds_read_b128 v[152:155], v241
	ds_read_b128 v[164:167], v241 offset:1024
	ds_read_b128 v[168:171], v241 offset:2048
	ds_read_b128 v[172:175], v241 offset:3072
	ds_read_b128 v[176:179], v241 offset:4096
	ds_read_b128 v[180:183], v241 offset:5120
	ds_read_b128 v[184:187], v241 offset:6144
	ds_read_b128 v[208:211], v241 offset:7168
	global_load_lds_dwordx4 v[212:213], off
	v_lshl_add_u64 v[212:213], s[26:27], 0, v[206:207]
	s_add_i32 m0, s38, 0xe000
	s_nop 0
	global_load_lds_dwordx4 v[212:213], off
	s_waitcnt vmcnt(8)
	s_waitcnt lgkmcnt(0)
	s_barrier
	s_setprio 1
	s_waitcnt lgkmcnt(0)
	v_mfma_f32_16x16x32_bf16 v[160:163], v[112:115], v[152:155], v[160:163]
	v_mfma_f32_16x16x32_bf16 v[156:159], v[120:123], v[152:155], v[156:159]
	v_mfma_f32_16x16x32_bf16 v[108:111], v[112:115], v[168:171], v[108:111]
	v_mfma_f32_16x16x32_bf16 v[104:107], v[120:123], v[168:171], v[104:107]
	v_mfma_f32_16x16x32_bf16 v[92:95], v[112:115], v[176:179], v[92:95]
	v_mfma_f32_16x16x32_bf16 v[88:91], v[120:123], v[176:179], v[88:91]
	v_mfma_f32_16x16x32_bf16 v[76:79], v[112:115], v[184:187], v[76:79]
	v_mfma_f32_16x16x32_bf16 v[72:75], v[120:123], v[184:187], v[72:75]
	v_mfma_f32_16x16x32_bf16 v[160:163], v[116:119], v[164:167], v[160:163]
	v_mfma_f32_16x16x32_bf16 v[156:159], v[124:127], v[164:167], v[156:159]
	v_mfma_f32_16x16x32_bf16 v[108:111], v[116:119], v[172:175], v[108:111]
	v_mfma_f32_16x16x32_bf16 v[104:107], v[124:127], v[172:175], v[104:107]
	v_mfma_f32_16x16x32_bf16 v[92:95], v[116:119], v[180:183], v[92:95]
	v_mfma_f32_16x16x32_bf16 v[88:91], v[124:127], v[180:183], v[88:91]
	v_mfma_f32_16x16x32_bf16 v[76:79], v[116:119], v[208:211], v[76:79]
	v_mfma_f32_16x16x32_bf16 v[72:75], v[124:127], v[208:211], v[72:75]
	v_mfma_f32_16x16x32_bf16 v[136:139], v[132:135], v[152:155], v[136:139]
	v_mfma_f32_16x16x32_bf16 v[128:131], v[144:147], v[152:155], v[128:131]
	v_mfma_f32_16x16x32_bf16 v[100:103], v[132:135], v[168:171], v[100:103]
	v_mfma_f32_16x16x32_bf16 v[96:99], v[144:147], v[168:171], v[96:99]
	v_mfma_f32_16x16x32_bf16 v[84:87], v[132:135], v[176:179], v[84:87]
	v_mfma_f32_16x16x32_bf16 v[80:83], v[144:147], v[176:179], v[80:83]
	v_mfma_f32_16x16x32_bf16 v[68:71], v[132:135], v[184:187], v[68:71]
	v_mfma_f32_16x16x32_bf16 v[64:67], v[144:147], v[184:187], v[64:67]
	v_mfma_f32_16x16x32_bf16 v[136:139], v[140:143], v[164:167], v[136:139]
	v_mfma_f32_16x16x32_bf16 v[128:131], v[148:151], v[164:167], v[128:131]
	v_mfma_f32_16x16x32_bf16 v[100:103], v[140:143], v[172:175], v[100:103]
	v_mfma_f32_16x16x32_bf16 v[96:99], v[148:151], v[172:175], v[96:99]
	v_mfma_f32_16x16x32_bf16 v[84:87], v[140:143], v[180:183], v[84:87]
	v_mfma_f32_16x16x32_bf16 v[80:83], v[148:151], v[180:183], v[80:83]
	v_mfma_f32_16x16x32_bf16 v[68:71], v[140:143], v[208:211], v[68:71]
	v_mfma_f32_16x16x32_bf16 v[64:67], v[148:151], v[208:211], v[64:67]
	s_setprio 0
	s_barrier
	s_add_i32 s60, s60, s37
	v_lshl_add_u64 v[212:213], s[28:29], 0, v[188:189]
	s_mov_b32 m0, s60
	ds_read_b128 v[152:155], v241 offset:16384
	ds_read_b128 v[164:167], v241 offset:17408
	ds_read_b128 v[168:171], v241 offset:18432
	ds_read_b128 v[172:175], v241 offset:19456
	ds_read_b128 v[176:179], v241 offset:20480
	ds_read_b128 v[180:183], v241 offset:21504
	ds_read_b128 v[184:187], v241 offset:22528
	ds_read_b128 v[208:211], v241 offset:23552
	global_load_lds_dwordx4 v[212:213], off
	s_add_i32 m0, s60, 0x2000
	s_add_u32 s60, s28, 0x200000
	v_lshl_add_u64 v[214:215], s[28:29], 0, v[198:199]
	s_addc_u32 s61, s29, 0
	s_add_i32 s73, s73, s37
	global_load_lds_dwordx4 v[214:215], off
	v_lshl_add_u64 v[216:217], s[60:61], 0, v[188:189]
	s_mov_b32 m0, s73
	v_lshl_add_u64 v[218:219], s[30:31], 0, v[200:201]
	global_load_lds_dwordx4 v[216:217], off
	v_lshl_add_u64 v[216:217], s[60:61], 0, v[198:199]
	s_add_i32 m0, s73, 0x2000
	s_nop 0
	global_load_lds_dwordx4 v[216:217], off
	v_lshl_add_u64 v[216:217], s[30:31], 0, v[202:203]
	s_mov_b32 m0, s38
	s_nop 0
	global_load_lds_dwordx4 v[216:217], off
	s_mov_b32 m0, s39
	s_nop 0
	global_load_lds_dwordx4 v[218:219], off
	s_nop 0
	s_waitcnt vmcnt(8)
	s_waitcnt lgkmcnt(0)
	s_barrier
; #define PG8_STAGE(bufoff, gbase, voff) do { _Pragma("unroll") for (int _i = 0; _i < 2; ++_i) \
;         __builtin_amdgcn_global_load_lds((const unsigned*)((const char*)(gbase) + (voff)[_i]), (PG8_LAS unsigned*)(lds + (bufoff) + ldsw + _i * 8192), 16, 0, 0); } while (0)
; #define PG8_LDA(dst, b, h) do { _Pragma("unroll") for (int m = 0; m < 4; ++m) _Pragma("unroll") for (int k = 0; k < 2; ++k) dst[m][k] = *(const PG8_LAS bf16x8*)(lds + PG8_SA(b, h) + aoff + m * 2048 + k * 1024); } while (0)
; #define PG8_LDB(dst, b, h) do { _Pragma("unroll") for (int n = 0; n < 2; ++n) _Pragma("unroll") for (int k = 0; k < 2; ++k) dst[n][k] = *(const PG8_LAS bf16x8*)(lds + PG8_SB(b, h) + boff + n * 2048 + k * 1024); } while (0)
; #define PG8_MMA(ai, bj, At, Bt) do { __builtin_amdgcn_s_setprio(1); _Pragma("unroll") for (int m = 0; m < 4; ++m) _Pragma("unroll") for (int n = 0; n < 2; ++n) _Pragma("unroll") for (int k = 0; k < 2; ++k) \
;         acc[ai][bj][m][n] = __builtin_amdgcn_mfma_f32_16x16x32_bf16(Bt[n][k], At[m][k], acc[ai][bj][m][n], 0, 0, 0); __builtin_amdgcn_s_setprio(0); } while (0)
; #define PG8_WAIT_V(n) asm volatile("s_waitcnt vmcnt(" #n ")" ::: "memory")
; #define PG8_WAIT_L(n) asm volatile("s_waitcnt lgkmcnt(" #n ")" ::: "memory")
; #define PG8_BAR __builtin_amdgcn_s_barrier()
; #define PG8_SCHED __builtin_amdgcn_sched_barrier(0)
; template <class Epi, class Sched, bool ALIGN_EPI = false, bool SP2 = false>
; __device__ __forceinline__ void gemm_phase(PG8_LAS unsigned char* lds, const Gemm g, const Sched& S, const Epi& E) {
;     ...
;             PG8_WAIT_V(8); PG8_WAIT_L(0); PG8_BAR; PG8_MMA(1, 0, At, B0); PG8_MMA(1, 1, At, B1); PG8_BAR; PG8_SCHED;
;             PG8_LDB(B0, 1, 0); PG8_LDB(B1, 1, 1); PG8_SCHED; PG8_LDA(At, 1, 0); PG8_STAGE(PG8_SA(0, 1), a2 + hstep, voffA);
;             PG8_WAIT_V(8); PG8_WAIT_L(0); PG8_BAR; PG8_MMA(0, 0, At, B0); PG8_MMA(0, 1, At, B1); PG8_BAR; PG8_SCHED;
	s_setprio 1
	s_waitcnt lgkmcnt(0)
	v_mfma_f32_16x16x32_bf16 v[60:63], v[112:115], v[152:155], v[60:63]
	v_mfma_f32_16x16x32_bf16 v[56:59], v[120:123], v[152:155], v[56:59]
	v_mfma_f32_16x16x32_bf16 v[44:47], v[112:115], v[168:171], v[44:47]
	v_mfma_f32_16x16x32_bf16 v[40:43], v[120:123], v[168:171], v[40:43]
	v_mfma_f32_16x16x32_bf16 v[28:31], v[112:115], v[176:179], v[28:31]
	v_mfma_f32_16x16x32_bf16 v[24:27], v[120:123], v[176:179], v[24:27]
	v_mfma_f32_16x16x32_bf16 v[12:15], v[112:115], v[184:187], v[12:15]
	v_mfma_f32_16x16x32_bf16 v[8:11], v[120:123], v[184:187], v[8:11]
	v_mfma_f32_16x16x32_bf16 v[60:63], v[116:119], v[164:167], v[60:63]
	v_mfma_f32_16x16x32_bf16 v[56:59], v[124:127], v[164:167], v[56:59]
	v_mfma_f32_16x16x32_bf16 v[44:47], v[116:119], v[172:175], v[44:47]
	v_mfma_f32_16x16x32_bf16 v[40:43], v[124:127], v[172:175], v[40:43]
	v_mfma_f32_16x16x32_bf16 v[28:31], v[116:119], v[180:183], v[28:31]
	v_mfma_f32_16x16x32_bf16 v[24:27], v[124:127], v[180:183], v[24:27]
	v_mfma_f32_16x16x32_bf16 v[12:15], v[116:119], v[208:211], v[12:15]
	v_mfma_f32_16x16x32_bf16 v[8:11], v[124:127], v[208:211], v[8:11]
	v_mfma_f32_16x16x32_bf16 v[52:55], v[132:135], v[152:155], v[52:55]
	v_mfma_f32_16x16x32_bf16 v[48:51], v[144:147], v[152:155], v[48:51]
	v_mfma_f32_16x16x32_bf16 v[36:39], v[132:135], v[168:171], v[36:39]
	v_mfma_f32_16x16x32_bf16 v[32:35], v[144:147], v[168:171], v[32:35]
	v_mfma_f32_16x16x32_bf16 v[20:23], v[132:135], v[176:179], v[20:23]
	v_mfma_f32_16x16x32_bf16 v[16:19], v[144:147], v[176:179], v[16:19]
	v_mfma_f32_16x16x32_bf16 v[4:7], v[132:135], v[184:187], v[4:7]
	v_mfma_f32_16x16x32_bf16 v[0:3], v[144:147], v[184:187], v[0:3]
	v_mfma_f32_16x16x32_bf16 v[52:55], v[140:143], v[164:167], v[52:55]
	v_mfma_f32_16x16x32_bf16 v[48:51], v[148:151], v[164:167], v[48:51]
	v_mfma_f32_16x16x32_bf16 v[36:39], v[140:143], v[172:175], v[36:39]
	v_mfma_f32_16x16x32_bf16 v[32:35], v[148:151], v[172:175], v[32:35]
	v_mfma_f32_16x16x32_bf16 v[20:23], v[140:143], v[180:183], v[20:23]
	v_mfma_f32_16x16x32_bf16 v[16:19], v[148:151], v[180:183], v[16:19]
	v_mfma_f32_16x16x32_bf16 v[4:7], v[140:143], v[208:211], v[4:7]
	v_mfma_f32_16x16x32_bf16 v[0:3], v[148:151], v[208:211], v[0:3]
	s_setprio 0
	s_barrier
	s_add_i32 s60, 0, 0x18000
	s_add_i32 s61, 0, 0x1c000
	v_add_u32_e32 v124, s60, v239
	v_add_u32_e32 v148, s61, v239
	ds_read_b128 v[112:115], v124
	ds_read_b128 v[116:119], v124 offset:1024
	ds_read_b128 v[120:123], v124 offset:2048
	ds_read_b128 v[124:127], v124 offset:3072
	ds_read_b128 v[132:135], v148
	ds_read_b128 v[140:143], v148 offset:1024
	ds_read_b128 v[144:147], v148 offset:2048
	ds_read_b128 v[148:151], v148 offset:3072
	s_add_u32 s30, s30, 0x200000
	s_addc_u32 s31, s31, 0
	s_mov_b32 m0, s40
	v_lshl_add_u64 v[220:221], s[30:31], 0, v[202:203]
	ds_read_b128 v[152:155], v241 offset:32768
	ds_read_b128 v[164:167], v241 offset:33792
	ds_read_b128 v[168:171], v241 offset:34816
	ds_read_b128 v[172:175], v241 offset:35840
	ds_read_b128 v[176:179], v241 offset:36864
	ds_read_b128 v[180:183], v241 offset:37888
	ds_read_b128 v[184:187], v241 offset:38912
	ds_read_b128 v[208:211], v241 offset:39936
	global_load_lds_dwordx4 v[220:221], off
	v_lshl_add_u64 v[220:221], s[30:31], 0, v[200:201]
	s_mov_b32 m0, s41
	s_nop 0
	global_load_lds_dwordx4 v[220:221], off
	s_nop 0
	s_waitcnt vmcnt(8)
	s_waitcnt lgkmcnt(0)
	s_barrier
	s_setprio 1
	s_waitcnt lgkmcnt(0)
	v_mfma_f32_16x16x32_bf16 v[160:163], v[112:115], v[152:155], v[160:163]
	v_mfma_f32_16x16x32_bf16 v[156:159], v[120:123], v[152:155], v[156:159]
	v_mfma_f32_16x16x32_bf16 v[108:111], v[112:115], v[168:171], v[108:111]
	v_mfma_f32_16x16x32_bf16 v[104:107], v[120:123], v[168:171], v[104:107]
	v_mfma_f32_16x16x32_bf16 v[92:95], v[112:115], v[176:179], v[92:95]
	v_mfma_f32_16x16x32_bf16 v[88:91], v[120:123], v[176:179], v[88:91]
	v_mfma_f32_16x16x32_bf16 v[76:79], v[112:115], v[184:187], v[76:79]
	v_mfma_f32_16x16x32_bf16 v[72:75], v[120:123], v[184:187], v[72:75]
	v_mfma_f32_16x16x32_bf16 v[160:163], v[116:119], v[164:167], v[160:163]
	v_mfma_f32_16x16x32_bf16 v[156:159], v[124:127], v[164:167], v[156:159]
	v_mfma_f32_16x16x32_bf16 v[108:111], v[116:119], v[172:175], v[108:111]
	v_mfma_f32_16x16x32_bf16 v[104:107], v[124:127], v[172:175], v[104:107]
	v_mfma_f32_16x16x32_bf16 v[92:95], v[116:119], v[180:183], v[92:95]
	v_mfma_f32_16x16x32_bf16 v[88:91], v[124:127], v[180:183], v[88:91]
	v_mfma_f32_16x16x32_bf16 v[76:79], v[116:119], v[208:211], v[76:79]
	v_mfma_f32_16x16x32_bf16 v[72:75], v[124:127], v[208:211], v[72:75]
	v_mfma_f32_16x16x32_bf16 v[136:139], v[132:135], v[152:155], v[136:139]
	v_mfma_f32_16x16x32_bf16 v[128:131], v[144:147], v[152:155], v[128:131]
	v_mfma_f32_16x16x32_bf16 v[100:103], v[132:135], v[168:171], v[100:103]
	v_mfma_f32_16x16x32_bf16 v[96:99], v[144:147], v[168:171], v[96:99]
	v_mfma_f32_16x16x32_bf16 v[84:87], v[132:135], v[176:179], v[84:87]
	v_mfma_f32_16x16x32_bf16 v[80:83], v[144:147], v[176:179], v[80:83]
	v_mfma_f32_16x16x32_bf16 v[68:71], v[132:135], v[184:187], v[68:71]
	v_mfma_f32_16x16x32_bf16 v[64:67], v[144:147], v[184:187], v[64:67]
	v_mfma_f32_16x16x32_bf16 v[136:139], v[140:143], v[164:167], v[136:139]
	v_mfma_f32_16x16x32_bf16 v[128:131], v[148:151], v[164:167], v[128:131]
	v_mfma_f32_16x16x32_bf16 v[100:103], v[140:143], v[172:175], v[100:103]
	v_mfma_f32_16x16x32_bf16 v[96:99], v[148:151], v[172:175], v[96:99]
	v_mfma_f32_16x16x32_bf16 v[84:87], v[140:143], v[180:183], v[84:87]
	v_mfma_f32_16x16x32_bf16 v[80:83], v[148:151], v[180:183], v[80:83]
	v_mfma_f32_16x16x32_bf16 v[68:71], v[140:143], v[208:211], v[68:71]
	v_mfma_f32_16x16x32_bf16 v[64:67], v[148:151], v[208:211], v[64:67]
	s_setprio 0
	s_barrier
; #define PG8_STAGE(bufoff, gbase, voff) do { _Pragma("unroll") for (int _i = 0; _i < 2; ++_i) \
;         __builtin_amdgcn_global_load_lds((const unsigned*)((const char*)(gbase) + (voff)[_i]), (PG8_LAS unsigned*)(lds + (bufoff) + ldsw + _i * 8192), 16, 0, 0); } while (0)
; #define PG8_LDA(dst, b, h) do { _Pragma("unroll") for (int m = 0; m < 4; ++m) _Pragma("unroll") for (int k = 0; k < 2; ++k) dst[m][k] = *(const PG8_LAS bf16x8*)(lds + PG8_SA(b, h) + aoff + m * 2048 + k * 1024); } while (0)
; #define PG8_MMA(ai, bj, At, Bt) do { __builtin_amdgcn_s_setprio(1); _Pragma("unroll") for (int m = 0; m < 4; ++m) _Pragma("unroll") for (int n = 0; n < 2; ++n) _Pragma("unroll") for (int k = 0; k < 2; ++k) \
;         acc[ai][bj][m][n] = __builtin_amdgcn_mfma_f32_16x16x32_bf16(Bt[n][k], At[m][k], acc[ai][bj][m][n], 0, 0, 0); __builtin_amdgcn_s_setprio(0); } while (0)
; #define PG8_WAIT_V(n) asm volatile("s_waitcnt vmcnt(" #n ")" ::: "memory")
; #define PG8_WAIT_L(n) asm volatile("s_waitcnt lgkmcnt(" #n ")" ::: "memory")
; #define PG8_BAR __builtin_amdgcn_s_barrier()
; #define PG8_SCHED __builtin_amdgcn_sched_barrier(0)
; template <class Epi, class Sched, bool ALIGN_EPI = false, bool SP2 = false>
; __device__ __forceinline__ void gemm_phase(PG8_LAS unsigned char* lds, const Gemm g, const Sched& S, const Epi& E) {
;     ...
;             PG8_LDA(At, 1, 1); PG8_STAGE(PG8_SB(1, 0), b3, voffB); PG8_STAGE(PG8_SB(1, 1), b3 + hstep, voffB); PG8_STAGE(PG8_SA(1, 0), a3, voffA);
;             PG8_WAIT_V(8); PG8_WAIT_L(0); PG8_BAR; PG8_MMA(1, 0, At, B0); PG8_MMA(1, 1, At, B1); PG8_BAR; PG8_SCHED;
	s_add_i32 s30, s60, s37
	v_lshl_add_u64 v[212:213], v[212:213], 0, s[78:79]
	s_mov_b32 m0, s30
	ds_read_b128 v[152:155], v241 offset:49152
	ds_read_b128 v[164:167], v241 offset:50176
	ds_read_b128 v[168:171], v241 offset:51200
	ds_read_b128 v[172:175], v241 offset:52224
	ds_read_b128 v[176:179], v241 offset:53248
	ds_read_b128 v[180:183], v241 offset:54272
	ds_read_b128 v[184:187], v241 offset:55296
	ds_read_b128 v[208:211], v241 offset:56320
	global_load_lds_dwordx4 v[212:213], off
	s_add_i32 m0, s30, 0x2000
	s_add_u32 s28, s28, 0x200080
	v_lshl_add_u64 v[212:213], v[214:215], 0, s[78:79]
	s_addc_u32 s29, s29, 0
	s_add_i32 s30, s61, s37
	global_load_lds_dwordx4 v[212:213], off
	v_lshl_add_u64 v[212:213], s[28:29], 0, v[188:189]
	s_mov_b32 m0, s30
	s_nop 0
	global_load_lds_dwordx4 v[212:213], off
	v_lshl_add_u64 v[212:213], s[28:29], 0, v[198:199]
	s_add_i32 m0, s30, 0x2000
	s_nop 0
	global_load_lds_dwordx4 v[212:213], off
	v_lshl_add_u64 v[212:213], v[216:217], 0, s[78:79]
	s_mov_b32 m0, s44
	s_nop 0
	global_load_lds_dwordx4 v[212:213], off
	v_lshl_add_u64 v[212:213], v[218:219], 0, s[78:79]
	s_mov_b32 m0, s45
	s_nop 0
	global_load_lds_dwordx4 v[212:213], off
	s_waitcnt vmcnt(8)
	s_waitcnt lgkmcnt(0)
	s_barrier
	s_setprio 1
	s_waitcnt lgkmcnt(0)
	v_mfma_f32_16x16x32_bf16 v[60:63], v[112:115], v[152:155], v[60:63]
	v_mfma_f32_16x16x32_bf16 v[56:59], v[120:123], v[152:155], v[56:59]
	v_mfma_f32_16x16x32_bf16 v[44:47], v[112:115], v[168:171], v[44:47]
	v_mfma_f32_16x16x32_bf16 v[40:43], v[120:123], v[168:171], v[40:43]
	v_mfma_f32_16x16x32_bf16 v[28:31], v[112:115], v[176:179], v[28:31]
	v_mfma_f32_16x16x32_bf16 v[24:27], v[120:123], v[176:179], v[24:27]
	v_mfma_f32_16x16x32_bf16 v[12:15], v[112:115], v[184:187], v[12:15]
	v_mfma_f32_16x16x32_bf16 v[8:11], v[120:123], v[184:187], v[8:11]
	v_mfma_f32_16x16x32_bf16 v[60:63], v[116:119], v[164:167], v[60:63]
	v_mfma_f32_16x16x32_bf16 v[56:59], v[124:127], v[164:167], v[56:59]
	v_mfma_f32_16x16x32_bf16 v[44:47], v[116:119], v[172:175], v[44:47]
	v_mfma_f32_16x16x32_bf16 v[40:43], v[124:127], v[172:175], v[40:43]
	v_mfma_f32_16x16x32_bf16 v[28:31], v[116:119], v[180:183], v[28:31]
	v_mfma_f32_16x16x32_bf16 v[24:27], v[124:127], v[180:183], v[24:27]
	v_mfma_f32_16x16x32_bf16 v[12:15], v[116:119], v[208:211], v[12:15]
	v_mfma_f32_16x16x32_bf16 v[8:11], v[124:127], v[208:211], v[8:11]
	v_mfma_f32_16x16x32_bf16 v[52:55], v[132:135], v[152:155], v[52:55]
	v_mfma_f32_16x16x32_bf16 v[48:51], v[144:147], v[152:155], v[48:51]
	v_mfma_f32_16x16x32_bf16 v[36:39], v[132:135], v[168:171], v[36:39]
	v_mfma_f32_16x16x32_bf16 v[32:35], v[144:147], v[168:171], v[32:35]
	v_mfma_f32_16x16x32_bf16 v[20:23], v[132:135], v[176:179], v[20:23]
	v_mfma_f32_16x16x32_bf16 v[16:19], v[144:147], v[176:179], v[16:19]
	v_mfma_f32_16x16x32_bf16 v[4:7], v[132:135], v[184:187], v[4:7]
	v_mfma_f32_16x16x32_bf16 v[0:3], v[144:147], v[184:187], v[0:3]
	v_mfma_f32_16x16x32_bf16 v[52:55], v[140:143], v[164:167], v[52:55]
	v_mfma_f32_16x16x32_bf16 v[48:51], v[148:151], v[164:167], v[48:51]
	v_mfma_f32_16x16x32_bf16 v[36:39], v[140:143], v[172:175], v[36:39]
	v_mfma_f32_16x16x32_bf16 v[32:35], v[148:151], v[172:175], v[32:35]
	v_mfma_f32_16x16x32_bf16 v[20:23], v[140:143], v[180:183], v[20:23]
	v_mfma_f32_16x16x32_bf16 v[16:19], v[148:151], v[180:183], v[16:19]
	v_mfma_f32_16x16x32_bf16 v[4:7], v[140:143], v[208:211], v[4:7]
	v_mfma_f32_16x16x32_bf16 v[0:3], v[148:151], v[208:211], v[0:3]
	s_setprio 0
	s_barrier
	s_add_i32 s72, s72, 2
	s_add_u32 s26, s26, 0x100
	s_addc_u32 s27, s27, 0
	s_add_u32 s67, s67, 0x100
	s_addc_u32 s68, s68, 0
	s_cmpk_gt_u32 s72, 0x7d
	s_cbranch_scc0 .LBB0_757
	s_and_b64 vcc, exec, s[16:17]
	s_cbranch_vccz .LBB0_760
	s_barrier

; #define PG8_STAGE(bufoff, gbase, voff) do { _Pragma("unroll") for (int _i = 0; _i < 2; ++_i) \
;         __builtin_amdgcn_global_load_lds((const unsigned*)((const char*)(gbase) + (voff)[_i]), (PG8_LAS unsigned*)(lds + (bufoff) + ldsw + _i * 8192), 16, 0, 0); } while (0)
; #define PG8_LDA(dst, b, h) do { _Pragma("unroll") for (int m = 0; m < 4; ++m) _Pragma("unroll") for (int k = 0; k < 2; ++k) dst[m][k] = *(const PG8_LAS bf16x8*)(lds + PG8_SA(b, h) + aoff + m * 2048 + k * 1024); } while (0)
; #define PG8_LDB(dst, b, h) do { _Pragma("unroll") for (int n = 0; n < 2; ++n) _Pragma("unroll") for (int k = 0; k < 2; ++k) dst[n][k] = *(const PG8_LAS bf16x8*)(lds + PG8_SB(b, h) + boff + n * 2048 + k * 1024); } while (0)
; #define PG8_MMA(ai, bj, At, Bt) do { __builtin_amdgcn_s_setprio(1); _Pragma("unroll") for (int m = 0; m < 4; ++m) _Pragma("unroll") for (int n = 0; n < 2; ++n) _Pragma("unroll") for (int k = 0; k < 2; ++k) \
;         acc[ai][bj][m][n] = __builtin_amdgcn_mfma_f32_16x16x32_bf16(Bt[n][k], At[m][k], acc[ai][bj][m][n], 0, 0, 0); __builtin_amdgcn_s_setprio(0); } while (0)
; #define PG8_WAIT_V(n) asm volatile("s_waitcnt vmcnt(" #n ")" ::: "memory")
; #define PG8_WAIT_L(n) asm volatile("s_waitcnt lgkmcnt(" #n ")" ::: "memory")
; #define PG8_BAR __builtin_amdgcn_s_barrier()
; #define PG8_SCHED __builtin_amdgcn_sched_barrier(0)
; template <class Epi, class Sched, bool ALIGN_EPI = false, bool SP2 = false>
; __device__ __forceinline__ void gemm_phase(PG8_LAS unsigned char* lds, const Gemm g, const Sched& S, const Epi& E) {
;     ...
;             const bool last = (t == nt - 2);
;             const char* a1 = cA + (size_t)(t + 1) * kstep;
;             const char* a2 = last ? nA : cA + (size_t)(t + 2) * kstep; const char* b2 = last ? nB : cB + (size_t)(t + 2) * kstep;
;             const char* a3 = a2 + kstep; const char* b3 = b2 + kstep;
;             if (last && has_next) S.a_ready(nxt);
;             if constexpr (SP2) {
;             PG8_LDB(B0, 0, 0); PG8_LDB(B1, 0, 1); PG8_SCHED; PG8_LDA(At, 0, 0); PG8_STAGE(PG8_SA(1, 1), a1 + hstep, voffA);
;             PG8_WAIT_V(8); PG8_WAIT_L(0); PG8_BAR; PG8_MMA(0, 0, At, B0); PG8_MMA(0, 1, At, B1); PG8_BAR; PG8_SCHED;
;             PG8_LDA(At, 0, 1); PG8_STAGE(PG8_SB(0, 0), b2, voffB); PG8_STAGE(PG8_SB(0, 1), b2 + hstep, voffB); PG8_STAGE(PG8_SA(0, 0), a2, voffA);
.LBB0_851:
	s_add_i32 s63, s24, 2
	s_add_u32 s60, s22, 0x80
	s_addc_u32 s25, s23, 0
	s_add_i32 s66, 0, 0x10000
	s_cmp_eq_u32 s39, s24
	s_cselect_b32 s25, s7, s25
	s_cselect_b32 s24, s6, s60
	s_cselect_b32 s61, s21, s62
	s_cselect_b32 s60, s20, s58
	s_add_i32 s67, 0, 0x14000
	v_add_u32_e32 v154, s66, v139
	v_add_u32_e32 v170, s67, v139
	ds_read_b128 v[142:145], v154
	ds_read_b128 v[146:149], v154 offset:1024
	ds_read_b128 v[150:153], v154 offset:2048
	ds_read_b128 v[154:157], v154 offset:3072
	ds_read_b128 v[158:161], v170
	ds_read_b128 v[162:165], v170 offset:1024
	ds_read_b128 v[166:169], v170 offset:2048
	ds_read_b128 v[170:173], v170 offset:3072
	v_lshl_add_u64 v[186:187], s[22:23], 0, v[134:135]
	s_add_i32 m0, s30, 0xc000
	ds_read_b128 v[174:177], v141
	ds_read_b128 v[178:181], v141 offset:1024
	ds_read_b128 v[182:185], v141 offset:2048
	ds_read_b128 v[198:201], v141 offset:3072
	ds_read_b128 v[202:205], v141 offset:4096
	ds_read_b128 v[206:209], v141 offset:5120
	ds_read_b128 v[210:213], v141 offset:6144
	ds_read_b128 v[214:217], v141 offset:7168
	global_load_lds_dwordx4 v[186:187], off
	v_lshl_add_u64 v[186:187], s[22:23], 0, v[136:137]
	s_add_i32 m0, s30, 0xe000
	s_nop 0
	global_load_lds_dwordx4 v[186:187], off
	s_nop 0
	s_waitcnt vmcnt(8)
	s_waitcnt lgkmcnt(0)
	s_barrier
	s_setprio 1
	s_waitcnt lgkmcnt(0)
	v_mfma_f32_16x16x32_bf16 v[120:123], v[142:145], v[174:177], v[120:123]
	v_mfma_f32_16x16x32_bf16 v[124:127], v[150:153], v[174:177], v[124:127]
	v_mfma_f32_16x16x32_bf16 v[108:111], v[142:145], v[182:185], v[108:111]
	v_mfma_f32_16x16x32_bf16 v[104:107], v[150:153], v[182:185], v[104:107]
	v_mfma_f32_16x16x32_bf16 v[92:95], v[142:145], v[202:205], v[92:95]
	v_mfma_f32_16x16x32_bf16 v[88:91], v[150:153], v[202:205], v[88:91]
	v_mfma_f32_16x16x32_bf16 v[76:79], v[142:145], v[210:213], v[76:79]
	v_mfma_f32_16x16x32_bf16 v[72:75], v[150:153], v[210:213], v[72:75]
	v_mfma_f32_16x16x32_bf16 v[120:123], v[146:149], v[178:181], v[120:123]
	v_mfma_f32_16x16x32_bf16 v[124:127], v[154:157], v[178:181], v[124:127]
	v_mfma_f32_16x16x32_bf16 v[108:111], v[146:149], v[198:201], v[108:111]
	v_mfma_f32_16x16x32_bf16 v[104:107], v[154:157], v[198:201], v[104:107]
	v_mfma_f32_16x16x32_bf16 v[92:95], v[146:149], v[206:209], v[92:95]
	v_mfma_f32_16x16x32_bf16 v[88:91], v[154:157], v[206:209], v[88:91]
	v_mfma_f32_16x16x32_bf16 v[76:79], v[146:149], v[214:217], v[76:79]
	v_mfma_f32_16x16x32_bf16 v[72:75], v[154:157], v[214:217], v[72:75]
	v_mfma_f32_16x16x32_bf16 v[116:119], v[158:161], v[174:177], v[116:119]
	v_mfma_f32_16x16x32_bf16 v[112:115], v[166:169], v[174:177], v[112:115]
	v_mfma_f32_16x16x32_bf16 v[100:103], v[158:161], v[182:185], v[100:103]
	v_mfma_f32_16x16x32_bf16 v[96:99], v[166:169], v[182:185], v[96:99]
	v_mfma_f32_16x16x32_bf16 v[84:87], v[158:161], v[202:205], v[84:87]
	v_mfma_f32_16x16x32_bf16 v[80:83], v[166:169], v[202:205], v[80:83]
	v_mfma_f32_16x16x32_bf16 v[68:71], v[158:161], v[210:213], v[68:71]
	v_mfma_f32_16x16x32_bf16 v[64:67], v[166:169], v[210:213], v[64:67]
	v_mfma_f32_16x16x32_bf16 v[116:119], v[162:165], v[178:181], v[116:119]
	v_mfma_f32_16x16x32_bf16 v[112:115], v[170:173], v[178:181], v[112:115]
	v_mfma_f32_16x16x32_bf16 v[100:103], v[162:165], v[198:201], v[100:103]
	v_mfma_f32_16x16x32_bf16 v[96:99], v[170:173], v[198:201], v[96:99]
	v_mfma_f32_16x16x32_bf16 v[84:87], v[162:165], v[206:209], v[84:87]
	v_mfma_f32_16x16x32_bf16 v[80:83], v[170:173], v[206:209], v[80:83]
	v_mfma_f32_16x16x32_bf16 v[68:71], v[162:165], v[214:217], v[68:71]
	v_mfma_f32_16x16x32_bf16 v[64:67], v[170:173], v[214:217], v[64:67]
	s_setprio 0
	s_barrier
	s_add_i32 s66, s66, s29
	v_lshl_add_u64 v[186:187], s[60:61], 0, v[188:189]
	s_mov_b32 m0, s66
	ds_read_b128 v[174:177], v141 offset:16384
	ds_read_b128 v[178:181], v141 offset:17408
	ds_read_b128 v[182:185], v141 offset:18432
	ds_read_b128 v[198:201], v141 offset:19456
	ds_read_b128 v[202:205], v141 offset:20480
	ds_read_b128 v[206:209], v141 offset:21504
	ds_read_b128 v[210:213], v141 offset:22528
	ds_read_b128 v[214:217], v141 offset:23552
	global_load_lds_dwordx4 v[186:187], off
	s_add_i32 m0, s66, 0x2000
	v_lshl_add_u64 v[218:219], s[60:61], 0, v[128:129]
	s_add_u32 s60, s60, s0
	s_addc_u32 s61, s61, s1
	s_add_i32 s66, s67, s29
	global_load_lds_dwordx4 v[218:219], off
	v_lshl_add_u64 v[220:221], s[60:61], 0, v[188:189]
	s_mov_b32 m0, s66
	v_lshl_add_u64 v[222:223], s[60:61], 0, v[128:129]
	global_load_lds_dwordx4 v[220:221], off
	s_add_i32 m0, s66, 0x2000
	v_lshl_add_u64 v[224:225], s[24:25], 0, v[132:133]
	global_load_lds_dwordx4 v[222:223], off
	s_mov_b32 m0, s30
	v_lshl_add_u64 v[226:227], s[24:25], 0, v[130:131]
	global_load_lds_dwordx4 v[224:225], off
	s_mov_b32 m0, s31
	s_nop 0
	global_load_lds_dwordx4 v[226:227], off
	s_waitcnt vmcnt(8)
	s_waitcnt lgkmcnt(0)
	s_barrier
; #define PG8_STAGE(bufoff, gbase, voff) do { _Pragma("unroll") for (int _i = 0; _i < 2; ++_i) \
;         __builtin_amdgcn_global_load_lds((const unsigned*)((const char*)(gbase) + (voff)[_i]), (PG8_LAS unsigned*)(lds + (bufoff) + ldsw + _i * 8192), 16, 0, 0); } while (0)
; #define PG8_LDA(dst, b, h) do { _Pragma("unroll") for (int m = 0; m < 4; ++m) _Pragma("unroll") for (int k = 0; k < 2; ++k) dst[m][k] = *(const PG8_LAS bf16x8*)(lds + PG8_SA(b, h) + aoff + m * 2048 + k * 1024); } while (0)
; #define PG8_LDB(dst, b, h) do { _Pragma("unroll") for (int n = 0; n < 2; ++n) _Pragma("unroll") for (int k = 0; k < 2; ++k) dst[n][k] = *(const PG8_LAS bf16x8*)(lds + PG8_SB(b, h) + boff + n * 2048 + k * 1024); } while (0)
; #define PG8_MMA(ai, bj, At, Bt) do { __builtin_amdgcn_s_setprio(1); _Pragma("unroll") for (int m = 0; m < 4; ++m) _Pragma("unroll") for (int n = 0; n < 2; ++n) _Pragma("unroll") for (int k = 0; k < 2; ++k) \
;         acc[ai][bj][m][n] = __builtin_amdgcn_mfma_f32_16x16x32_bf16(Bt[n][k], At[m][k], acc[ai][bj][m][n], 0, 0, 0); __builtin_amdgcn_s_setprio(0); } while (0)
; #define PG8_WAIT_V(n) asm volatile("s_waitcnt vmcnt(" #n ")" ::: "memory")
; #define PG8_WAIT_L(n) asm volatile("s_waitcnt lgkmcnt(" #n ")" ::: "memory")
; #define PG8_BAR __builtin_amdgcn_s_barrier()
; #define PG8_SCHED __builtin_amdgcn_sched_barrier(0)
; template <class Epi, class Sched, bool ALIGN_EPI = false, bool SP2 = false>
; __device__ __forceinline__ void gemm_phase(PG8_LAS unsigned char* lds, const Gemm g, const Sched& S, const Epi& E) {
;     ...
;             PG8_WAIT_V(8); PG8_WAIT_L(0); PG8_BAR; PG8_MMA(1, 0, At, B0); PG8_MMA(1, 1, At, B1); PG8_BAR; PG8_SCHED;
;             PG8_LDB(B0, 1, 0); PG8_LDB(B1, 1, 1); PG8_SCHED; PG8_LDA(At, 1, 0); PG8_STAGE(PG8_SA(0, 1), a2 + hstep, voffA);
;             PG8_WAIT_V(8); PG8_WAIT_L(0); PG8_BAR; PG8_MMA(0, 0, At, B0); PG8_MMA(0, 1, At, B1); PG8_BAR; PG8_SCHED;
	s_setprio 1
	s_waitcnt lgkmcnt(0)
	v_mfma_f32_16x16x32_bf16 v[60:63], v[142:145], v[174:177], v[60:63]
	v_mfma_f32_16x16x32_bf16 v[56:59], v[150:153], v[174:177], v[56:59]
	v_mfma_f32_16x16x32_bf16 v[44:47], v[142:145], v[182:185], v[44:47]
	v_mfma_f32_16x16x32_bf16 v[40:43], v[150:153], v[182:185], v[40:43]
	v_mfma_f32_16x16x32_bf16 v[28:31], v[142:145], v[202:205], v[28:31]
	v_mfma_f32_16x16x32_bf16 v[24:27], v[150:153], v[202:205], v[24:27]
	v_mfma_f32_16x16x32_bf16 v[12:15], v[142:145], v[210:213], v[12:15]
	v_mfma_f32_16x16x32_bf16 v[8:11], v[150:153], v[210:213], v[8:11]
	v_mfma_f32_16x16x32_bf16 v[60:63], v[146:149], v[178:181], v[60:63]
	v_mfma_f32_16x16x32_bf16 v[56:59], v[154:157], v[178:181], v[56:59]
	v_mfma_f32_16x16x32_bf16 v[44:47], v[146:149], v[198:201], v[44:47]
	v_mfma_f32_16x16x32_bf16 v[40:43], v[154:157], v[198:201], v[40:43]
	v_mfma_f32_16x16x32_bf16 v[28:31], v[146:149], v[206:209], v[28:31]
	v_mfma_f32_16x16x32_bf16 v[24:27], v[154:157], v[206:209], v[24:27]
	v_mfma_f32_16x16x32_bf16 v[12:15], v[146:149], v[214:217], v[12:15]
	v_mfma_f32_16x16x32_bf16 v[8:11], v[154:157], v[214:217], v[8:11]
	v_mfma_f32_16x16x32_bf16 v[52:55], v[158:161], v[174:177], v[52:55]
	v_mfma_f32_16x16x32_bf16 v[48:51], v[166:169], v[174:177], v[48:51]
	v_mfma_f32_16x16x32_bf16 v[36:39], v[158:161], v[182:185], v[36:39]
	v_mfma_f32_16x16x32_bf16 v[32:35], v[166:169], v[182:185], v[32:35]
	v_mfma_f32_16x16x32_bf16 v[20:23], v[158:161], v[202:205], v[20:23]
	v_mfma_f32_16x16x32_bf16 v[16:19], v[166:169], v[202:205], v[16:19]
	v_mfma_f32_16x16x32_bf16 v[4:7], v[158:161], v[210:213], v[4:7]
	v_mfma_f32_16x16x32_bf16 v[0:3], v[166:169], v[210:213], v[0:3]
	v_mfma_f32_16x16x32_bf16 v[52:55], v[162:165], v[178:181], v[52:55]
	v_mfma_f32_16x16x32_bf16 v[48:51], v[170:173], v[178:181], v[48:51]
	v_mfma_f32_16x16x32_bf16 v[36:39], v[162:165], v[198:201], v[36:39]
	v_mfma_f32_16x16x32_bf16 v[32:35], v[170:173], v[198:201], v[32:35]
	v_mfma_f32_16x16x32_bf16 v[20:23], v[162:165], v[206:209], v[20:23]
	v_mfma_f32_16x16x32_bf16 v[16:19], v[170:173], v[206:209], v[16:19]
	v_mfma_f32_16x16x32_bf16 v[4:7], v[162:165], v[214:217], v[4:7]
	v_mfma_f32_16x16x32_bf16 v[0:3], v[170:173], v[214:217], v[0:3]
	s_setprio 0
	s_barrier
	s_add_i32 s60, 0, 0x18000
	s_add_i32 s61, 0, 0x1c000
	v_add_u32_e32 v154, s60, v139
	v_add_u32_e32 v170, s61, v139
	ds_read_b128 v[142:145], v154
	ds_read_b128 v[146:149], v154 offset:1024
	ds_read_b128 v[150:153], v154 offset:2048
	ds_read_b128 v[154:157], v154 offset:3072
	ds_read_b128 v[158:161], v170
	ds_read_b128 v[162:165], v170 offset:1024
	ds_read_b128 v[166:169], v170 offset:2048
	ds_read_b128 v[170:173], v170 offset:3072
	s_add_u32 s24, s24, s0
	s_addc_u32 s25, s25, s1
	s_mov_b32 m0, s34
	v_lshl_add_u64 v[228:229], s[24:25], 0, v[132:133]
	ds_read_b128 v[174:177], v141 offset:32768
	ds_read_b128 v[178:181], v141 offset:33792
	ds_read_b128 v[182:185], v141 offset:34816
	ds_read_b128 v[198:201], v141 offset:35840
	ds_read_b128 v[202:205], v141 offset:36864
	ds_read_b128 v[206:209], v141 offset:37888
	ds_read_b128 v[210:213], v141 offset:38912
	ds_read_b128 v[214:217], v141 offset:39936
	global_load_lds_dwordx4 v[228:229], off
	v_lshl_add_u64 v[228:229], s[24:25], 0, v[130:131]
	s_mov_b32 m0, s35
	s_nop 0
	global_load_lds_dwordx4 v[228:229], off
	s_waitcnt vmcnt(8)
	s_waitcnt lgkmcnt(0)
	s_barrier
	s_setprio 1
	s_waitcnt lgkmcnt(0)
	v_mfma_f32_16x16x32_bf16 v[120:123], v[142:145], v[174:177], v[120:123]
	v_mfma_f32_16x16x32_bf16 v[124:127], v[150:153], v[174:177], v[124:127]
	v_mfma_f32_16x16x32_bf16 v[108:111], v[142:145], v[182:185], v[108:111]
	v_mfma_f32_16x16x32_bf16 v[104:107], v[150:153], v[182:185], v[104:107]
	v_mfma_f32_16x16x32_bf16 v[92:95], v[142:145], v[202:205], v[92:95]
	v_mfma_f32_16x16x32_bf16 v[88:91], v[150:153], v[202:205], v[88:91]
	v_mfma_f32_16x16x32_bf16 v[76:79], v[142:145], v[210:213], v[76:79]
	v_mfma_f32_16x16x32_bf16 v[72:75], v[150:153], v[210:213], v[72:75]
	v_mfma_f32_16x16x32_bf16 v[120:123], v[146:149], v[178:181], v[120:123]
	v_mfma_f32_16x16x32_bf16 v[124:127], v[154:157], v[178:181], v[124:127]
	v_mfma_f32_16x16x32_bf16 v[108:111], v[146:149], v[198:201], v[108:111]
	v_mfma_f32_16x16x32_bf16 v[104:107], v[154:157], v[198:201], v[104:107]
	v_mfma_f32_16x16x32_bf16 v[92:95], v[146:149], v[206:209], v[92:95]
	v_mfma_f32_16x16x32_bf16 v[88:91], v[154:157], v[206:209], v[88:91]
	v_mfma_f32_16x16x32_bf16 v[76:79], v[146:149], v[214:217], v[76:79]
	v_mfma_f32_16x16x32_bf16 v[72:75], v[154:157], v[214:217], v[72:75]
	v_mfma_f32_16x16x32_bf16 v[116:119], v[158:161], v[174:177], v[116:119]
	v_mfma_f32_16x16x32_bf16 v[112:115], v[166:169], v[174:177], v[112:115]
	v_mfma_f32_16x16x32_bf16 v[100:103], v[158:161], v[182:185], v[100:103]
	v_mfma_f32_16x16x32_bf16 v[96:99], v[166:169], v[182:185], v[96:99]
	v_mfma_f32_16x16x32_bf16 v[84:87], v[158:161], v[202:205], v[84:87]
	v_mfma_f32_16x16x32_bf16 v[80:83], v[166:169], v[202:205], v[80:83]
	v_mfma_f32_16x16x32_bf16 v[68:71], v[158:161], v[210:213], v[68:71]
	v_mfma_f32_16x16x32_bf16 v[64:67], v[166:169], v[210:213], v[64:67]
	v_mfma_f32_16x16x32_bf16 v[116:119], v[162:165], v[178:181], v[116:119]
	v_mfma_f32_16x16x32_bf16 v[112:115], v[170:173], v[178:181], v[112:115]
	v_mfma_f32_16x16x32_bf16 v[100:103], v[162:165], v[198:201], v[100:103]
	v_mfma_f32_16x16x32_bf16 v[96:99], v[170:173], v[198:201], v[96:99]
	v_mfma_f32_16x16x32_bf16 v[84:87], v[162:165], v[206:209], v[84:87]
	v_mfma_f32_16x16x32_bf16 v[80:83], v[170:173], v[206:209], v[80:83]
	v_mfma_f32_16x16x32_bf16 v[68:71], v[162:165], v[214:217], v[68:71]
	v_mfma_f32_16x16x32_bf16 v[64:67], v[170:173], v[214:217], v[64:67]
	s_setprio 0
	s_barrier
; #define PG8_STAGE(bufoff, gbase, voff) do { _Pragma("unroll") for (int _i = 0; _i < 2; ++_i) \
;         __builtin_amdgcn_global_load_lds((const unsigned*)((const char*)(gbase) + (voff)[_i]), (PG8_LAS unsigned*)(lds + (bufoff) + ldsw + _i * 8192), 16, 0, 0); } while (0)
; #define PG8_LDA(dst, b, h) do { _Pragma("unroll") for (int m = 0; m < 4; ++m) _Pragma("unroll") for (int k = 0; k < 2; ++k) dst[m][k] = *(const PG8_LAS bf16x8*)(lds + PG8_SA(b, h) + aoff + m * 2048 + k * 1024); } while (0)
; #define PG8_MMA(ai, bj, At, Bt) do { __builtin_amdgcn_s_setprio(1); _Pragma("unroll") for (int m = 0; m < 4; ++m) _Pragma("unroll") for (int n = 0; n < 2; ++n) _Pragma("unroll") for (int k = 0; k < 2; ++k) \
;         acc[ai][bj][m][n] = __builtin_amdgcn_mfma_f32_16x16x32_bf16(Bt[n][k], At[m][k], acc[ai][bj][m][n], 0, 0, 0); __builtin_amdgcn_s_setprio(0); } while (0)
; #define PG8_WAIT_V(n) asm volatile("s_waitcnt vmcnt(" #n ")" ::: "memory")
; #define PG8_WAIT_L(n) asm volatile("s_waitcnt lgkmcnt(" #n ")" ::: "memory")
; #define PG8_BAR __builtin_amdgcn_s_barrier()
; #define PG8_SCHED __builtin_amdgcn_sched_barrier(0)
; template <class Epi, class Sched, bool ALIGN_EPI = false, bool SP2 = false>
; __device__ __forceinline__ void gemm_phase(PG8_LAS unsigned char* lds, const Gemm g, const Sched& S, const Epi& E) {
;     ...
;             PG8_LDA(At, 1, 1); PG8_STAGE(PG8_SB(1, 0), b3, voffB); PG8_STAGE(PG8_SB(1, 1), b3 + hstep, voffB); PG8_STAGE(PG8_SA(1, 0), a3, voffA);
;             PG8_WAIT_V(8); PG8_WAIT_L(0); PG8_BAR; PG8_MMA(1, 0, At, B0); PG8_MMA(1, 1, At, B1); PG8_BAR; PG8_SCHED;
	s_add_i32 s24, s60, s29
	v_lshl_add_u64 v[186:187], v[186:187], 0, s[78:79]
	s_mov_b32 m0, s24
	ds_read_b128 v[174:177], v141 offset:49152
	ds_read_b128 v[178:181], v141 offset:50176
	ds_read_b128 v[182:185], v141 offset:51200
	ds_read_b128 v[198:201], v141 offset:52224
	ds_read_b128 v[202:205], v141 offset:53248
	ds_read_b128 v[206:209], v141 offset:54272
	ds_read_b128 v[210:213], v141 offset:55296
	ds_read_b128 v[214:217], v141 offset:56320
	global_load_lds_dwordx4 v[186:187], off
	v_lshl_add_u64 v[186:187], v[218:219], 0, s[78:79]
	s_add_i32 m0, s24, 0x2000
	s_add_i32 s24, s61, s29
	global_load_lds_dwordx4 v[186:187], off
	v_lshl_add_u64 v[186:187], v[220:221], 0, s[78:79]
	s_mov_b32 m0, s24
	s_nop 0
	global_load_lds_dwordx4 v[186:187], off
	v_lshl_add_u64 v[186:187], v[222:223], 0, s[78:79]
	s_add_i32 m0, s24, 0x2000
	s_nop 0
	global_load_lds_dwordx4 v[186:187], off
	v_lshl_add_u64 v[186:187], v[224:225], 0, s[78:79]
	s_mov_b32 m0, s37
	s_nop 0
	global_load_lds_dwordx4 v[186:187], off
	v_lshl_add_u64 v[186:187], v[226:227], 0, s[78:79]
	s_mov_b32 m0, s38
	s_nop 0
	global_load_lds_dwordx4 v[186:187], off
	s_nop 0
	s_waitcnt vmcnt(8)
	s_waitcnt lgkmcnt(0)
	s_barrier
	s_setprio 1
	s_waitcnt lgkmcnt(0)
	v_mfma_f32_16x16x32_bf16 v[60:63], v[142:145], v[174:177], v[60:63]
	v_mfma_f32_16x16x32_bf16 v[56:59], v[150:153], v[174:177], v[56:59]
	v_mfma_f32_16x16x32_bf16 v[44:47], v[142:145], v[182:185], v[44:47]
	v_mfma_f32_16x16x32_bf16 v[40:43], v[150:153], v[182:185], v[40:43]
	v_mfma_f32_16x16x32_bf16 v[28:31], v[142:145], v[202:205], v[28:31]
	v_mfma_f32_16x16x32_bf16 v[24:27], v[150:153], v[202:205], v[24:27]
	v_mfma_f32_16x16x32_bf16 v[12:15], v[142:145], v[210:213], v[12:15]
	v_mfma_f32_16x16x32_bf16 v[8:11], v[150:153], v[210:213], v[8:11]
	v_mfma_f32_16x16x32_bf16 v[60:63], v[146:149], v[178:181], v[60:63]
	v_mfma_f32_16x16x32_bf16 v[56:59], v[154:157], v[178:181], v[56:59]
	v_mfma_f32_16x16x32_bf16 v[44:47], v[146:149], v[198:201], v[44:47]
	v_mfma_f32_16x16x32_bf16 v[40:43], v[154:157], v[198:201], v[40:43]
	v_mfma_f32_16x16x32_bf16 v[28:31], v[146:149], v[206:209], v[28:31]
	v_mfma_f32_16x16x32_bf16 v[24:27], v[154:157], v[206:209], v[24:27]
	v_mfma_f32_16x16x32_bf16 v[12:15], v[146:149], v[214:217], v[12:15]
	v_mfma_f32_16x16x32_bf16 v[8:11], v[154:157], v[214:217], v[8:11]
	v_mfma_f32_16x16x32_bf16 v[52:55], v[158:161], v[174:177], v[52:55]
	v_mfma_f32_16x16x32_bf16 v[48:51], v[166:169], v[174:177], v[48:51]
	v_mfma_f32_16x16x32_bf16 v[36:39], v[158:161], v[182:185], v[36:39]
	v_mfma_f32_16x16x32_bf16 v[32:35], v[166:169], v[182:185], v[32:35]
	v_mfma_f32_16x16x32_bf16 v[20:23], v[158:161], v[202:205], v[20:23]
	v_mfma_f32_16x16x32_bf16 v[16:19], v[166:169], v[202:205], v[16:19]
	v_mfma_f32_16x16x32_bf16 v[4:7], v[158:161], v[210:213], v[4:7]
	v_mfma_f32_16x16x32_bf16 v[0:3], v[166:169], v[210:213], v[0:3]
	v_mfma_f32_16x16x32_bf16 v[52:55], v[162:165], v[178:181], v[52:55]
	v_mfma_f32_16x16x32_bf16 v[48:51], v[170:173], v[178:181], v[48:51]
	v_mfma_f32_16x16x32_bf16 v[36:39], v[162:165], v[198:201], v[36:39]
	v_mfma_f32_16x16x32_bf16 v[32:35], v[170:173], v[198:201], v[32:35]
	v_mfma_f32_16x16x32_bf16 v[20:23], v[162:165], v[206:209], v[20:23]
	v_mfma_f32_16x16x32_bf16 v[16:19], v[170:173], v[206:209], v[16:19]
	v_mfma_f32_16x16x32_bf16 v[4:7], v[162:165], v[214:217], v[4:7]
	v_mfma_f32_16x16x32_bf16 v[0:3], v[170:173], v[214:217], v[0:3]
	s_setprio 0
	s_barrier
	s_add_u32 s22, s22, 0x100
	s_addc_u32 s23, s23, 0
	s_add_u32 s58, s58, 0x100
	s_addc_u32 s62, s62, 0
	s_cmp_ge_i32 s63, s36
	s_mov_b32 s24, s63
	s_cbranch_scc0 .LBB0_851
	s_mov_b32 s67, 0x20000
	s_mov_b32 s66, 0x30000

; #define PG8_STAGE(bufoff, gbase, voff) do { _Pragma("unroll") for (int _i = 0; _i < 2; ++_i) \
;         __builtin_amdgcn_global_load_lds((const unsigned*)((const char*)(gbase) + (voff)[_i]), (PG8_LAS unsigned*)(lds + (bufoff) + ldsw + _i * 8192), 16, 0, 0); } while (0)
; #define PG8_LDA(dst, b, h) do { _Pragma("unroll") for (int m = 0; m < 4; ++m) _Pragma("unroll") for (int k = 0; k < 2; ++k) dst[m][k] = *(const PG8_LAS bf16x8*)(lds + PG8_SA(b, h) + aoff + m * 2048 + k * 1024); } while (0)
; #define PG8_LDB(dst, b, h) do { _Pragma("unroll") for (int n = 0; n < 2; ++n) _Pragma("unroll") for (int k = 0; k < 2; ++k) dst[n][k] = *(const PG8_LAS bf16x8*)(lds + PG8_SB(b, h) + boff + n * 2048 + k * 1024); } while (0)
; #define PG8_MMA(ai, bj, At, Bt) do { __builtin_amdgcn_s_setprio(1); _Pragma("unroll") for (int m = 0; m < 4; ++m) _Pragma("unroll") for (int n = 0; n < 2; ++n) _Pragma("unroll") for (int k = 0; k < 2; ++k) \
;         acc[ai][bj][m][n] = __builtin_amdgcn_mfma_f32_16x16x32_bf16(Bt[n][k], At[m][k], acc[ai][bj][m][n], 0, 0, 0); __builtin_amdgcn_s_setprio(0); } while (0)
; #define PG8_WAIT_V(n) asm volatile("s_waitcnt vmcnt(" #n ")" ::: "memory")
; #define PG8_WAIT_L(n) asm volatile("s_waitcnt lgkmcnt(" #n ")" ::: "memory")
; #define PG8_BAR __builtin_amdgcn_s_barrier()
; #define PG8_SCHED __builtin_amdgcn_sched_barrier(0)
; template <class Epi, class Sched, bool ALIGN_EPI = false, bool SP2 = false>
; __device__ __forceinline__ void gemm_phase(PG8_LAS unsigned char* lds, const Gemm g, const Sched& S, const Epi& E) {
;     ...
;             const bool last = (t == nt - 2);
;             const char* a1 = cA + (size_t)(t + 1) * kstep;
;             const char* a2 = last ? nA : cA + (size_t)(t + 2) * kstep; const char* b2 = last ? nB : cB + (size_t)(t + 2) * kstep;
;             const char* a3 = a2 + kstep; const char* b3 = b2 + kstep;
;             if (last && has_next) S.a_ready(nxt);
;             if constexpr (SP2) {
;             PG8_LDB(B0, 0, 0); PG8_LDB(B1, 0, 1); PG8_SCHED; PG8_LDA(At, 0, 0); PG8_STAGE(PG8_SA(1, 1), a1 + hstep, voffA);
;             PG8_WAIT_V(8); PG8_WAIT_L(0); PG8_BAR; PG8_MMA(0, 0, At, B0); PG8_MMA(0, 1, At, B1); PG8_BAR; PG8_SCHED;
;             PG8_LDA(At, 0, 1); PG8_STAGE(PG8_SB(0, 0), b2, voffB); PG8_STAGE(PG8_SB(0, 1), b2 + hstep, voffB); PG8_STAGE(PG8_SA(0, 0), a2, voffA);
.LBB0_872:
	s_add_u32 s36, s34, 0xfff80080
	s_addc_u32 s37, s35, -1
	s_add_i32 s60, 0, 0x10000
	s_cmp_eq_u32 s72, 28
	s_cselect_b32 s39, s23, s37
	s_cselect_b32 s38, s29, s36
	s_cselect_b32 s37, s21, s68
	s_cselect_b32 s36, s66, s67
	s_add_i32 s73, 0, 0x14000
	v_add_u32_e32 v132, s60, v225
	v_add_u32_e32 v156, s73, v225
	ds_read_b128 v[112:115], v132
	ds_read_b128 v[116:119], v132 offset:1024
	ds_read_b128 v[120:123], v132 offset:2048
	ds_read_b128 v[132:135], v132 offset:3072
	ds_read_b128 v[140:143], v156
	ds_read_b128 v[148:151], v156 offset:1024
	ds_read_b128 v[152:155], v156 offset:2048
	ds_read_b128 v[156:159], v156 offset:3072
	v_lshl_add_u64 v[212:213], s[34:35], 0, v[186:187]
	s_add_i32 m0, s2, 0xc000
	ds_read_b128 v[160:163], v227
	ds_read_b128 v[164:167], v227 offset:1024
	ds_read_b128 v[168:171], v227 offset:2048
	ds_read_b128 v[172:175], v227 offset:3072
	ds_read_b128 v[176:179], v227 offset:4096
	ds_read_b128 v[200:203], v227 offset:5120
	ds_read_b128 v[204:207], v227 offset:6144
	ds_read_b128 v[208:211], v227 offset:7168
	global_load_lds_dwordx4 v[212:213], off
	v_lshl_add_u64 v[212:213], s[34:35], 0, v[198:199]
	s_add_i32 m0, s2, 0xe000
	s_nop 0
	global_load_lds_dwordx4 v[212:213], off
	s_waitcnt vmcnt(8)
	s_waitcnt lgkmcnt(0)
	s_barrier
	s_setprio 1
	s_waitcnt lgkmcnt(0)
	v_mfma_f32_16x16x32_bf16 v[144:147], v[112:115], v[160:163], v[144:147]
	v_mfma_f32_16x16x32_bf16 v[136:139], v[120:123], v[160:163], v[136:139]
	v_mfma_f32_16x16x32_bf16 v[108:111], v[112:115], v[168:171], v[108:111]
	v_mfma_f32_16x16x32_bf16 v[104:107], v[120:123], v[168:171], v[104:107]
	v_mfma_f32_16x16x32_bf16 v[92:95], v[112:115], v[176:179], v[92:95]
	v_mfma_f32_16x16x32_bf16 v[88:91], v[120:123], v[176:179], v[88:91]
	v_mfma_f32_16x16x32_bf16 v[76:79], v[112:115], v[204:207], v[76:79]
	v_mfma_f32_16x16x32_bf16 v[72:75], v[120:123], v[204:207], v[72:75]
	v_mfma_f32_16x16x32_bf16 v[144:147], v[116:119], v[164:167], v[144:147]
	v_mfma_f32_16x16x32_bf16 v[136:139], v[132:135], v[164:167], v[136:139]
	v_mfma_f32_16x16x32_bf16 v[108:111], v[116:119], v[172:175], v[108:111]
	v_mfma_f32_16x16x32_bf16 v[104:107], v[132:135], v[172:175], v[104:107]
	v_mfma_f32_16x16x32_bf16 v[92:95], v[116:119], v[200:203], v[92:95]
	v_mfma_f32_16x16x32_bf16 v[88:91], v[132:135], v[200:203], v[88:91]
	v_mfma_f32_16x16x32_bf16 v[76:79], v[116:119], v[208:211], v[76:79]
	v_mfma_f32_16x16x32_bf16 v[72:75], v[132:135], v[208:211], v[72:75]
	v_mfma_f32_16x16x32_bf16 v[128:131], v[140:143], v[160:163], v[128:131]
	v_mfma_f32_16x16x32_bf16 v[124:127], v[152:155], v[160:163], v[124:127]
	v_mfma_f32_16x16x32_bf16 v[100:103], v[140:143], v[168:171], v[100:103]
	v_mfma_f32_16x16x32_bf16 v[96:99], v[152:155], v[168:171], v[96:99]
	v_mfma_f32_16x16x32_bf16 v[84:87], v[140:143], v[176:179], v[84:87]
	v_mfma_f32_16x16x32_bf16 v[80:83], v[152:155], v[176:179], v[80:83]
	v_mfma_f32_16x16x32_bf16 v[68:71], v[140:143], v[204:207], v[68:71]
	v_mfma_f32_16x16x32_bf16 v[64:67], v[152:155], v[204:207], v[64:67]
	v_mfma_f32_16x16x32_bf16 v[128:131], v[148:151], v[164:167], v[128:131]
	v_mfma_f32_16x16x32_bf16 v[124:127], v[156:159], v[164:167], v[124:127]
	v_mfma_f32_16x16x32_bf16 v[100:103], v[148:151], v[172:175], v[100:103]
	v_mfma_f32_16x16x32_bf16 v[96:99], v[156:159], v[172:175], v[96:99]
	v_mfma_f32_16x16x32_bf16 v[84:87], v[148:151], v[200:203], v[84:87]
	v_mfma_f32_16x16x32_bf16 v[80:83], v[156:159], v[200:203], v[80:83]
	v_mfma_f32_16x16x32_bf16 v[68:71], v[148:151], v[208:211], v[68:71]
	v_mfma_f32_16x16x32_bf16 v[64:67], v[156:159], v[208:211], v[64:67]
	s_setprio 0
	s_barrier
	s_add_i32 s60, s60, s44
	v_lshl_add_u64 v[212:213], s[36:37], 0, v[188:189]
	s_mov_b32 m0, s60
	ds_read_b128 v[160:163], v227 offset:16384
	ds_read_b128 v[164:167], v227 offset:17408
	ds_read_b128 v[168:171], v227 offset:18432
	ds_read_b128 v[172:175], v227 offset:19456
	ds_read_b128 v[176:179], v227 offset:20480
	ds_read_b128 v[200:203], v227 offset:21504
	ds_read_b128 v[204:207], v227 offset:22528
	ds_read_b128 v[208:211], v227 offset:23552
	global_load_lds_dwordx4 v[212:213], off
	s_add_i32 m0, s60, 0x2000
	s_add_u32 s60, s36, 0x80000
	v_lshl_add_u64 v[214:215], s[36:37], 0, v[180:181]
	s_addc_u32 s61, s37, 0
	s_add_i32 s73, s73, s44
	global_load_lds_dwordx4 v[214:215], off
	v_lshl_add_u64 v[216:217], s[60:61], 0, v[188:189]
	s_mov_b32 m0, s73
	v_lshl_add_u64 v[218:219], s[38:39], 0, v[182:183]
	global_load_lds_dwordx4 v[216:217], off
	v_lshl_add_u64 v[216:217], s[60:61], 0, v[180:181]
	s_add_i32 m0, s73, 0x2000
	s_nop 0
	global_load_lds_dwordx4 v[216:217], off
	v_lshl_add_u64 v[216:217], s[38:39], 0, v[184:185]
	s_mov_b32 m0, s2
	s_nop 0
	global_load_lds_dwordx4 v[216:217], off
	s_mov_b32 m0, s31
	s_nop 0
	global_load_lds_dwordx4 v[218:219], off
	s_nop 0
	s_waitcnt vmcnt(8)
	s_waitcnt lgkmcnt(0)
	s_barrier
; #define PG8_STAGE(bufoff, gbase, voff) do { _Pragma("unroll") for (int _i = 0; _i < 2; ++_i) \
;         __builtin_amdgcn_global_load_lds((const unsigned*)((const char*)(gbase) + (voff)[_i]), (PG8_LAS unsigned*)(lds + (bufoff) + ldsw + _i * 8192), 16, 0, 0); } while (0)
; #define PG8_LDA(dst, b, h) do { _Pragma("unroll") for (int m = 0; m < 4; ++m) _Pragma("unroll") for (int k = 0; k < 2; ++k) dst[m][k] = *(const PG8_LAS bf16x8*)(lds + PG8_SA(b, h) + aoff + m * 2048 + k * 1024); } while (0)
; #define PG8_LDB(dst, b, h) do { _Pragma("unroll") for (int n = 0; n < 2; ++n) _Pragma("unroll") for (int k = 0; k < 2; ++k) dst[n][k] = *(const PG8_LAS bf16x8*)(lds + PG8_SB(b, h) + boff + n * 2048 + k * 1024); } while (0)
; #define PG8_MMA(ai, bj, At, Bt) do { __builtin_amdgcn_s_setprio(1); _Pragma("unroll") for (int m = 0; m < 4; ++m) _Pragma("unroll") for (int n = 0; n < 2; ++n) _Pragma("unroll") for (int k = 0; k < 2; ++k) \
;         acc[ai][bj][m][n] = __builtin_amdgcn_mfma_f32_16x16x32_bf16(Bt[n][k], At[m][k], acc[ai][bj][m][n], 0, 0, 0); __builtin_amdgcn_s_setprio(0); } while (0)
; #define PG8_WAIT_V(n) asm volatile("s_waitcnt vmcnt(" #n ")" ::: "memory")
; #define PG8_WAIT_L(n) asm volatile("s_waitcnt lgkmcnt(" #n ")" ::: "memory")
; #define PG8_BAR __builtin_amdgcn_s_barrier()
; #define PG8_SCHED __builtin_amdgcn_sched_barrier(0)
; template <class Epi, class Sched, bool ALIGN_EPI = false, bool SP2 = false>
; __device__ __forceinline__ void gemm_phase(PG8_LAS unsigned char* lds, const Gemm g, const Sched& S, const Epi& E) {
;     ...
;             PG8_WAIT_V(8); PG8_WAIT_L(0); PG8_BAR; PG8_MMA(1, 0, At, B0); PG8_MMA(1, 1, At, B1); PG8_BAR; PG8_SCHED;
;             PG8_LDB(B0, 1, 0); PG8_LDB(B1, 1, 1); PG8_SCHED; PG8_LDA(At, 1, 0); PG8_STAGE(PG8_SA(0, 1), a2 + hstep, voffA);
;             PG8_WAIT_V(8); PG8_WAIT_L(0); PG8_BAR; PG8_MMA(0, 0, At, B0); PG8_MMA(0, 1, At, B1); PG8_BAR; PG8_SCHED;
	s_setprio 1
	s_waitcnt lgkmcnt(0)
	v_mfma_f32_16x16x32_bf16 v[60:63], v[112:115], v[160:163], v[60:63]
	v_mfma_f32_16x16x32_bf16 v[56:59], v[120:123], v[160:163], v[56:59]
	v_mfma_f32_16x16x32_bf16 v[44:47], v[112:115], v[168:171], v[44:47]
	v_mfma_f32_16x16x32_bf16 v[40:43], v[120:123], v[168:171], v[40:43]
	v_mfma_f32_16x16x32_bf16 v[28:31], v[112:115], v[176:179], v[28:31]
	v_mfma_f32_16x16x32_bf16 v[24:27], v[120:123], v[176:179], v[24:27]
	v_mfma_f32_16x16x32_bf16 v[12:15], v[112:115], v[204:207], v[12:15]
	v_mfma_f32_16x16x32_bf16 v[8:11], v[120:123], v[204:207], v[8:11]
	v_mfma_f32_16x16x32_bf16 v[60:63], v[116:119], v[164:167], v[60:63]
	v_mfma_f32_16x16x32_bf16 v[56:59], v[132:135], v[164:167], v[56:59]
	v_mfma_f32_16x16x32_bf16 v[44:47], v[116:119], v[172:175], v[44:47]
	v_mfma_f32_16x16x32_bf16 v[40:43], v[132:135], v[172:175], v[40:43]
	v_mfma_f32_16x16x32_bf16 v[28:31], v[116:119], v[200:203], v[28:31]
	v_mfma_f32_16x16x32_bf16 v[24:27], v[132:135], v[200:203], v[24:27]
	v_mfma_f32_16x16x32_bf16 v[12:15], v[116:119], v[208:211], v[12:15]
	v_mfma_f32_16x16x32_bf16 v[8:11], v[132:135], v[208:211], v[8:11]
	v_mfma_f32_16x16x32_bf16 v[52:55], v[140:143], v[160:163], v[52:55]
	v_mfma_f32_16x16x32_bf16 v[48:51], v[152:155], v[160:163], v[48:51]
	v_mfma_f32_16x16x32_bf16 v[36:39], v[140:143], v[168:171], v[36:39]
	v_mfma_f32_16x16x32_bf16 v[32:35], v[152:155], v[168:171], v[32:35]
	v_mfma_f32_16x16x32_bf16 v[20:23], v[140:143], v[176:179], v[20:23]
	v_mfma_f32_16x16x32_bf16 v[16:19], v[152:155], v[176:179], v[16:19]
	v_mfma_f32_16x16x32_bf16 v[4:7], v[140:143], v[204:207], v[4:7]
	v_mfma_f32_16x16x32_bf16 v[0:3], v[152:155], v[204:207], v[0:3]
	v_mfma_f32_16x16x32_bf16 v[52:55], v[148:151], v[164:167], v[52:55]
	v_mfma_f32_16x16x32_bf16 v[48:51], v[156:159], v[164:167], v[48:51]
	v_mfma_f32_16x16x32_bf16 v[36:39], v[148:151], v[172:175], v[36:39]
	v_mfma_f32_16x16x32_bf16 v[32:35], v[156:159], v[172:175], v[32:35]
	v_mfma_f32_16x16x32_bf16 v[20:23], v[148:151], v[200:203], v[20:23]
	v_mfma_f32_16x16x32_bf16 v[16:19], v[156:159], v[200:203], v[16:19]
	v_mfma_f32_16x16x32_bf16 v[4:7], v[148:151], v[208:211], v[4:7]
	v_mfma_f32_16x16x32_bf16 v[0:3], v[156:159], v[208:211], v[0:3]
	s_setprio 0
	s_barrier
	s_add_i32 s60, 0, 0x18000
	s_add_i32 s61, 0, 0x1c000
	v_add_u32_e32 v132, s60, v225
	v_add_u32_e32 v156, s61, v225
	ds_read_b128 v[112:115], v132
	ds_read_b128 v[116:119], v132 offset:1024
	ds_read_b128 v[120:123], v132 offset:2048
	ds_read_b128 v[132:135], v132 offset:3072
	ds_read_b128 v[140:143], v156
	ds_read_b128 v[148:151], v156 offset:1024
	ds_read_b128 v[152:155], v156 offset:2048
	ds_read_b128 v[156:159], v156 offset:3072
	s_add_u32 s38, s38, 0x80000
	s_addc_u32 s39, s39, 0
	s_mov_b32 m0, s45
	v_lshl_add_u64 v[220:221], s[38:39], 0, v[184:185]
	ds_read_b128 v[160:163], v227 offset:32768
	ds_read_b128 v[164:167], v227 offset:33792
	ds_read_b128 v[168:171], v227 offset:34816
	ds_read_b128 v[172:175], v227 offset:35840
	ds_read_b128 v[176:179], v227 offset:36864
	ds_read_b128 v[200:203], v227 offset:37888
	ds_read_b128 v[204:207], v227 offset:38912
	ds_read_b128 v[208:211], v227 offset:39936
	global_load_lds_dwordx4 v[220:221], off
	v_lshl_add_u64 v[220:221], s[38:39], 0, v[182:183]
	s_mov_b32 m0, s52
	s_nop 0
	global_load_lds_dwordx4 v[220:221], off
	s_nop 0
	s_waitcnt vmcnt(8)
	s_waitcnt lgkmcnt(0)
	s_barrier
	s_setprio 1
	s_waitcnt lgkmcnt(0)
	v_mfma_f32_16x16x32_bf16 v[144:147], v[112:115], v[160:163], v[144:147]
	v_mfma_f32_16x16x32_bf16 v[136:139], v[120:123], v[160:163], v[136:139]
	v_mfma_f32_16x16x32_bf16 v[108:111], v[112:115], v[168:171], v[108:111]
	v_mfma_f32_16x16x32_bf16 v[104:107], v[120:123], v[168:171], v[104:107]
	v_mfma_f32_16x16x32_bf16 v[92:95], v[112:115], v[176:179], v[92:95]
	v_mfma_f32_16x16x32_bf16 v[88:91], v[120:123], v[176:179], v[88:91]
	v_mfma_f32_16x16x32_bf16 v[76:79], v[112:115], v[204:207], v[76:79]
	v_mfma_f32_16x16x32_bf16 v[72:75], v[120:123], v[204:207], v[72:75]
	v_mfma_f32_16x16x32_bf16 v[144:147], v[116:119], v[164:167], v[144:147]
	v_mfma_f32_16x16x32_bf16 v[136:139], v[132:135], v[164:167], v[136:139]
	v_mfma_f32_16x16x32_bf16 v[108:111], v[116:119], v[172:175], v[108:111]
	v_mfma_f32_16x16x32_bf16 v[104:107], v[132:135], v[172:175], v[104:107]
	v_mfma_f32_16x16x32_bf16 v[92:95], v[116:119], v[200:203], v[92:95]
	v_mfma_f32_16x16x32_bf16 v[88:91], v[132:135], v[200:203], v[88:91]
	v_mfma_f32_16x16x32_bf16 v[76:79], v[116:119], v[208:211], v[76:79]
	v_mfma_f32_16x16x32_bf16 v[72:75], v[132:135], v[208:211], v[72:75]
	v_mfma_f32_16x16x32_bf16 v[128:131], v[140:143], v[160:163], v[128:131]
	v_mfma_f32_16x16x32_bf16 v[124:127], v[152:155], v[160:163], v[124:127]
	v_mfma_f32_16x16x32_bf16 v[100:103], v[140:143], v[168:171], v[100:103]
	v_mfma_f32_16x16x32_bf16 v[96:99], v[152:155], v[168:171], v[96:99]
	v_mfma_f32_16x16x32_bf16 v[84:87], v[140:143], v[176:179], v[84:87]
	v_mfma_f32_16x16x32_bf16 v[80:83], v[152:155], v[176:179], v[80:83]
	v_mfma_f32_16x16x32_bf16 v[68:71], v[140:143], v[204:207], v[68:71]
	v_mfma_f32_16x16x32_bf16 v[64:67], v[152:155], v[204:207], v[64:67]
	v_mfma_f32_16x16x32_bf16 v[128:131], v[148:151], v[164:167], v[128:131]
	v_mfma_f32_16x16x32_bf16 v[124:127], v[156:159], v[164:167], v[124:127]
	v_mfma_f32_16x16x32_bf16 v[100:103], v[148:151], v[172:175], v[100:103]
	v_mfma_f32_16x16x32_bf16 v[96:99], v[156:159], v[172:175], v[96:99]
	v_mfma_f32_16x16x32_bf16 v[84:87], v[148:151], v[200:203], v[84:87]
	v_mfma_f32_16x16x32_bf16 v[80:83], v[156:159], v[200:203], v[80:83]
	v_mfma_f32_16x16x32_bf16 v[68:71], v[148:151], v[208:211], v[68:71]
	v_mfma_f32_16x16x32_bf16 v[64:67], v[156:159], v[208:211], v[64:67]
	s_setprio 0
	s_barrier
; #define PG8_STAGE(bufoff, gbase, voff) do { _Pragma("unroll") for (int _i = 0; _i < 2; ++_i) \
;         __builtin_amdgcn_global_load_lds((const unsigned*)((const char*)(gbase) + (voff)[_i]), (PG8_LAS unsigned*)(lds + (bufoff) + ldsw + _i * 8192), 16, 0, 0); } while (0)
; #define PG8_LDA(dst, b, h) do { _Pragma("unroll") for (int m = 0; m < 4; ++m) _Pragma("unroll") for (int k = 0; k < 2; ++k) dst[m][k] = *(const PG8_LAS bf16x8*)(lds + PG8_SA(b, h) + aoff + m * 2048 + k * 1024); } while (0)
; #define PG8_MMA(ai, bj, At, Bt) do { __builtin_amdgcn_s_setprio(1); _Pragma("unroll") for (int m = 0; m < 4; ++m) _Pragma("unroll") for (int n = 0; n < 2; ++n) _Pragma("unroll") for (int k = 0; k < 2; ++k) \
;         acc[ai][bj][m][n] = __builtin_amdgcn_mfma_f32_16x16x32_bf16(Bt[n][k], At[m][k], acc[ai][bj][m][n], 0, 0, 0); __builtin_amdgcn_s_setprio(0); } while (0)
; #define PG8_WAIT_V(n) asm volatile("s_waitcnt vmcnt(" #n ")" ::: "memory")
; #define PG8_WAIT_L(n) asm volatile("s_waitcnt lgkmcnt(" #n ")" ::: "memory")
; #define PG8_BAR __builtin_amdgcn_s_barrier()
; #define PG8_SCHED __builtin_amdgcn_sched_barrier(0)
; template <class Epi, class Sched, bool ALIGN_EPI = false, bool SP2 = false>
; __device__ __forceinline__ void gemm_phase(PG8_LAS unsigned char* lds, const Gemm g, const Sched& S, const Epi& E) {
;     ...
;         for (int t = 0; t < nt; t += 2) {
;             const bool last = (t == nt - 2);
;     ...
;             PG8_LDA(At, 1, 1); PG8_STAGE(PG8_SB(1, 0), b3, voffB); PG8_STAGE(PG8_SB(1, 1), b3 + hstep, voffB); PG8_STAGE(PG8_SA(1, 0), a3, voffA);
;             PG8_WAIT_V(8); PG8_WAIT_L(0); PG8_BAR; PG8_MMA(1, 0, At, B0); PG8_MMA(1, 1, At, B1); PG8_BAR; PG8_SCHED;
	s_add_i32 s38, s60, s44
	v_lshl_add_u64 v[212:213], v[212:213], 0, s[78:79]
	s_mov_b32 m0, s38
	ds_read_b128 v[160:163], v227 offset:49152
	ds_read_b128 v[164:167], v227 offset:50176
	ds_read_b128 v[168:171], v227 offset:51200
	ds_read_b128 v[172:175], v227 offset:52224
	ds_read_b128 v[176:179], v227 offset:53248
	ds_read_b128 v[200:203], v227 offset:54272
	ds_read_b128 v[204:207], v227 offset:55296
	ds_read_b128 v[208:211], v227 offset:56320
	global_load_lds_dwordx4 v[212:213], off
	s_add_i32 m0, s38, 0x2000
	s_add_u32 s36, s36, 0x80080
	v_lshl_add_u64 v[212:213], v[214:215], 0, s[78:79]
	s_addc_u32 s37, s37, 0
	s_add_i32 s38, s61, s44
	global_load_lds_dwordx4 v[212:213], off
	v_lshl_add_u64 v[212:213], s[36:37], 0, v[188:189]
	s_mov_b32 m0, s38
	s_nop 0
	global_load_lds_dwordx4 v[212:213], off
	v_lshl_add_u64 v[212:213], s[36:37], 0, v[180:181]
	s_add_i32 m0, s38, 0x2000
	s_nop 0
	global_load_lds_dwordx4 v[212:213], off
	v_lshl_add_u64 v[212:213], v[216:217], 0, s[78:79]
	s_mov_b32 m0, s58
	s_nop 0
	global_load_lds_dwordx4 v[212:213], off
	v_lshl_add_u64 v[212:213], v[218:219], 0, s[78:79]
	s_mov_b32 m0, s62
	s_nop 0
	global_load_lds_dwordx4 v[212:213], off
	s_waitcnt vmcnt(8)
	s_waitcnt lgkmcnt(0)
	s_barrier
	s_setprio 1
	s_waitcnt lgkmcnt(0)
	v_mfma_f32_16x16x32_bf16 v[60:63], v[112:115], v[160:163], v[60:63]
	v_mfma_f32_16x16x32_bf16 v[56:59], v[120:123], v[160:163], v[56:59]
	v_mfma_f32_16x16x32_bf16 v[44:47], v[112:115], v[168:171], v[44:47]
	v_mfma_f32_16x16x32_bf16 v[40:43], v[120:123], v[168:171], v[40:43]
	v_mfma_f32_16x16x32_bf16 v[28:31], v[112:115], v[176:179], v[28:31]
	v_mfma_f32_16x16x32_bf16 v[24:27], v[120:123], v[176:179], v[24:27]
	v_mfma_f32_16x16x32_bf16 v[12:15], v[112:115], v[204:207], v[12:15]
	v_mfma_f32_16x16x32_bf16 v[8:11], v[120:123], v[204:207], v[8:11]
	v_mfma_f32_16x16x32_bf16 v[60:63], v[116:119], v[164:167], v[60:63]
	v_mfma_f32_16x16x32_bf16 v[56:59], v[132:135], v[164:167], v[56:59]
	v_mfma_f32_16x16x32_bf16 v[44:47], v[116:119], v[172:175], v[44:47]
	v_mfma_f32_16x16x32_bf16 v[40:43], v[132:135], v[172:175], v[40:43]
	v_mfma_f32_16x16x32_bf16 v[28:31], v[116:119], v[200:203], v[28:31]
	v_mfma_f32_16x16x32_bf16 v[24:27], v[132:135], v[200:203], v[24:27]
	v_mfma_f32_16x16x32_bf16 v[12:15], v[116:119], v[208:211], v[12:15]
	v_mfma_f32_16x16x32_bf16 v[8:11], v[132:135], v[208:211], v[8:11]
	v_mfma_f32_16x16x32_bf16 v[52:55], v[140:143], v[160:163], v[52:55]
	v_mfma_f32_16x16x32_bf16 v[48:51], v[152:155], v[160:163], v[48:51]
	v_mfma_f32_16x16x32_bf16 v[36:39], v[140:143], v[168:171], v[36:39]
	v_mfma_f32_16x16x32_bf16 v[32:35], v[152:155], v[168:171], v[32:35]
	v_mfma_f32_16x16x32_bf16 v[20:23], v[140:143], v[176:179], v[20:23]
	v_mfma_f32_16x16x32_bf16 v[16:19], v[152:155], v[176:179], v[16:19]
	v_mfma_f32_16x16x32_bf16 v[4:7], v[140:143], v[204:207], v[4:7]
	v_mfma_f32_16x16x32_bf16 v[0:3], v[152:155], v[204:207], v[0:3]
	v_mfma_f32_16x16x32_bf16 v[52:55], v[148:151], v[164:167], v[52:55]
	v_mfma_f32_16x16x32_bf16 v[48:51], v[156:159], v[164:167], v[48:51]
	v_mfma_f32_16x16x32_bf16 v[36:39], v[148:151], v[172:175], v[36:39]
	v_mfma_f32_16x16x32_bf16 v[32:35], v[156:159], v[172:175], v[32:35]
	v_mfma_f32_16x16x32_bf16 v[20:23], v[148:151], v[200:203], v[20:23]
	v_mfma_f32_16x16x32_bf16 v[16:19], v[156:159], v[200:203], v[16:19]
	v_mfma_f32_16x16x32_bf16 v[4:7], v[148:151], v[208:211], v[4:7]
	v_mfma_f32_16x16x32_bf16 v[0:3], v[156:159], v[208:211], v[0:3]
	s_setprio 0
	s_barrier
	s_add_i32 s72, s72, 2
	s_add_u32 s34, s34, 0x100
	s_addc_u32 s35, s35, 0
	s_add_u32 s67, s67, 0x100
	s_addc_u32 s68, s68, 0
	s_cmp_gt_u32 s72, 29
	s_cbranch_scc0 .LBB0_872
	v_mov_b32_e32 v196, 0x2000
	s_and_b64 vcc, exec, s[18:19]
	s_cbranch_vccz .LBB0_875
	s_barrier
